# speedup vs baseline: 1.0903x; 1.0824x over previous
; __device__ __forceinline__ void phase_rwkv_scan(const Params& p, int l, const int tidx) {
;     ...
;     const int pw = w - 4, j = lane;
;     bf16_t* myA = sAp + pw * 16 * LSTR;
;     for (int e = lane; e < 16 * LSTR; e += 64) myA[e] = 0;
;     float* myT = sTmp + pw * 16 * 68;
;     const float mu_r = p.in[I_RWMU][(size_t)l * 3328 + h * 64 + j];
;     const float mu_k = p.in[I_RWMU][(size_t)l * 3328 + 1024 + h * 64 + j];
;     const float mu_v = p.in[I_RWMU][(size_t)l * 3328 + 2048 + h * 64 + j];
;     const float mu_w = p.in[I_RWMU][(size_t)l * 3328 + 3072 + dir * 64 + j];
;     const float mu_a = p.in[I_RWMU][(size_t)l * 3328 + 3200 + dir * 64 + j];
;     const float kks = p.in[I_RWKK][(size_t)l * 1024 + h * 64 + j];
;     const float kap = p.in[I_RWKA][(size_t)l * 1024 + h * 64 + j];
;     const float rkj = p.in[I_RWRK][(size_t)l * 1024 + h * 64 + j];
;     const float w0j = p.in[I_RWW0][((size_t)l * 2 + dir) * 1024 + h * 64 + j];
;     const float a0j = p.in[I_RWA0][((size_t)l * 2 + dir) * 1024 + h * 64 + j];
;     const int colr = OFF_CU + h * 64 + j, colk = OFF_CU + 1024 + h * 64 + j, colv = OFF_CU + 2048 + h * 64 + j;
;     const int colw = OFF_CU + 3072 + dir * 64 + j, cola = OFF_CU + 3200 + dir * 64 + j;
;     unsigned raw[TPW + 2][5];
;     ...
;     RW_LOAD_RAW(0);
.LBB0_441:
	s_or_b64 exec, exec, s[12:13]
	v_cmp_gt_i32_e32 vcc, 64, v150
	s_and_saveexec_b64 s[12:13], vcc
	v_lshl_add_u32 v0, v150, 1, 0
	v_add_u32_e32 v0, 0x23200, v0
	ds_write_b16 v0, v1
	s_or_b64 exec, exec, s[12:13]
	s_waitcnt vmcnt(16)
	v_ashrrev_i32_e32 v17, 6, v150
	s_waitcnt vmcnt(13)
	v_and_b32_e32 v13, 15, v150
	v_lshrrev_b32_e32 v19, 4, v2
	v_cmp_lt_i32_e32 vcc, 3, v17
	s_waitcnt lgkmcnt(0)
	s_barrier
	s_and_saveexec_b64 s[12:13], vcc
	s_xor_b64 s[14:15], exec, s[12:13]
	s_cbranch_execz .LBB0_503
	v_readlane_b32 s16, v253, 30
	v_readlane_b32 s18, v253, 32
	v_readlane_b32 s19, v251, 56
	v_readlane_b32 s5, v252, 40
	v_readfirstlane_b32 s17, v17
	s_nop 0
	s_sub_i32 s17, s17, 4
	v_readlane_b32 s20, v252, 43
	v_readlane_b32 s21, v252, 44
	v_readlane_b32 s22, v252, 41
	v_readlane_b32 s23, v252, 42
	v_lshlrev_b32_e32 v63, 1, v2
	v_lshlrev_b32_e32 v64, 2, v2
	v_readlane_b32 s72, v252, 13
	v_readlane_b32 s73, v252, 14
	s_mul_i32 s10, s56, 0x3400
	s_lshl_b32 s11, s18, 2
	s_add_u32 s74, s72, s10
	s_addc_u32 s75, s73, 0
	s_add_u32 s76, s74, s11
	s_addc_u32 s77, s75, 0
	global_load_dword v238, v64, s[76:77]
	s_add_u32 s76, s76, 0x1000
	s_addc_u32 s77, s77, 0
	global_load_dword v239, v64, s[76:77]
	s_add_u32 s76, s76, 0x1000
	s_addc_u32 s77, s77, 0
	global_load_dword v240, v64, s[76:77]
	s_lshl_b32 s11, s19, 2
	s_add_u32 s76, s74, s11
	s_addc_u32 s77, s75, 0
	s_add_u32 s76, s76, 0x3000
	s_addc_u32 s77, s77, 0
	global_load_dword v241, v64, s[76:77]
	global_load_dword v242, v64, s[76:77] offset:512
	s_lshl_b32 s10, s56, 12
	s_lshl_b32 s11, s18, 2
	s_add_u32 s10, s10, s11
	v_readlane_b32 s72, v252, 25
	v_readlane_b32 s73, v252, 26
	s_add_u32 s76, s72, s10
	s_addc_u32 s77, s73, 0
	global_load_dword v243, v64, s[76:77]
	v_readlane_b32 s72, v252, 27
	v_readlane_b32 s73, v252, 28
	s_add_u32 s76, s72, s10
	s_addc_u32 s77, s73, 0
	global_load_dword v244, v64, s[76:77]
	v_readlane_b32 s72, v252, 29
	v_readlane_b32 s73, v252, 30
	s_add_u32 s76, s72, s10
	s_addc_u32 s77, s73, 0
	global_load_dword v245, v64, s[76:77]
	s_lshl_b32 s10, s56, 1
	s_add_u32 s10, s10, s16
	s_lshl_b32 s10, s10, 12
	s_add_u32 s10, s10, s11
	v_readlane_b32 s72, v252, 15
	v_readlane_b32 s73, v252, 16
	s_add_u32 s76, s72, s10
	s_addc_u32 s77, s73, 0
	global_load_dword v246, v64, s[76:77]
	v_readlane_b32 s72, v252, 19
	v_readlane_b32 s73, v252, 20
	s_add_u32 s76, s72, s10
	s_addc_u32 s77, s73, 0
	global_load_dword v247, v64, s[76:77]
	s_mul_i32 s10, s17, 0x900
	s_add_u32 s10, s10, 0x1ca00
	v_mul_u32_u24_e32 v65, 0x90, v13
	v_lshl_add_u32 v65, v19, 4, v65
	v_add_u32_e32 v69, 0x18200, v65
	v_add_u32_e32 v65, s10, v65
	v_add_u32_e32 v67, s10, v63
	s_mul_i32 s10, s17, 0x1100
	s_add_u32 s10, s10, 0x1ee00
	v_mul_u32_u24_e32 v66, 0x440, v19
	v_lshl_add_u32 v66, v13, 2, v66
	v_add_u32_e32 v66, s10, v66
	v_add_u32_e32 v68, s10, v64
	ds_read_b128 v[170:173], v69 offset:0
	ds_read_b128 v[174:177], v69 offset:64
	ds_read_b128 v[178:181], v69 offset:2304
	ds_read_b128 v[182:185], v69 offset:2368
	ds_read_b128 v[186:189], v69 offset:4608
	ds_read_b128 v[190:193], v69 offset:4672
	ds_read_b128 v[194:197], v69 offset:6912
	ds_read_b128 v[198:201], v69 offset:6976
	ds_read_b128 v[202:205], v69 offset:9216
	ds_read_b128 v[206:209], v69 offset:9280
	ds_read_b128 v[210:213], v69 offset:11520
	ds_read_b128 v[214:217], v69 offset:11584
	ds_read_b128 v[218:221], v69 offset:13824
	ds_read_b128 v[222:225], v69 offset:13888
	ds_read_b128 v[226:229], v69 offset:16128
	ds_read_b128 v[230:233], v69 offset:16192
	v_add_u32_e32 v58, s18, v2
	v_lshlrev_b32_e32 v58, 1, v58
	v_add_u32_e32 v58, 0x1800, v58
	v_add_u32_e32 v59, 0x800, v58
	v_add_u32_e32 v60, 0x1000, v58
	v_add_u32_e32 v61, s19, v2
	v_lshlrev_b32_e32 v61, 1, v61
	v_add_u32_e32 v61, 0x3000, v61
	v_add_u32_e32 v62, 0x100, v61
	v_mov_b32_e32 v34, 0xbfb8aa3b
	v_mov_b32_e32 v36, 0x4038aa3b
	v_mov_b32_e32 v144, 0xbf60028b
	v_mov_b32_e32 v146, -1.0
	v_mov_b32_e32 v151, -2.0
	v_mov_b32_e32 v51, 1.0
	s_mov_b32 s24, 0xaaaaaaaa
	s_mov_b32 s25, 0xaaaaaaaa
	s_mov_b32 s26, 0xcccccccc
	s_mov_b32 s27, 0xcccccccc
	s_mov_b32 s28, 0xf0f0f0f0
	s_mov_b32 s29, 0xf0f0f0f0
	s_mov_b32 s30, -1
	s_mov_b32 s31, 0
	v_mov_b32_e32 v70, 0
	v_mov_b32_e32 v71, 0
	v_mov_b32_e32 v72, 0
	v_mov_b32_e32 v73, 0
	v_mov_b32_e32 v74, 0
	v_mov_b32_e32 v75, 0
	v_mov_b32_e32 v76, 0
	v_mov_b32_e32 v77, 0
	v_mov_b32_e32 v78, 0
	v_mov_b32_e32 v79, 0
	v_mov_b32_e32 v80, 0
	v_mov_b32_e32 v81, 0
	v_mov_b32_e32 v82, 0
	v_mov_b32_e32 v83, 0
	v_mov_b32_e32 v84, 0
	v_mov_b32_e32 v85, 0
	v_mov_b32_e32 v86, 0
	v_mov_b32_e32 v87, 0
	v_mov_b32_e32 v88, 0
	v_mov_b32_e32 v89, 0
	v_mov_b32_e32 v90, 0
	v_mov_b32_e32 v91, 0
	v_mov_b32_e32 v92, 0
	v_mov_b32_e32 v93, 0
	v_mov_b32_e32 v94, 0
	v_mov_b32_e32 v95, 0
	v_mov_b32_e32 v96, 0
	v_mov_b32_e32 v97, 0
	v_mov_b32_e32 v98, 0
	v_mov_b32_e32 v99, 0
	v_mov_b32_e32 v100, 0
	v_mov_b32_e32 v101, 0
	v_mov_b32_e32 v102, 0
	v_mov_b32_e32 v103, 0
	v_mov_b32_e32 v104, 0
	v_mov_b32_e32 v105, 0
	v_mov_b32_e32 v106, 0
	v_mov_b32_e32 v107, 0
	v_mov_b32_e32 v108, 0
	v_mov_b32_e32 v109, 0
	v_mov_b32_e32 v110, 0
	v_mov_b32_e32 v111, 0
	v_mov_b32_e32 v112, 0
	v_mov_b32_e32 v113, 0
	v_mov_b32_e32 v114, 0
	v_mov_b32_e32 v115, 0
	v_mov_b32_e32 v116, 0
	v_mov_b32_e32 v117, 0
	v_mov_b32_e32 v118, 0
	v_mov_b32_e32 v119, 0
	s_waitcnt vmcnt(0)
; __device__ __forceinline__ float bflo(unsigned w) { return __uint_as_float(w << 16); }
; __device__ __forceinline__ void phase_rwkv_scan(const Params& p, int l, const int tidx) {
;     ...
;     RW_LOAD_RAW(0);
; #pragma unroll 1
;     for (int it = -1; it < NCH; it++) {
;       const int pc = it + 1;
;       if (pc < NCH) {
;         float* nbw = sbuf + (pc & 1) * BUFSZ;
;         float ur[TPW], uk[TPW], uv[TPW];
;         float m0, m5;
;         {
;           int tau0 = pc * RTC + pw * TPW;
;           int ta = dir ? (4095 - tau0 + 1) : (tau0 - 1);
;           int tb = dir ? (4095 - tau0 - TPW) : (tau0 + TPW);
;           m0 = (ta >= 0 && ta < SEQ) ? 1.f : 0.f;
;           m5 = (tb >= 0 && tb < SEQ) ? 1.f : 0.f;
;         }
; #pragma unroll
;         for (int q = 0; q < TPW; q++) {
;           const int rr = 1 + q;
;           const float ma = (q == 0) ? m0 : 1.f, mb = (q == TPW - 1) ? m5 : 1.f;
;           float c0, nb;
;           c0 = bflo(raw[rr][0]); nb = 0.5f * (ma * bflo(raw[rr - 1][0]) + mb * bflo(raw[rr + 1][0])); ur[q] = c0 + mu_r * (nb - c0);
	v_mul_f32_e32 v38, 0.5, v238
	v_sub_f32_e32 v39, 1.0, v238
	v_mul_f32_e32 v40, 0.5, v239
	v_sub_f32_e32 v41, 1.0, v239
	v_mul_f32_e32 v42, 0.5, v240
	v_sub_f32_e32 v43, 1.0, v240
	v_mul_f32_e32 v44, 0.5, v241
	v_sub_f32_e32 v45, 1.0, v241
	v_mul_f32_e32 v46, 0.5, v242
	v_sub_f32_e32 v47, 1.0, v242
	v_mov_b32_e32 v48, v243
	v_mov_b32_e32 v50, v244
	v_mov_b32_e32 v52, v245
	v_mov_b32_e32 v54, v246
	v_mov_b32_e32 v56, v247
	s_mov_b32 s0, 0
	s_lshl_b32 s98, s0, 5
	s_lshl_b32 s99, s17, 3
	s_add_i32 s98, s98, s99
	s_sub_i32 s99, 0x1000, s98
	s_add_i32 s66, s98, -1
	s_cmp_eq_u32 s16, 0
	s_cselect_b32 s98, s66, s99
	s_cselect_b32 s67, 1, -1
	s_max_i32 s99, s98, 0
	s_min_i32 s99, s99, 0xfff
	s_add_i32 s99, s99, s5
	s_mul_i32 s99, s99, 0x3a00
	s_add_u32 s100, s94, s99
	s_addc_u32 s101, s95, 0
	global_load_short_d16_hi v70, v58, s[100:101]
	global_load_short_d16_hi v80, v59, s[100:101]
	global_load_short_d16_hi v90, v60, s[100:101]
	global_load_short_d16_hi v100, v61, s[100:101]
	global_load_short_d16_hi v110, v62, s[100:101]
	s_add_i32 s98, s98, s67
	s_max_i32 s99, s98, 0
	s_min_i32 s99, s99, 0xfff
	s_add_i32 s99, s99, s5
	s_mul_i32 s99, s99, 0x3a00
	s_add_u32 s100, s94, s99
	s_addc_u32 s101, s95, 0
	global_load_short_d16_hi v71, v58, s[100:101]
	global_load_short_d16_hi v81, v59, s[100:101]
	global_load_short_d16_hi v91, v60, s[100:101]
	global_load_short_d16_hi v101, v61, s[100:101]
	global_load_short_d16_hi v111, v62, s[100:101]
	s_add_i32 s98, s98, s67
	s_max_i32 s99, s98, 0
	s_min_i32 s99, s99, 0xfff
	s_add_i32 s99, s99, s5
	s_mul_i32 s99, s99, 0x3a00
	s_add_u32 s100, s94, s99
	s_addc_u32 s101, s95, 0
	global_load_short_d16_hi v72, v58, s[100:101]
	global_load_short_d16_hi v82, v59, s[100:101]
	global_load_short_d16_hi v92, v60, s[100:101]
	global_load_short_d16_hi v102, v61, s[100:101]
	global_load_short_d16_hi v112, v62, s[100:101]
	s_add_i32 s98, s98, s67
	s_max_i32 s99, s98, 0
	s_min_i32 s99, s99, 0xfff
	s_add_i32 s99, s99, s5
	s_mul_i32 s99, s99, 0x3a00
	s_add_u32 s100, s94, s99
	s_addc_u32 s101, s95, 0
	global_load_short_d16_hi v73, v58, s[100:101]
	global_load_short_d16_hi v83, v59, s[100:101]
	global_load_short_d16_hi v93, v60, s[100:101]
	global_load_short_d16_hi v103, v61, s[100:101]
	global_load_short_d16_hi v113, v62, s[100:101]
	s_add_i32 s98, s98, s67
	s_max_i32 s99, s98, 0
	s_min_i32 s99, s99, 0xfff
	s_add_i32 s99, s99, s5
	s_mul_i32 s99, s99, 0x3a00
	s_add_u32 s100, s94, s99
	s_addc_u32 s101, s95, 0
	global_load_short_d16_hi v74, v58, s[100:101]
	global_load_short_d16_hi v84, v59, s[100:101]
	global_load_short_d16_hi v94, v60, s[100:101]
	global_load_short_d16_hi v104, v61, s[100:101]
	global_load_short_d16_hi v114, v62, s[100:101]
	s_add_i32 s98, s98, s67
	s_max_i32 s99, s98, 0
	s_min_i32 s99, s99, 0xfff
	s_add_i32 s99, s99, s5
	s_mul_i32 s99, s99, 0x3a00
	s_add_u32 s100, s94, s99
	s_addc_u32 s101, s95, 0
	global_load_short_d16_hi v75, v58, s[100:101]
	global_load_short_d16_hi v85, v59, s[100:101]
	global_load_short_d16_hi v95, v60, s[100:101]
	global_load_short_d16_hi v105, v61, s[100:101]
	global_load_short_d16_hi v115, v62, s[100:101]
	s_add_i32 s98, s98, s67
	s_max_i32 s99, s98, 0
	s_min_i32 s99, s99, 0xfff
	s_add_i32 s99, s99, s5
	s_mul_i32 s99, s99, 0x3a00
	s_add_u32 s100, s94, s99
	s_addc_u32 s101, s95, 0
	global_load_short_d16_hi v76, v58, s[100:101]
	global_load_short_d16_hi v86, v59, s[100:101]
	global_load_short_d16_hi v96, v60, s[100:101]
	global_load_short_d16_hi v106, v61, s[100:101]
	global_load_short_d16_hi v116, v62, s[100:101]
	s_add_i32 s98, s98, s67
	s_max_i32 s99, s98, 0
	s_min_i32 s99, s99, 0xfff
	s_add_i32 s99, s99, s5
	s_mul_i32 s99, s99, 0x3a00
	s_add_u32 s100, s94, s99
	s_addc_u32 s101, s95, 0
	global_load_short_d16_hi v77, v58, s[100:101]
	global_load_short_d16_hi v87, v59, s[100:101]
	global_load_short_d16_hi v97, v60, s[100:101]
	global_load_short_d16_hi v107, v61, s[100:101]
	global_load_short_d16_hi v117, v62, s[100:101]
	s_add_i32 s98, s98, s67
	s_max_i32 s99, s98, 0
	s_min_i32 s99, s99, 0xfff
	s_add_i32 s99, s99, s5
	s_mul_i32 s99, s99, 0x3a00
	s_add_u32 s100, s94, s99
	s_addc_u32 s101, s95, 0
	global_load_short_d16_hi v78, v58, s[100:101]
	global_load_short_d16_hi v88, v59, s[100:101]
	global_load_short_d16_hi v98, v60, s[100:101]
	global_load_short_d16_hi v108, v61, s[100:101]
	global_load_short_d16_hi v118, v62, s[100:101]
	s_add_i32 s98, s98, s67
	s_max_i32 s99, s98, 0
	s_min_i32 s99, s99, 0xfff
	s_add_i32 s99, s99, s5
	s_mul_i32 s99, s99, 0x3a00
	s_add_u32 s100, s94, s99
	s_addc_u32 s101, s95, 0
	global_load_short_d16_hi v79, v58, s[100:101]
	global_load_short_d16_hi v89, v59, s[100:101]
	global_load_short_d16_hi v99, v60, s[100:101]
	global_load_short_d16_hi v109, v61, s[100:101]
	global_load_short_d16_hi v119, v62, s[100:101]
	s_waitcnt vmcnt(0) lgkmcnt(0)
.Lrp_loop:
	s_bitcmp1_b32 s0, 0
	s_cselect_b32 s11, 0xc100, 0
	s_lshl_b32 s12, s17, 11
	s_add_u32 s12, s12, s11
	v_add_u32_e32 v234, s12, v64
	v_add_u32_e32 v235, s12, v63
	v_add_u32_e32 v235, 0x6000, v235
	s_lshl_b32 s13, s17, 6
	s_add_u32 s13, s13, s11
	v_mov_b32_e32 v236, s13
	v_add_u32_e32 v237, 0xa000, v234
	s_cmpk_lt_i32 s0, 0x80
	s_cbranch_scc0 .Lrp_noprep
	s_waitcnt vmcnt(0)
	s_or_b32 s12, s0, s17
	s_cmp_eq_u32 s12, 0
	s_cbranch_scc0 .Lrp_nb0
	v_mov_b32_e32 v70, 0
	v_mov_b32_e32 v80, 0
	v_mov_b32_e32 v90, 0
	v_mov_b32_e32 v100, 0
	v_mov_b32_e32 v110, 0
.Lrp_nb0:
	s_lshl_b32 s12, s0, 2
	s_add_i32 s12, s12, s17
	s_cmpk_eq_i32 s12, 0x1ff
	s_cbranch_scc0 .Lrp_nb1
	v_mov_b32_e32 v79, 0
	v_mov_b32_e32 v89, 0
	v_mov_b32_e32 v99, 0
	v_mov_b32_e32 v109, 0
	v_mov_b32_e32 v119, 0
; __device__ __forceinline__ float bflo(unsigned w) { return __uint_as_float(w << 16); }
; __device__ __forceinline__ void phase_rwkv_scan(const Params& p, int l, const int tidx) {
;     ...
;         for (int q = 0; q < TPW; q++) {
;           const int rr = 1 + q;
;           const float ma = (q == 0) ? m0 : 1.f, mb = (q == TPW - 1) ? m5 : 1.f;
;           float c0, nb;
;           c0 = bflo(raw[rr][0]); nb = 0.5f * (ma * bflo(raw[rr - 1][0]) + mb * bflo(raw[rr + 1][0])); ur[q] = c0 + mu_r * (nb - c0);
;           c0 = bflo(raw[rr][1]); nb = 0.5f * (ma * bflo(raw[rr - 1][1]) + mb * bflo(raw[rr + 1][1])); uk[q] = c0 + mu_k * (nb - c0);
;           c0 = bflo(raw[rr][2]); nb = 0.5f * (ma * bflo(raw[rr - 1][2]) + mb * bflo(raw[rr + 1][2])); uv[q] = c0 + mu_v * (nb - c0);
;           c0 = bflo(raw[rr][3]); nb = 0.5f * (ma * bflo(raw[rr - 1][3]) + mb * bflo(raw[rr + 1][3]));
;           float ulw = c0 + mu_w * (nb - c0);
;           float th = 1.f - 2.f * __builtin_amdgcn_rcpf(1.f + __expf(2.f * ulw));
;           myA[q * LSTR + j] = f2bf(th);
;           c0 = bflo(raw[rr][4]); nb = 0.5f * (ma * bflo(raw[rr - 1][4]) + mb * bflo(raw[rr + 1][4]));
;           myA[(TPW + q) * LSTR + j] = f2bf(c0 + mu_a * (nb - c0));
;         }
;         if (pc + 1 < NCH) RW_LOAD_RAW(pc + 1);
.Lrp_nb1:
	v_pk_add_f32 v[248:249], v[70:71], v[72:73]
	v_mul_f32_e32 v120, v71, v39
	v_mul_f32_e32 v121, v72, v39
	v_pk_fma_f32 v[120:121], v[248:249], v[38:39], v[120:121] op_sel_hi:[1,0,1]
	v_pk_add_f32 v[248:249], v[80:81], v[82:83]
	v_mul_f32_e32 v128, v81, v41
	v_mul_f32_e32 v129, v82, v41
	v_pk_fma_f32 v[128:129], v[248:249], v[40:41], v[128:129] op_sel_hi:[1,0,1]
	v_pk_add_f32 v[248:249], v[90:91], v[92:93]
	v_mul_f32_e32 v136, v91, v43
	v_mul_f32_e32 v137, v92, v43
	v_pk_fma_f32 v[136:137], v[248:249], v[42:43], v[136:137] op_sel_hi:[1,0,1]
	v_pk_add_f32 v[248:249], v[100:101], v[102:103]
	v_mul_f32_e32 v238, v101, v45
	v_mul_f32_e32 v239, v102, v45
	v_pk_fma_f32 v[238:239], v[248:249], v[44:45], v[238:239] op_sel_hi:[1,0,1]
	v_pk_add_f32 v[248:249], v[110:111], v[112:113]
	v_mul_f32_e32 v240, v111, v47
	v_mul_f32_e32 v241, v112, v47
	v_pk_fma_f32 v[240:241], v[248:249], v[46:47], v[240:241] op_sel_hi:[1,0,1]
	v_pk_mul_f32 v[238:239], v[238:239], v[36:37] op_sel_hi:[1,0]
	v_exp_f32_e32 v238, v238
	v_exp_f32_e32 v239, v239
	s_nop 0
	v_pk_add_f32 v[238:239], v[238:239], v[50:51] op_sel:[0,1] op_sel_hi:[1,1]
	v_rcp_f32_e32 v238, v238
	v_rcp_f32_e32 v239, v239
	s_nop 0
	v_pk_fma_f32 v[238:239], v[238:239], v[150:151], v[50:51] op_sel:[0,1,1] op_sel_hi:[1,1,1]
	v_cvt_pk_bf16_f32 v238, v238, v239
	v_cvt_pk_bf16_f32 v240, v240, v241
	ds_write_b16 v67, v238 offset:0
	ds_write_b16_d16_hi v67, v238 offset:144
	ds_write_b16 v67, v240 offset:1152
	ds_write_b16_d16_hi v67, v240 offset:1296
	v_pk_add_f32 v[248:249], v[72:73], v[74:75]
	v_mul_f32_e32 v122, v73, v39
	v_mul_f32_e32 v123, v74, v39
	v_pk_fma_f32 v[122:123], v[248:249], v[38:39], v[122:123] op_sel_hi:[1,0,1]
	v_pk_add_f32 v[248:249], v[82:83], v[84:85]
	v_mul_f32_e32 v130, v83, v41
	v_mul_f32_e32 v131, v84, v41
	v_pk_fma_f32 v[130:131], v[248:249], v[40:41], v[130:131] op_sel_hi:[1,0,1]
	v_pk_add_f32 v[248:249], v[92:93], v[94:95]
	v_mul_f32_e32 v138, v93, v43
	v_mul_f32_e32 v139, v94, v43
	v_pk_fma_f32 v[138:139], v[248:249], v[42:43], v[138:139] op_sel_hi:[1,0,1]
	v_pk_add_f32 v[248:249], v[102:103], v[104:105]
	v_mul_f32_e32 v238, v103, v45
	v_mul_f32_e32 v239, v104, v45
	v_pk_fma_f32 v[238:239], v[248:249], v[44:45], v[238:239] op_sel_hi:[1,0,1]
	v_pk_add_f32 v[248:249], v[112:113], v[114:115]
	v_mul_f32_e32 v240, v113, v47
	v_mul_f32_e32 v241, v114, v47
	v_pk_fma_f32 v[240:241], v[248:249], v[46:47], v[240:241] op_sel_hi:[1,0,1]
	v_pk_mul_f32 v[238:239], v[238:239], v[36:37] op_sel_hi:[1,0]
	v_exp_f32_e32 v238, v238
	v_exp_f32_e32 v239, v239
	s_nop 0
	v_pk_add_f32 v[238:239], v[238:239], v[50:51] op_sel:[0,1] op_sel_hi:[1,1]
	v_rcp_f32_e32 v238, v238
	v_rcp_f32_e32 v239, v239
	s_nop 0
	v_pk_fma_f32 v[238:239], v[238:239], v[150:151], v[50:51] op_sel:[0,1,1] op_sel_hi:[1,1,1]
	v_cvt_pk_bf16_f32 v238, v238, v239
	v_cvt_pk_bf16_f32 v240, v240, v241
	ds_write_b16 v67, v238 offset:288
	ds_write_b16_d16_hi v67, v238 offset:432
	ds_write_b16 v67, v240 offset:1440
	ds_write_b16_d16_hi v67, v240 offset:1584
	v_pk_add_f32 v[248:249], v[74:75], v[76:77]
	v_mul_f32_e32 v124, v75, v39
	v_mul_f32_e32 v125, v76, v39
	v_pk_fma_f32 v[124:125], v[248:249], v[38:39], v[124:125] op_sel_hi:[1,0,1]
	v_pk_add_f32 v[248:249], v[84:85], v[86:87]
	v_mul_f32_e32 v132, v85, v41
	v_mul_f32_e32 v133, v86, v41
	v_pk_fma_f32 v[132:133], v[248:249], v[40:41], v[132:133] op_sel_hi:[1,0,1]
	v_pk_add_f32 v[248:249], v[94:95], v[96:97]
	v_mul_f32_e32 v140, v95, v43
	v_mul_f32_e32 v141, v96, v43
	v_pk_fma_f32 v[140:141], v[248:249], v[42:43], v[140:141] op_sel_hi:[1,0,1]
	v_pk_add_f32 v[248:249], v[104:105], v[106:107]
	v_mul_f32_e32 v238, v105, v45
	v_mul_f32_e32 v239, v106, v45
	v_pk_fma_f32 v[238:239], v[248:249], v[44:45], v[238:239] op_sel_hi:[1,0,1]
	v_pk_add_f32 v[248:249], v[114:115], v[116:117]
	v_mul_f32_e32 v240, v115, v47
	v_mul_f32_e32 v241, v116, v47
	v_pk_fma_f32 v[240:241], v[248:249], v[46:47], v[240:241] op_sel_hi:[1,0,1]
	v_pk_mul_f32 v[238:239], v[238:239], v[36:37] op_sel_hi:[1,0]
	v_exp_f32_e32 v238, v238
	v_exp_f32_e32 v239, v239
	s_nop 0
	v_pk_add_f32 v[238:239], v[238:239], v[50:51] op_sel:[0,1] op_sel_hi:[1,1]
	v_rcp_f32_e32 v238, v238
	v_rcp_f32_e32 v239, v239
	s_nop 0
	v_pk_fma_f32 v[238:239], v[238:239], v[150:151], v[50:51] op_sel:[0,1,1] op_sel_hi:[1,1,1]
	v_cvt_pk_bf16_f32 v238, v238, v239
	v_cvt_pk_bf16_f32 v240, v240, v241
	ds_write_b16 v67, v238 offset:576
	ds_write_b16_d16_hi v67, v238 offset:720
	ds_write_b16 v67, v240 offset:1728
	ds_write_b16_d16_hi v67, v240 offset:1872
	v_pk_add_f32 v[248:249], v[76:77], v[78:79]
	v_mul_f32_e32 v126, v77, v39
	v_mul_f32_e32 v127, v78, v39
	v_pk_fma_f32 v[126:127], v[248:249], v[38:39], v[126:127] op_sel_hi:[1,0,1]
	v_pk_add_f32 v[248:249], v[86:87], v[88:89]
	v_mul_f32_e32 v134, v87, v41
	v_mul_f32_e32 v135, v88, v41
	v_pk_fma_f32 v[134:135], v[248:249], v[40:41], v[134:135] op_sel_hi:[1,0,1]
	v_pk_add_f32 v[248:249], v[96:97], v[98:99]
	v_mul_f32_e32 v142, v97, v43
	v_mul_f32_e32 v143, v98, v43
	v_pk_fma_f32 v[142:143], v[248:249], v[42:43], v[142:143] op_sel_hi:[1,0,1]
	v_pk_add_f32 v[248:249], v[106:107], v[108:109]
	v_mul_f32_e32 v238, v107, v45
	v_mul_f32_e32 v239, v108, v45
	v_pk_fma_f32 v[238:239], v[248:249], v[44:45], v[238:239] op_sel_hi:[1,0,1]
	v_pk_add_f32 v[248:249], v[116:117], v[118:119]
	v_mul_f32_e32 v240, v117, v47
	v_mul_f32_e32 v241, v118, v47
	v_pk_fma_f32 v[240:241], v[248:249], v[46:47], v[240:241] op_sel_hi:[1,0,1]
	v_pk_mul_f32 v[238:239], v[238:239], v[36:37] op_sel_hi:[1,0]
	v_exp_f32_e32 v238, v238
	v_exp_f32_e32 v239, v239
	s_nop 0
	v_pk_add_f32 v[238:239], v[238:239], v[50:51] op_sel:[0,1] op_sel_hi:[1,1]
	v_rcp_f32_e32 v238, v238
	v_rcp_f32_e32 v239, v239
	s_nop 0
	v_pk_fma_f32 v[238:239], v[238:239], v[150:151], v[50:51] op_sel:[0,1,1] op_sel_hi:[1,1,1]
	v_cvt_pk_bf16_f32 v238, v238, v239
	v_cvt_pk_bf16_f32 v240, v240, v241
	ds_write_b16 v67, v238 offset:864
	ds_write_b16_d16_hi v67, v238 offset:1008
	ds_write_b16 v67, v240 offset:2016
	ds_write_b16_d16_hi v67, v240 offset:2160
	s_add_i32 s13, s0, 1
	s_cmpk_lt_i32 s13, 0x80
	s_cbranch_scc0 .Lrp_noload
	s_lshl_b32 s98, s13, 5
	s_lshl_b32 s99, s17, 3
	s_add_i32 s98, s98, s99
	s_sub_i32 s99, 0x1000, s98
	s_add_i32 s66, s98, -1
	s_cmp_eq_u32 s16, 0
	s_cselect_b32 s98, s66, s99
	s_cselect_b32 s67, 1, -1
	s_max_i32 s99, s98, 0
	s_min_i32 s99, s99, 0xfff
	s_add_i32 s99, s99, s5
	s_mul_i32 s99, s99, 0x3a00
	s_add_u32 s100, s94, s99
	s_addc_u32 s101, s95, 0
	global_load_short_d16_hi v70, v58, s[100:101]
	global_load_short_d16_hi v80, v59, s[100:101]
	global_load_short_d16_hi v90, v60, s[100:101]
	global_load_short_d16_hi v100, v61, s[100:101]
	global_load_short_d16_hi v110, v62, s[100:101]
	s_add_i32 s98, s98, s67
	s_max_i32 s99, s98, 0
	s_min_i32 s99, s99, 0xfff
	s_add_i32 s99, s99, s5
	s_mul_i32 s99, s99, 0x3a00
	s_add_u32 s100, s94, s99
	s_addc_u32 s101, s95, 0
	global_load_short_d16_hi v71, v58, s[100:101]
	global_load_short_d16_hi v81, v59, s[100:101]
	global_load_short_d16_hi v91, v60, s[100:101]
	global_load_short_d16_hi v101, v61, s[100:101]
	global_load_short_d16_hi v111, v62, s[100:101]
	s_add_i32 s98, s98, s67
	s_max_i32 s99, s98, 0
	s_min_i32 s99, s99, 0xfff
	s_add_i32 s99, s99, s5
	s_mul_i32 s99, s99, 0x3a00
	s_add_u32 s100, s94, s99
	s_addc_u32 s101, s95, 0
	global_load_short_d16_hi v72, v58, s[100:101]
	global_load_short_d16_hi v82, v59, s[100:101]
	global_load_short_d16_hi v92, v60, s[100:101]
	global_load_short_d16_hi v102, v61, s[100:101]
	global_load_short_d16_hi v112, v62, s[100:101]
	s_add_i32 s98, s98, s67
	s_max_i32 s99, s98, 0
	s_min_i32 s99, s99, 0xfff
	s_add_i32 s99, s99, s5
	s_mul_i32 s99, s99, 0x3a00
	s_add_u32 s100, s94, s99
	s_addc_u32 s101, s95, 0
	global_load_short_d16_hi v73, v58, s[100:101]
	global_load_short_d16_hi v83, v59, s[100:101]
	global_load_short_d16_hi v93, v60, s[100:101]
	global_load_short_d16_hi v103, v61, s[100:101]
	global_load_short_d16_hi v113, v62, s[100:101]
	s_add_i32 s98, s98, s67
	s_max_i32 s99, s98, 0
	s_min_i32 s99, s99, 0xfff
	s_add_i32 s99, s99, s5
	s_mul_i32 s99, s99, 0x3a00
	s_add_u32 s100, s94, s99
	s_addc_u32 s101, s95, 0
	global_load_short_d16_hi v74, v58, s[100:101]
	global_load_short_d16_hi v84, v59, s[100:101]
	global_load_short_d16_hi v94, v60, s[100:101]
	global_load_short_d16_hi v104, v61, s[100:101]
	global_load_short_d16_hi v114, v62, s[100:101]
	s_add_i32 s98, s98, s67
	s_max_i32 s99, s98, 0
	s_min_i32 s99, s99, 0xfff
	s_add_i32 s99, s99, s5
	s_mul_i32 s99, s99, 0x3a00
	s_add_u32 s100, s94, s99
	s_addc_u32 s101, s95, 0
	global_load_short_d16_hi v75, v58, s[100:101]
	global_load_short_d16_hi v85, v59, s[100:101]
	global_load_short_d16_hi v95, v60, s[100:101]
	global_load_short_d16_hi v105, v61, s[100:101]
	global_load_short_d16_hi v115, v62, s[100:101]
	s_add_i32 s98, s98, s67
	s_max_i32 s99, s98, 0
	s_min_i32 s99, s99, 0xfff
	s_add_i32 s99, s99, s5
	s_mul_i32 s99, s99, 0x3a00
	s_add_u32 s100, s94, s99
	s_addc_u32 s101, s95, 0
	global_load_short_d16_hi v76, v58, s[100:101]
	global_load_short_d16_hi v86, v59, s[100:101]
	global_load_short_d16_hi v96, v60, s[100:101]
	global_load_short_d16_hi v106, v61, s[100:101]
	global_load_short_d16_hi v116, v62, s[100:101]
	s_add_i32 s98, s98, s67
	s_max_i32 s99, s98, 0
	s_min_i32 s99, s99, 0xfff
	s_add_i32 s99, s99, s5
	s_mul_i32 s99, s99, 0x3a00
	s_add_u32 s100, s94, s99
	s_addc_u32 s101, s95, 0
	global_load_short_d16_hi v77, v58, s[100:101]
	global_load_short_d16_hi v87, v59, s[100:101]
	global_load_short_d16_hi v97, v60, s[100:101]
	global_load_short_d16_hi v107, v61, s[100:101]
	global_load_short_d16_hi v117, v62, s[100:101]
	s_add_i32 s98, s98, s67
	s_max_i32 s99, s98, 0
	s_min_i32 s99, s99, 0xfff
	s_add_i32 s99, s99, s5
	s_mul_i32 s99, s99, 0x3a00
	s_add_u32 s100, s94, s99
	s_addc_u32 s101, s95, 0
	global_load_short_d16_hi v78, v58, s[100:101]
	global_load_short_d16_hi v88, v59, s[100:101]
	global_load_short_d16_hi v98, v60, s[100:101]
	global_load_short_d16_hi v108, v61, s[100:101]
	global_load_short_d16_hi v118, v62, s[100:101]
	s_add_i32 s98, s98, s67
	s_max_i32 s99, s98, 0
	s_min_i32 s99, s99, 0xfff
	s_add_i32 s99, s99, s5
	s_mul_i32 s99, s99, 0x3a00
	s_add_u32 s100, s94, s99
	s_addc_u32 s101, s95, 0
	global_load_short_d16_hi v79, v58, s[100:101]
	global_load_short_d16_hi v89, v59, s[100:101]
	global_load_short_d16_hi v99, v60, s[100:101]
	global_load_short_d16_hi v109, v61, s[100:101]
	global_load_short_d16_hi v119, v62, s[100:101]
; __device__ __forceinline__ float sigmoidf_(float x) { return __builtin_amdgcn_rcpf(1.f + __expf(-x)); }
; __device__ __forceinline__ void phase_rwkv_scan(const Params& p, int l, const int tidx) {
;     ...
;         __builtin_amdgcn_wave_barrier();
;         {
;           f32x4 acc[8];
; #pragma unroll
;           for (int nt = 0; nt < 8; nt++) acc[nt] = f32x4{0.f, 0.f, 0.f, 0.f};
; #pragma unroll
;           for (int k2 = 0; k2 < 2; k2++) {
;             bf16x8 af = *(const bf16x8*)(myA + l15 * LSTR + k2 * 32 + quad * 8);
; #pragma unroll
;             for (int nt = 0; nt < 8; nt++) {
;               bf16x8 bfv = *(const bf16x8*)(sBT + (nt * 16 + l15) * LSTR + k2 * 32 + quad * 8);
;               acc[nt] = __builtin_amdgcn_mfma_f32_16x16x32_bf16(af, bfv, acc[nt], 0, 0, 0);
;             }
;           }
;           if (quad < 2) {
; #pragma unroll
;             for (int nt = 0; nt < 4; nt++)
; #pragma unroll
;               for (int r = 0; r < 4; r++) myT[(quad * 4 + r) * 68 + nt * 16 + l15] = acc[nt][r];
;           } else {
; #pragma unroll
;             for (int nt = 0; nt < 4; nt++)
; #pragma unroll
;               for (int r = 0; r < 4; r++) myT[(quad * 4 + r) * 68 + nt * 16 + l15] = acc[4 + nt][r];
;           }
;         }
;         __builtin_amdgcn_wave_barrier();
; #pragma unroll
;         for (int q = 0; q < TPW; q++) {
;           const int s = pw * TPW + q;
;           float wl = w0j + myT[q * 68 + j];
;           float al = a0j + myT[(TPW + q) * 68 + j];
;           float dec = __expf(-0.6065306597126334f * sigmoidf_(wl));
;           float av = sigmoidf_(al);
;           float kkr = uk[q] * kks;
;           float ss = wave_sum(kkr * kkr);
;           float kk = kkr * __builtin_amdgcn_rcpf(fmaxf(sqrtf(ss), 1e-12f));
;           float kd = uk[q] * (1.f + (av - 1.f) * kap);
;           float bt = wave_sum(ur[q] * kd * rkj);
;           float c1 = wave_sum(kk * av * ur[q]);
;           float c2 = wave_sum(kd * ur[q]);
;           nbw[s * 64 + j] = dec;
.Lrp_noload:
	s_waitcnt lgkmcnt(0)
	ds_read_b128 v[152:155], v65
	ds_read_b128 v[156:159], v65 offset:64
	s_waitcnt lgkmcnt(1)
	v_mfma_f32_16x16x32_bf16 v[2:5], v[152:155], v[170:173], 0
	v_mfma_f32_16x16x32_bf16 v[6:9], v[152:155], v[178:181], 0
	v_mfma_f32_16x16x32_bf16 v[10:13], v[152:155], v[186:189], 0
	v_mfma_f32_16x16x32_bf16 v[14:17], v[152:155], v[194:197], 0
	v_mfma_f32_16x16x32_bf16 v[18:21], v[152:155], v[202:205], 0
	v_mfma_f32_16x16x32_bf16 v[22:25], v[152:155], v[210:213], 0
	v_mfma_f32_16x16x32_bf16 v[26:29], v[152:155], v[218:221], 0
	v_mfma_f32_16x16x32_bf16 v[30:33], v[152:155], v[226:229], 0
	s_waitcnt lgkmcnt(0)
	v_mfma_f32_16x16x32_bf16 v[2:5], v[156:159], v[174:177], v[2:5]
	v_mfma_f32_16x16x32_bf16 v[6:9], v[156:159], v[182:185], v[6:9]
	v_mfma_f32_16x16x32_bf16 v[10:13], v[156:159], v[190:193], v[10:13]
	v_mfma_f32_16x16x32_bf16 v[14:17], v[156:159], v[198:201], v[14:17]
	v_mfma_f32_16x16x32_bf16 v[18:21], v[156:159], v[206:209], v[18:21]
	v_mfma_f32_16x16x32_bf16 v[22:25], v[156:159], v[214:217], v[22:25]
	v_mfma_f32_16x16x32_bf16 v[26:29], v[156:159], v[222:225], v[26:29]
	v_mfma_f32_16x16x32_bf16 v[30:33], v[156:159], v[230:233], v[30:33]
	s_nop 4
	v_cndmask_b32_e64 v2, v18, v2, s[30:31]
	v_cndmask_b32_e64 v3, v19, v3, s[30:31]
	v_cndmask_b32_e64 v4, v20, v4, s[30:31]
	v_cndmask_b32_e64 v5, v21, v5, s[30:31]
	v_cndmask_b32_e64 v6, v22, v6, s[30:31]
	v_cndmask_b32_e64 v7, v23, v7, s[30:31]
	v_cndmask_b32_e64 v8, v24, v8, s[30:31]
	v_cndmask_b32_e64 v9, v25, v9, s[30:31]
	v_cndmask_b32_e64 v10, v26, v10, s[30:31]
	v_cndmask_b32_e64 v11, v27, v11, s[30:31]
	v_cndmask_b32_e64 v12, v28, v12, s[30:31]
	v_cndmask_b32_e64 v13, v29, v13, s[30:31]
	v_cndmask_b32_e64 v14, v30, v14, s[30:31]
	v_cndmask_b32_e64 v15, v31, v15, s[30:31]
	v_cndmask_b32_e64 v16, v32, v16, s[30:31]
	v_cndmask_b32_e64 v17, v33, v17, s[30:31]
	ds_write2_b32 v66, v2, v3 offset0:0 offset1:68
	ds_write2_b32 v66, v4, v5 offset0:136 offset1:204
	ds_write2_b32 v66, v6, v7 offset0:16 offset1:84
	ds_write2_b32 v66, v8, v9 offset0:152 offset1:220
	ds_write2_b32 v66, v10, v11 offset0:32 offset1:100
	ds_write2_b32 v66, v12, v13 offset0:168 offset1:236
	ds_write2_b32 v66, v14, v15 offset0:48 offset1:116
	ds_write2_b32 v66, v16, v17 offset0:184 offset1:252
	s_waitcnt lgkmcnt(0)
	v_mov_b32_e32 v152, 1.0
	ds_read_b32 v2, v68 offset:0
	ds_read_b32 v3, v68 offset:272
	ds_read_b32 v4, v68 offset:2176
	ds_read_b32 v5, v68 offset:2448
	v_pk_mul_f32 v[12:13], v[128:129], v[48:49] op_sel_hi:[1,0]
	v_pk_mul_f32 v[18:19], v[12:13], v[12:13]
	s_waitcnt lgkmcnt(0)
	v_pk_add_f32 v[2:3], v[2:3], v[54:55] op_sel_hi:[1,0]
	v_pk_add_f32 v[4:5], v[4:5], v[56:57] op_sel_hi:[1,0]
	v_pk_mul_f32 v[6:7], v[2:3], v[34:35] op_sel_hi:[1,0]
	v_pk_mul_f32 v[10:11], v[4:5], v[34:35] op_sel_hi:[1,0]
	v_exp_f32_e32 v6, v6
	v_exp_f32_e32 v7, v7
	v_exp_f32_e32 v10, v10
	v_exp_f32_e32 v11, v11
	v_pk_add_f32 v[6:7], v[6:7], v[50:51] op_sel:[0,1] op_sel_hi:[1,1]
	v_pk_add_f32 v[10:11], v[10:11], v[50:51] op_sel:[0,1] op_sel_hi:[1,1]
	v_rcp_f32_e32 v6, v6
	v_rcp_f32_e32 v7, v7
	v_rcp_f32_e32 v10, v10
	v_rcp_f32_e32 v11, v11
	v_pk_mul_f32 v[8:9], v[6:7], v[144:145] op_sel_hi:[1,0]
	v_exp_f32_e32 v8, v8
	v_exp_f32_e32 v9, v9
	v_mul_f32_e32 v153, v152, v8
	v_mov_b32_e32 v154, v153
	v_mul_f32_e32 v155, v153, v9
	v_rcp_f32_e32 v156, v154
	v_rcp_f32_e32 v157, v155
	v_pk_add_f32 v[14:15], v[10:11], v[146:147] op_sel_hi:[1,0]
	v_pk_fma_f32 v[14:15], v[14:15], v[50:51], v[50:51] op_sel:[0,0,1] op_sel_hi:[1,0,1]
	v_pk_mul_f32 v[16:17], v[128:129], v[14:15]
	v_pk_mul_f32 v[20:21], v[120:121], v[16:17]
	v_pk_mul_f32 v[22:23], v[20:21], v[52:53] op_sel_hi:[1,0]
	v_pk_mul_f32 v[24:25], v[12:13], v[10:11]
	v_pk_mul_f32 v[24:25], v[24:25], v[120:121]
	v_add_f32_dpp v18, v18, v18 quad_perm:[1,0,3,2] row_mask:0xf bank_mask:0xf
	v_add_f32_dpp v19, v19, v19 quad_perm:[1,0,3,2] row_mask:0xf bank_mask:0xf
	v_add_f32_dpp v22, v22, v22 quad_perm:[1,0,3,2] row_mask:0xf bank_mask:0xf
	v_add_f32_dpp v23, v23, v23 quad_perm:[1,0,3,2] row_mask:0xf bank_mask:0xf
	v_add_f32_dpp v24, v24, v24 quad_perm:[1,0,3,2] row_mask:0xf bank_mask:0xf
	v_add_f32_dpp v25, v25, v25 quad_perm:[1,0,3,2] row_mask:0xf bank_mask:0xf
	v_add_f32_dpp v20, v20, v20 quad_perm:[1,0,3,2] row_mask:0xf bank_mask:0xf
	v_add_f32_dpp v21, v21, v21 quad_perm:[1,0,3,2] row_mask:0xf bank_mask:0xf
	v_cndmask_b32_e64 v26, v18, v19, s[24:25]
	v_cndmask_b32_e64 v27, v22, v23, s[24:25]
	v_cndmask_b32_e64 v28, v24, v25, s[24:25]
	v_cndmask_b32_e64 v29, v20, v21, s[24:25]
	v_add_f32_dpp v26, v26, v26 quad_perm:[2,3,0,1] row_mask:0xf bank_mask:0xf
	v_add_f32_dpp v27, v27, v27 quad_perm:[2,3,0,1] row_mask:0xf bank_mask:0xf
	v_add_f32_dpp v28, v28, v28 quad_perm:[2,3,0,1] row_mask:0xf bank_mask:0xf
	v_add_f32_dpp v29, v29, v29 quad_perm:[2,3,0,1] row_mask:0xf bank_mask:0xf
	v_cndmask_b32_e64 v30, v26, v27, s[26:27]
	v_cndmask_b32_e64 v31, v28, v29, s[26:27]
	s_nop 0
	v_add_f32_dpp v30, v30, v30 row_ror:4 row_mask:0xf bank_mask:0xf
	v_add_f32_dpp v31, v31, v31 row_ror:4 row_mask:0xf bank_mask:0xf
	v_cndmask_b32_e64 v32, v30, v31, s[28:29]
	s_nop 1
	v_add_f32_dpp v32, v32, v32 row_ror:8 row_mask:0xf bank_mask:0xf
	v_mov_b32_e32 v33, v32
	s_nop 1
	v_permlane16_swap_b32 v33, v32
	v_add_f32_e32 v32, v33, v32
	v_mov_b32_e32 v33, v32
	s_nop 1
	v_permlane32_swap_b32 v33, v32
	v_add_f32_e32 v32, v33, v32
	s_nop 1
	v_mov_b32_dpp v246, v32 row_newbcast:0 row_mask:0xf bank_mask:0xf
	v_mov_b32_dpp v247, v32 row_newbcast:1 row_mask:0xf bank_mask:0xf
	v_sqrt_f32_e32 v240, v246
	v_sqrt_f32_e32 v241, v247
	v_add_u32_e32 v248, -1, v240
	v_fma_f32 v249, -v248, v240, v246
; __device__ __forceinline__ void phase_rwkv_scan(const Params& p, int l, const int tidx) {
;     ...
;           float kkr = uk[q] * kks;
;           float ss = wave_sum(kkr * kkr);
;           float kk = kkr * __builtin_amdgcn_rcpf(fmaxf(sqrtf(ss), 1e-12f));
;           float kd = uk[q] * (1.f + (av - 1.f) * kap);
;           float bt = wave_sum(ur[q] * kd * rkj);
;           float c1 = wave_sum(kk * av * ur[q]);
;           float c2 = wave_sum(kd * ur[q]);
;           nbw[s * 64 + j] = dec;
;           nbw[1 * VSZ + s * 64 + j] = kk * av;
;           nbw[2 * VSZ + s * 64 + j] = kd;
;           ((bf16_t*)(nbw + 3 * VSZ))[s * 128 + j] = f2bf(kk);
;           ((bf16_t*)(nbw + 3 * VSZ))[s * 128 + 64 + j] = f2bf(dec * ur[q]);
;           nbw[4 * VSZ + s * 64 + j] = uv[q];
;           if (lane == 1) *(float2*)(nbw + 6 * VSZ + 2 * s) = float2{c1, c2};
;           if (lane == 0) {
;             int tau = pc * RTC + s;
;             int t = dir ? (4095 - tau) : tau;
;             beta[(size_t)(b * SEQ + t) * 16 + h] = bt;
;           }
	v_cmp_ge_f32_e64 s[12:13], 0, v249
	v_add_u32_e32 v249, 1, v240
	s_nop 0
	v_cndmask_b32_e64 v248, v240, v248, s[12:13]
	v_fma_f32 v240, -v249, v240, v246
	v_cmp_lt_f32_e64 s[12:13], 0, v240
	s_nop 1
	v_cndmask_b32_e64 v240, v248, v249, s[12:13]
	v_add_u32_e32 v248, -1, v241
	v_fma_f32 v249, -v248, v241, v247
	v_cmp_ge_f32_e64 s[12:13], 0, v249
	v_add_u32_e32 v249, 1, v241
	s_nop 0
	v_cndmask_b32_e64 v248, v241, v248, s[12:13]
	v_fma_f32 v241, -v249, v241, v247
	v_cmp_lt_f32_e64 s[12:13], 0, v241
	s_nop 1
	v_cndmask_b32_e64 v241, v248, v249, s[12:13]
	v_max_f32_e32 v240, 0x2b8cbccc, v240
	v_max_f32_e32 v241, 0x2b8cbccc, v241
	v_rcp_f32_e32 v238, v240
	v_rcp_f32_e32 v239, v241
	s_nop 0
	v_pk_mul_f32 v[242:243], v[12:13], v[238:239]
	v_mul_f32_dpp v244, v32, v238 row_newbcast:4 row_mask:0xf bank_mask:0xf
	v_mul_f32_dpp v245, v32, v239 row_newbcast:5 row_mask:0xf bank_mask:0xf
	v_pk_mul_f32 v[6:7], v[242:243], v[10:11]
	v_pk_mul_f32 v[14:15], v[154:155], v[120:121]
	v_pk_mul_f32 v[242:243], v[242:243], v[152:153]
	v_pk_mul_f32 v[6:7], v[6:7], v[156:157]
	v_pk_mul_f32 v[16:17], v[16:17], v[156:157]
	v_cvt_pk_bf16_f32 v248, v242, v243
	v_cvt_pk_bf16_f32 v249, v14, v15
	v_mov_b32_e32 v152, v155
	ds_write_b32 v234, v6 offset:8192
	ds_write_b32 v234, v16 offset:16384
	ds_write_b32 v234, v136 offset:32768
	ds_write_b32 v234, v7 offset:8448
	ds_write_b32 v234, v17 offset:16640
	ds_write_b32 v234, v137 offset:33024
	ds_write_b16 v235, v248 offset:0
	ds_write_b16_d16_hi v235, v248 offset:256
	ds_write_b16 v235, v249 offset:128
	ds_write_b16_d16_hi v235, v249 offset:384
	s_lshl_b32 s12, s0, 5
	s_lshl_b32 s13, s17, 3
	s_add_i32 s12, s12, s13
	s_add_i32 s12, s12, 0
	s_sub_i32 s67, 0xfff, s12
	s_cmp_eq_u32 s16, 0
	s_cselect_b32 s13, s12, s67
	s_add_i32 s13, s13, s5
	s_lshl_b32 s13, s13, 6
	s_add_u32 s72, s22, s13
	s_addc_u32 s73, s23, 0
	s_add_i32 s12, s12, 1
	s_sub_i32 s67, 0xfff, s12
	s_cmp_eq_u32 s16, 0
	s_cselect_b32 s13, s12, s67
	s_add_i32 s13, s13, s5
	s_lshl_b32 s13, s13, 6
	s_add_u32 s74, s22, s13
	s_addc_u32 s75, s23, 0
	s_mov_b64 exec, 1
	ds_write_b32 v236, v244 offset:49152
	ds_write_b32 v236, v245 offset:49160
	s_mov_b64 exec, 0x40
	ds_write_b32 v236, v32 offset:49156
	s_mov_b64 exec, 0x80
	ds_write_b32 v236, v32 offset:49164
	s_mov_b64 exec, 4
	global_store_dword v1, v32, s[72:73]
	s_mov_b64 exec, 8
	global_store_dword v1, v32, s[74:75]
	s_mov_b64 exec, -1
	ds_read_b32 v2, v68 offset:544
	ds_read_b32 v3, v68 offset:816
	ds_read_b32 v4, v68 offset:2720
	ds_read_b32 v5, v68 offset:2992
	v_pk_mul_f32 v[12:13], v[130:131], v[48:49] op_sel_hi:[1,0]
	v_pk_mul_f32 v[18:19], v[12:13], v[12:13]
	s_waitcnt lgkmcnt(0)
	v_pk_add_f32 v[2:3], v[2:3], v[54:55] op_sel_hi:[1,0]
	v_pk_add_f32 v[4:5], v[4:5], v[56:57] op_sel_hi:[1,0]
	v_pk_mul_f32 v[6:7], v[2:3], v[34:35] op_sel_hi:[1,0]
	v_pk_mul_f32 v[10:11], v[4:5], v[34:35] op_sel_hi:[1,0]
	v_exp_f32_e32 v6, v6
	v_exp_f32_e32 v7, v7
	v_exp_f32_e32 v10, v10
	v_exp_f32_e32 v11, v11
	v_pk_add_f32 v[6:7], v[6:7], v[50:51] op_sel:[0,1] op_sel_hi:[1,1]
	v_pk_add_f32 v[10:11], v[10:11], v[50:51] op_sel:[0,1] op_sel_hi:[1,1]
	v_rcp_f32_e32 v6, v6
	v_rcp_f32_e32 v7, v7
	v_rcp_f32_e32 v10, v10
	v_rcp_f32_e32 v11, v11
	v_pk_mul_f32 v[8:9], v[6:7], v[144:145] op_sel_hi:[1,0]
	v_exp_f32_e32 v8, v8
	v_exp_f32_e32 v9, v9
	v_mul_f32_e32 v153, v152, v8
	v_mov_b32_e32 v154, v153
	v_mul_f32_e32 v155, v153, v9
	v_rcp_f32_e32 v156, v154
	v_rcp_f32_e32 v157, v155
	v_pk_add_f32 v[14:15], v[10:11], v[146:147] op_sel_hi:[1,0]
	v_pk_fma_f32 v[14:15], v[14:15], v[50:51], v[50:51] op_sel:[0,0,1] op_sel_hi:[1,0,1]
	v_pk_mul_f32 v[16:17], v[130:131], v[14:15]
	v_pk_mul_f32 v[20:21], v[122:123], v[16:17]
	v_pk_mul_f32 v[22:23], v[20:21], v[52:53] op_sel_hi:[1,0]
	v_pk_mul_f32 v[24:25], v[12:13], v[10:11]
	v_pk_mul_f32 v[24:25], v[24:25], v[122:123]
	v_add_f32_dpp v18, v18, v18 quad_perm:[1,0,3,2] row_mask:0xf bank_mask:0xf
	v_add_f32_dpp v19, v19, v19 quad_perm:[1,0,3,2] row_mask:0xf bank_mask:0xf
	v_add_f32_dpp v22, v22, v22 quad_perm:[1,0,3,2] row_mask:0xf bank_mask:0xf
	v_add_f32_dpp v23, v23, v23 quad_perm:[1,0,3,2] row_mask:0xf bank_mask:0xf
	v_add_f32_dpp v24, v24, v24 quad_perm:[1,0,3,2] row_mask:0xf bank_mask:0xf
	v_add_f32_dpp v25, v25, v25 quad_perm:[1,0,3,2] row_mask:0xf bank_mask:0xf
	v_add_f32_dpp v20, v20, v20 quad_perm:[1,0,3,2] row_mask:0xf bank_mask:0xf
	v_add_f32_dpp v21, v21, v21 quad_perm:[1,0,3,2] row_mask:0xf bank_mask:0xf
	v_cndmask_b32_e64 v26, v18, v19, s[24:25]
	v_cndmask_b32_e64 v27, v22, v23, s[24:25]
	v_cndmask_b32_e64 v28, v24, v25, s[24:25]
	v_cndmask_b32_e64 v29, v20, v21, s[24:25]
	v_add_f32_dpp v26, v26, v26 quad_perm:[2,3,0,1] row_mask:0xf bank_mask:0xf
	v_add_f32_dpp v27, v27, v27 quad_perm:[2,3,0,1] row_mask:0xf bank_mask:0xf
	v_add_f32_dpp v28, v28, v28 quad_perm:[2,3,0,1] row_mask:0xf bank_mask:0xf
	v_add_f32_dpp v29, v29, v29 quad_perm:[2,3,0,1] row_mask:0xf bank_mask:0xf
	v_cndmask_b32_e64 v30, v26, v27, s[26:27]
	v_cndmask_b32_e64 v31, v28, v29, s[26:27]
	s_nop 0
	v_add_f32_dpp v30, v30, v30 row_ror:4 row_mask:0xf bank_mask:0xf
	v_add_f32_dpp v31, v31, v31 row_ror:4 row_mask:0xf bank_mask:0xf
	v_cndmask_b32_e64 v32, v30, v31, s[28:29]
	s_nop 1
	v_add_f32_dpp v32, v32, v32 row_ror:8 row_mask:0xf bank_mask:0xf
	v_mov_b32_e32 v33, v32
	s_nop 1
	v_permlane16_swap_b32 v33, v32
	v_add_f32_e32 v32, v33, v32
	v_mov_b32_e32 v33, v32
	s_nop 1
	v_permlane32_swap_b32 v33, v32
	v_add_f32_e32 v32, v33, v32
	s_nop 1
	v_mov_b32_dpp v246, v32 row_newbcast:0 row_mask:0xf bank_mask:0xf
	v_mov_b32_dpp v247, v32 row_newbcast:1 row_mask:0xf bank_mask:0xf
	v_sqrt_f32_e32 v240, v246
	v_sqrt_f32_e32 v241, v247
; __device__ __forceinline__ void phase_rwkv_scan(const Params& p, int l, const int tidx) {
;     ...
;           float kkr = uk[q] * kks;
;           float ss = wave_sum(kkr * kkr);
;           float kk = kkr * __builtin_amdgcn_rcpf(fmaxf(sqrtf(ss), 1e-12f));
;           float kd = uk[q] * (1.f + (av - 1.f) * kap);
;           float bt = wave_sum(ur[q] * kd * rkj);
;           float c1 = wave_sum(kk * av * ur[q]);
;           float c2 = wave_sum(kd * ur[q]);
;           nbw[s * 64 + j] = dec;
;           nbw[1 * VSZ + s * 64 + j] = kk * av;
;           nbw[2 * VSZ + s * 64 + j] = kd;
;           ((bf16_t*)(nbw + 3 * VSZ))[s * 128 + j] = f2bf(kk);
;           ((bf16_t*)(nbw + 3 * VSZ))[s * 128 + 64 + j] = f2bf(dec * ur[q]);
;           nbw[4 * VSZ + s * 64 + j] = uv[q];
;           if (lane == 1) *(float2*)(nbw + 6 * VSZ + 2 * s) = float2{c1, c2};
;           if (lane == 0) {
;             int tau = pc * RTC + s;
;             int t = dir ? (4095 - tau) : tau;
;             beta[(size_t)(b * SEQ + t) * 16 + h] = bt;
;           }
	v_add_u32_e32 v248, -1, v240
	v_fma_f32 v249, -v248, v240, v246
	v_cmp_ge_f32_e64 s[12:13], 0, v249
	v_add_u32_e32 v249, 1, v240
	s_nop 0
	v_cndmask_b32_e64 v248, v240, v248, s[12:13]
	v_fma_f32 v240, -v249, v240, v246
	v_cmp_lt_f32_e64 s[12:13], 0, v240
	s_nop 1
	v_cndmask_b32_e64 v240, v248, v249, s[12:13]
	v_add_u32_e32 v248, -1, v241
	v_fma_f32 v249, -v248, v241, v247
	v_cmp_ge_f32_e64 s[12:13], 0, v249
	v_add_u32_e32 v249, 1, v241
	s_nop 0
	v_cndmask_b32_e64 v248, v241, v248, s[12:13]
	v_fma_f32 v241, -v249, v241, v247
	v_cmp_lt_f32_e64 s[12:13], 0, v241
	s_nop 1
	v_cndmask_b32_e64 v241, v248, v249, s[12:13]
	v_max_f32_e32 v240, 0x2b8cbccc, v240
	v_max_f32_e32 v241, 0x2b8cbccc, v241
	v_rcp_f32_e32 v238, v240
	v_rcp_f32_e32 v239, v241
	s_nop 0
	v_pk_mul_f32 v[242:243], v[12:13], v[238:239]
	v_mul_f32_dpp v244, v32, v238 row_newbcast:4 row_mask:0xf bank_mask:0xf
	v_mul_f32_dpp v245, v32, v239 row_newbcast:5 row_mask:0xf bank_mask:0xf
	v_pk_mul_f32 v[6:7], v[242:243], v[10:11]
	v_pk_mul_f32 v[14:15], v[154:155], v[122:123]
	v_pk_mul_f32 v[242:243], v[242:243], v[152:153]
	v_pk_mul_f32 v[6:7], v[6:7], v[156:157]
	v_pk_mul_f32 v[16:17], v[16:17], v[156:157]
	v_cvt_pk_bf16_f32 v248, v242, v243
	v_cvt_pk_bf16_f32 v249, v14, v15
	v_mov_b32_e32 v152, v155
	ds_write_b32 v234, v6 offset:8704
	ds_write_b32 v234, v16 offset:16896
	ds_write_b32 v234, v138 offset:33280
	ds_write_b32 v234, v7 offset:8960
	ds_write_b32 v234, v17 offset:17152
	ds_write_b32 v234, v139 offset:33536
	ds_write_b16 v235, v248 offset:512
	ds_write_b16_d16_hi v235, v248 offset:768
	ds_write_b16 v235, v249 offset:640
	ds_write_b16_d16_hi v235, v249 offset:896
	s_lshl_b32 s12, s0, 5
	s_lshl_b32 s13, s17, 3
	s_add_i32 s12, s12, s13
	s_add_i32 s12, s12, 2
	s_sub_i32 s67, 0xfff, s12
	s_cmp_eq_u32 s16, 0
	s_cselect_b32 s13, s12, s67
	s_add_i32 s13, s13, s5
	s_lshl_b32 s13, s13, 6
	s_add_u32 s72, s22, s13
	s_addc_u32 s73, s23, 0
	s_add_i32 s12, s12, 1
	s_sub_i32 s67, 0xfff, s12
	s_cmp_eq_u32 s16, 0
	s_cselect_b32 s13, s12, s67
	s_add_i32 s13, s13, s5
	s_lshl_b32 s13, s13, 6
	s_add_u32 s74, s22, s13
	s_addc_u32 s75, s23, 0
	s_mov_b64 exec, 1
	ds_write_b32 v236, v244 offset:49168
	ds_write_b32 v236, v245 offset:49176
	s_mov_b64 exec, 0x40
	ds_write_b32 v236, v32 offset:49172
	s_mov_b64 exec, 0x80
	ds_write_b32 v236, v32 offset:49180
	s_mov_b64 exec, 4
	global_store_dword v1, v32, s[72:73]
	s_mov_b64 exec, 8
	global_store_dword v1, v32, s[74:75]
	s_mov_b64 exec, -1
	ds_read_b32 v2, v68 offset:1088
	ds_read_b32 v3, v68 offset:1360
	ds_read_b32 v4, v68 offset:3264
	ds_read_b32 v5, v68 offset:3536
	v_pk_mul_f32 v[12:13], v[132:133], v[48:49] op_sel_hi:[1,0]
	v_pk_mul_f32 v[18:19], v[12:13], v[12:13]
	s_waitcnt lgkmcnt(0)
	v_pk_add_f32 v[2:3], v[2:3], v[54:55] op_sel_hi:[1,0]
	v_pk_add_f32 v[4:5], v[4:5], v[56:57] op_sel_hi:[1,0]
	v_pk_mul_f32 v[6:7], v[2:3], v[34:35] op_sel_hi:[1,0]
	v_pk_mul_f32 v[10:11], v[4:5], v[34:35] op_sel_hi:[1,0]
	v_exp_f32_e32 v6, v6
	v_exp_f32_e32 v7, v7
	v_exp_f32_e32 v10, v10
	v_exp_f32_e32 v11, v11
	v_pk_add_f32 v[6:7], v[6:7], v[50:51] op_sel:[0,1] op_sel_hi:[1,1]
	v_pk_add_f32 v[10:11], v[10:11], v[50:51] op_sel:[0,1] op_sel_hi:[1,1]
	v_rcp_f32_e32 v6, v6
	v_rcp_f32_e32 v7, v7
	v_rcp_f32_e32 v10, v10
	v_rcp_f32_e32 v11, v11
	v_pk_mul_f32 v[8:9], v[6:7], v[144:145] op_sel_hi:[1,0]
	v_exp_f32_e32 v8, v8
	v_exp_f32_e32 v9, v9
	v_mul_f32_e32 v153, v152, v8
	v_mov_b32_e32 v154, v153
	v_mul_f32_e32 v155, v153, v9
	v_rcp_f32_e32 v156, v154
	v_rcp_f32_e32 v157, v155
	v_pk_add_f32 v[14:15], v[10:11], v[146:147] op_sel_hi:[1,0]
	v_pk_fma_f32 v[14:15], v[14:15], v[50:51], v[50:51] op_sel:[0,0,1] op_sel_hi:[1,0,1]
	v_pk_mul_f32 v[16:17], v[132:133], v[14:15]
	v_pk_mul_f32 v[20:21], v[124:125], v[16:17]
	v_pk_mul_f32 v[22:23], v[20:21], v[52:53] op_sel_hi:[1,0]
	v_pk_mul_f32 v[24:25], v[12:13], v[10:11]
	v_pk_mul_f32 v[24:25], v[24:25], v[124:125]
	v_add_f32_dpp v18, v18, v18 quad_perm:[1,0,3,2] row_mask:0xf bank_mask:0xf
	v_add_f32_dpp v19, v19, v19 quad_perm:[1,0,3,2] row_mask:0xf bank_mask:0xf
	v_add_f32_dpp v22, v22, v22 quad_perm:[1,0,3,2] row_mask:0xf bank_mask:0xf
	v_add_f32_dpp v23, v23, v23 quad_perm:[1,0,3,2] row_mask:0xf bank_mask:0xf
	v_add_f32_dpp v24, v24, v24 quad_perm:[1,0,3,2] row_mask:0xf bank_mask:0xf
	v_add_f32_dpp v25, v25, v25 quad_perm:[1,0,3,2] row_mask:0xf bank_mask:0xf
	v_add_f32_dpp v20, v20, v20 quad_perm:[1,0,3,2] row_mask:0xf bank_mask:0xf
	v_add_f32_dpp v21, v21, v21 quad_perm:[1,0,3,2] row_mask:0xf bank_mask:0xf
	v_cndmask_b32_e64 v26, v18, v19, s[24:25]
	v_cndmask_b32_e64 v27, v22, v23, s[24:25]
	v_cndmask_b32_e64 v28, v24, v25, s[24:25]
	v_cndmask_b32_e64 v29, v20, v21, s[24:25]
	v_add_f32_dpp v26, v26, v26 quad_perm:[2,3,0,1] row_mask:0xf bank_mask:0xf
	v_add_f32_dpp v27, v27, v27 quad_perm:[2,3,0,1] row_mask:0xf bank_mask:0xf
	v_add_f32_dpp v28, v28, v28 quad_perm:[2,3,0,1] row_mask:0xf bank_mask:0xf
	v_add_f32_dpp v29, v29, v29 quad_perm:[2,3,0,1] row_mask:0xf bank_mask:0xf
	v_cndmask_b32_e64 v30, v26, v27, s[26:27]
	v_cndmask_b32_e64 v31, v28, v29, s[26:27]
	s_nop 0
	v_add_f32_dpp v30, v30, v30 row_ror:4 row_mask:0xf bank_mask:0xf
	v_add_f32_dpp v31, v31, v31 row_ror:4 row_mask:0xf bank_mask:0xf
	v_cndmask_b32_e64 v32, v30, v31, s[28:29]
	s_nop 1
	v_add_f32_dpp v32, v32, v32 row_ror:8 row_mask:0xf bank_mask:0xf
	v_mov_b32_e32 v33, v32
	s_nop 1
	v_permlane16_swap_b32 v33, v32
	v_add_f32_e32 v32, v33, v32
	v_mov_b32_e32 v33, v32
	s_nop 1
	v_permlane32_swap_b32 v33, v32
	v_add_f32_e32 v32, v33, v32
	s_nop 1
	v_mov_b32_dpp v246, v32 row_newbcast:0 row_mask:0xf bank_mask:0xf
	v_mov_b32_dpp v247, v32 row_newbcast:1 row_mask:0xf bank_mask:0xf
; __device__ __forceinline__ void phase_rwkv_scan(const Params& p, int l, const int tidx) {
;     ...
;           float kkr = uk[q] * kks;
;           float ss = wave_sum(kkr * kkr);
;           float kk = kkr * __builtin_amdgcn_rcpf(fmaxf(sqrtf(ss), 1e-12f));
;           float kd = uk[q] * (1.f + (av - 1.f) * kap);
;           float bt = wave_sum(ur[q] * kd * rkj);
;           float c1 = wave_sum(kk * av * ur[q]);
;           float c2 = wave_sum(kd * ur[q]);
;           nbw[s * 64 + j] = dec;
;           nbw[1 * VSZ + s * 64 + j] = kk * av;
;           nbw[2 * VSZ + s * 64 + j] = kd;
;           ((bf16_t*)(nbw + 3 * VSZ))[s * 128 + j] = f2bf(kk);
;           ((bf16_t*)(nbw + 3 * VSZ))[s * 128 + 64 + j] = f2bf(dec * ur[q]);
;           nbw[4 * VSZ + s * 64 + j] = uv[q];
;           if (lane == 1) *(float2*)(nbw + 6 * VSZ + 2 * s) = float2{c1, c2};
;           if (lane == 0) {
;             int tau = pc * RTC + s;
;             int t = dir ? (4095 - tau) : tau;
;             beta[(size_t)(b * SEQ + t) * 16 + h] = bt;
;           }
	v_sqrt_f32_e32 v240, v246
	v_sqrt_f32_e32 v241, v247
	v_add_u32_e32 v248, -1, v240
	v_fma_f32 v249, -v248, v240, v246
	v_cmp_ge_f32_e64 s[12:13], 0, v249
	v_add_u32_e32 v249, 1, v240
	s_nop 0
	v_cndmask_b32_e64 v248, v240, v248, s[12:13]
	v_fma_f32 v240, -v249, v240, v246
	v_cmp_lt_f32_e64 s[12:13], 0, v240
	s_nop 1
	v_cndmask_b32_e64 v240, v248, v249, s[12:13]
	v_add_u32_e32 v248, -1, v241
	v_fma_f32 v249, -v248, v241, v247
	v_cmp_ge_f32_e64 s[12:13], 0, v249
	v_add_u32_e32 v249, 1, v241
	s_nop 0
	v_cndmask_b32_e64 v248, v241, v248, s[12:13]
	v_fma_f32 v241, -v249, v241, v247
	v_cmp_lt_f32_e64 s[12:13], 0, v241
	s_nop 1
	v_cndmask_b32_e64 v241, v248, v249, s[12:13]
	v_max_f32_e32 v240, 0x2b8cbccc, v240
	v_max_f32_e32 v241, 0x2b8cbccc, v241
	v_rcp_f32_e32 v238, v240
	v_rcp_f32_e32 v239, v241
	s_nop 0
	v_pk_mul_f32 v[242:243], v[12:13], v[238:239]
	v_mul_f32_dpp v244, v32, v238 row_newbcast:4 row_mask:0xf bank_mask:0xf
	v_mul_f32_dpp v245, v32, v239 row_newbcast:5 row_mask:0xf bank_mask:0xf
	v_pk_mul_f32 v[6:7], v[242:243], v[10:11]
	v_pk_mul_f32 v[14:15], v[154:155], v[124:125]
	v_pk_mul_f32 v[242:243], v[242:243], v[152:153]
	v_pk_mul_f32 v[6:7], v[6:7], v[156:157]
	v_pk_mul_f32 v[16:17], v[16:17], v[156:157]
	v_cvt_pk_bf16_f32 v248, v242, v243
	v_cvt_pk_bf16_f32 v249, v14, v15
	v_mov_b32_e32 v152, v155
	ds_write_b32 v234, v6 offset:9216
	ds_write_b32 v234, v16 offset:17408
	ds_write_b32 v234, v140 offset:33792
	ds_write_b32 v234, v7 offset:9472
	ds_write_b32 v234, v17 offset:17664
	ds_write_b32 v234, v141 offset:34048
	ds_write_b16 v235, v248 offset:1024
	ds_write_b16_d16_hi v235, v248 offset:1280
	ds_write_b16 v235, v249 offset:1152
	ds_write_b16_d16_hi v235, v249 offset:1408
	s_lshl_b32 s12, s0, 5
	s_lshl_b32 s13, s17, 3
	s_add_i32 s12, s12, s13
	s_add_i32 s12, s12, 4
	s_sub_i32 s67, 0xfff, s12
	s_cmp_eq_u32 s16, 0
	s_cselect_b32 s13, s12, s67
	s_add_i32 s13, s13, s5
	s_lshl_b32 s13, s13, 6
	s_add_u32 s72, s22, s13
	s_addc_u32 s73, s23, 0
	s_add_i32 s12, s12, 1
	s_sub_i32 s67, 0xfff, s12
	s_cmp_eq_u32 s16, 0
	s_cselect_b32 s13, s12, s67
	s_add_i32 s13, s13, s5
	s_lshl_b32 s13, s13, 6
	s_add_u32 s74, s22, s13
	s_addc_u32 s75, s23, 0
	s_mov_b64 exec, 1
	ds_write_b32 v236, v244 offset:49184
	ds_write_b32 v236, v245 offset:49192
	s_mov_b64 exec, 0x40
	ds_write_b32 v236, v32 offset:49188
	s_mov_b64 exec, 0x80
	ds_write_b32 v236, v32 offset:49196
	s_mov_b64 exec, 4
	global_store_dword v1, v32, s[72:73]
	s_mov_b64 exec, 8
	global_store_dword v1, v32, s[74:75]
	s_mov_b64 exec, -1
	ds_read_b32 v2, v68 offset:1632
	ds_read_b32 v3, v68 offset:1904
	ds_read_b32 v4, v68 offset:3808
	ds_read_b32 v5, v68 offset:4080
	v_pk_mul_f32 v[12:13], v[134:135], v[48:49] op_sel_hi:[1,0]
	v_pk_mul_f32 v[18:19], v[12:13], v[12:13]
	s_waitcnt lgkmcnt(0)
	v_pk_add_f32 v[2:3], v[2:3], v[54:55] op_sel_hi:[1,0]
	v_pk_add_f32 v[4:5], v[4:5], v[56:57] op_sel_hi:[1,0]
	v_pk_mul_f32 v[6:7], v[2:3], v[34:35] op_sel_hi:[1,0]
	v_pk_mul_f32 v[10:11], v[4:5], v[34:35] op_sel_hi:[1,0]
	v_exp_f32_e32 v6, v6
	v_exp_f32_e32 v7, v7
	v_exp_f32_e32 v10, v10
	v_exp_f32_e32 v11, v11
	v_pk_add_f32 v[6:7], v[6:7], v[50:51] op_sel:[0,1] op_sel_hi:[1,1]
	v_pk_add_f32 v[10:11], v[10:11], v[50:51] op_sel:[0,1] op_sel_hi:[1,1]
	v_rcp_f32_e32 v6, v6
	v_rcp_f32_e32 v7, v7
	v_rcp_f32_e32 v10, v10
	v_rcp_f32_e32 v11, v11
	v_pk_mul_f32 v[8:9], v[6:7], v[144:145] op_sel_hi:[1,0]
	v_exp_f32_e32 v8, v8
	v_exp_f32_e32 v9, v9
	v_mul_f32_e32 v153, v152, v8
	v_mov_b32_e32 v154, v153
	v_mul_f32_e32 v155, v153, v9
	v_rcp_f32_e32 v156, v154
	v_rcp_f32_e32 v157, v155
	v_pk_add_f32 v[14:15], v[10:11], v[146:147] op_sel_hi:[1,0]
	v_pk_fma_f32 v[14:15], v[14:15], v[50:51], v[50:51] op_sel:[0,0,1] op_sel_hi:[1,0,1]
	v_pk_mul_f32 v[16:17], v[134:135], v[14:15]
	v_pk_mul_f32 v[20:21], v[126:127], v[16:17]
	v_pk_mul_f32 v[22:23], v[20:21], v[52:53] op_sel_hi:[1,0]
	v_pk_mul_f32 v[24:25], v[12:13], v[10:11]
	v_pk_mul_f32 v[24:25], v[24:25], v[126:127]
	v_add_f32_dpp v18, v18, v18 quad_perm:[1,0,3,2] row_mask:0xf bank_mask:0xf
	v_add_f32_dpp v19, v19, v19 quad_perm:[1,0,3,2] row_mask:0xf bank_mask:0xf
	v_add_f32_dpp v22, v22, v22 quad_perm:[1,0,3,2] row_mask:0xf bank_mask:0xf
	v_add_f32_dpp v23, v23, v23 quad_perm:[1,0,3,2] row_mask:0xf bank_mask:0xf
	v_add_f32_dpp v24, v24, v24 quad_perm:[1,0,3,2] row_mask:0xf bank_mask:0xf
	v_add_f32_dpp v25, v25, v25 quad_perm:[1,0,3,2] row_mask:0xf bank_mask:0xf
	v_add_f32_dpp v20, v20, v20 quad_perm:[1,0,3,2] row_mask:0xf bank_mask:0xf
	v_add_f32_dpp v21, v21, v21 quad_perm:[1,0,3,2] row_mask:0xf bank_mask:0xf
	v_cndmask_b32_e64 v26, v18, v19, s[24:25]
	v_cndmask_b32_e64 v27, v22, v23, s[24:25]
	v_cndmask_b32_e64 v28, v24, v25, s[24:25]
	v_cndmask_b32_e64 v29, v20, v21, s[24:25]
	v_add_f32_dpp v26, v26, v26 quad_perm:[2,3,0,1] row_mask:0xf bank_mask:0xf
	v_add_f32_dpp v27, v27, v27 quad_perm:[2,3,0,1] row_mask:0xf bank_mask:0xf
	v_add_f32_dpp v28, v28, v28 quad_perm:[2,3,0,1] row_mask:0xf bank_mask:0xf
	v_add_f32_dpp v29, v29, v29 quad_perm:[2,3,0,1] row_mask:0xf bank_mask:0xf
	v_cndmask_b32_e64 v30, v26, v27, s[26:27]
	v_cndmask_b32_e64 v31, v28, v29, s[26:27]
	s_nop 0
	v_add_f32_dpp v30, v30, v30 row_ror:4 row_mask:0xf bank_mask:0xf
	v_add_f32_dpp v31, v31, v31 row_ror:4 row_mask:0xf bank_mask:0xf
	v_cndmask_b32_e64 v32, v30, v31, s[28:29]
	s_nop 1
	v_add_f32_dpp v32, v32, v32 row_ror:8 row_mask:0xf bank_mask:0xf
	v_mov_b32_e32 v33, v32
	s_nop 1
	v_permlane16_swap_b32 v33, v32
	v_add_f32_e32 v32, v33, v32
	v_mov_b32_e32 v33, v32
	s_nop 1
	v_permlane32_swap_b32 v33, v32
	v_add_f32_e32 v32, v33, v32
	s_nop 1
	v_mov_b32_dpp v246, v32 row_newbcast:0 row_mask:0xf bank_mask:0xf
; __device__ __forceinline__ void phase_rwkv_scan(const Params& p, int l, const int tidx) {
;     ...
;           nbw[s * 64 + j] = dec;
;           nbw[1 * VSZ + s * 64 + j] = kk * av;
;           nbw[2 * VSZ + s * 64 + j] = kd;
;           ((bf16_t*)(nbw + 3 * VSZ))[s * 128 + j] = f2bf(kk);
;           ((bf16_t*)(nbw + 3 * VSZ))[s * 128 + 64 + j] = f2bf(dec * ur[q]);
;           nbw[4 * VSZ + s * 64 + j] = uv[q];
;           if (lane == 1) *(float2*)(nbw + 6 * VSZ + 2 * s) = float2{c1, c2};
;           if (lane == 0) {
;             int tau = pc * RTC + s;
;             int t = dir ? (4095 - tau) : tau;
;             beta[(size_t)(b * SEQ + t) * 16 + h] = bt;
;           }
;         }
;         __builtin_amdgcn_wave_barrier();
;       }
;       if (it >= 1) {
;         const float* py = sbuf + ((it - 1) & 1) * BUFSZ + 5 * VSZ;
; #pragma unroll
;         for (int q = 0; q < TPW; q++) {
;           int s = pw * TPW + q;
;           int tau = (it - 1) * RTC + s;
;           int t = dir ? (4095 - tau) : tau;
;           Y[(size_t)(b * SEQ + t) * 1024 + h * 64 + j] = f2bf(py[s * 64 + j]);
;         }
;       }
	v_mov_b32_dpp v247, v32 row_newbcast:1 row_mask:0xf bank_mask:0xf
	v_sqrt_f32_e32 v240, v246
	v_sqrt_f32_e32 v241, v247
	v_add_u32_e32 v248, -1, v240
	v_fma_f32 v249, -v248, v240, v246
	v_cmp_ge_f32_e64 s[12:13], 0, v249
	v_add_u32_e32 v249, 1, v240
	s_nop 0
	v_cndmask_b32_e64 v248, v240, v248, s[12:13]
	v_fma_f32 v240, -v249, v240, v246
	v_cmp_lt_f32_e64 s[12:13], 0, v240
	s_nop 1
	v_cndmask_b32_e64 v240, v248, v249, s[12:13]
	v_add_u32_e32 v248, -1, v241
	v_fma_f32 v249, -v248, v241, v247
	v_cmp_ge_f32_e64 s[12:13], 0, v249
	v_add_u32_e32 v249, 1, v241
	s_nop 0
	v_cndmask_b32_e64 v248, v241, v248, s[12:13]
	v_fma_f32 v241, -v249, v241, v247
	v_cmp_lt_f32_e64 s[12:13], 0, v241
	s_nop 1
	v_cndmask_b32_e64 v241, v248, v249, s[12:13]
	v_max_f32_e32 v240, 0x2b8cbccc, v240
	v_max_f32_e32 v241, 0x2b8cbccc, v241
	v_rcp_f32_e32 v238, v240
	v_rcp_f32_e32 v239, v241
	s_nop 0
	v_pk_mul_f32 v[242:243], v[12:13], v[238:239]
	v_mul_f32_dpp v244, v32, v238 row_newbcast:4 row_mask:0xf bank_mask:0xf
	v_mul_f32_dpp v245, v32, v239 row_newbcast:5 row_mask:0xf bank_mask:0xf
	v_pk_mul_f32 v[6:7], v[242:243], v[10:11]
	v_pk_mul_f32 v[14:15], v[154:155], v[126:127]
	v_pk_mul_f32 v[242:243], v[242:243], v[152:153]
	v_pk_mul_f32 v[6:7], v[6:7], v[156:157]
	v_pk_mul_f32 v[16:17], v[16:17], v[156:157]
	v_cvt_pk_bf16_f32 v248, v242, v243
	v_cvt_pk_bf16_f32 v249, v14, v15
	ds_write_b32 v234, v155 offset:1792
	v_mov_b32_e32 v152, v155
	ds_write_b32 v234, v6 offset:9728
	ds_write_b32 v234, v16 offset:17920
	ds_write_b32 v234, v142 offset:34304
	ds_write_b32 v234, v7 offset:9984
	ds_write_b32 v234, v17 offset:18176
	ds_write_b32 v234, v143 offset:34560
	ds_write_b16 v235, v248 offset:1536
	ds_write_b16_d16_hi v235, v248 offset:1792
	ds_write_b16 v235, v249 offset:1664
	ds_write_b16_d16_hi v235, v249 offset:1920
	s_lshl_b32 s12, s0, 5
	s_lshl_b32 s13, s17, 3
	s_add_i32 s12, s12, s13
	s_add_i32 s12, s12, 6
	s_sub_i32 s67, 0xfff, s12
	s_cmp_eq_u32 s16, 0
	s_cselect_b32 s13, s12, s67
	s_add_i32 s13, s13, s5
	s_lshl_b32 s13, s13, 6
	s_add_u32 s72, s22, s13
	s_addc_u32 s73, s23, 0
	s_add_i32 s12, s12, 1
	s_sub_i32 s67, 0xfff, s12
	s_cmp_eq_u32 s16, 0
	s_cselect_b32 s13, s12, s67
	s_add_i32 s13, s13, s5
	s_lshl_b32 s13, s13, 6
	s_add_u32 s74, s22, s13
	s_addc_u32 s75, s23, 0
	s_mov_b64 exec, 1
	ds_write_b32 v236, v244 offset:49200
	ds_write_b32 v236, v245 offset:49208
	s_mov_b64 exec, 0x40
	ds_write_b32 v236, v32 offset:49204
	s_mov_b64 exec, 0x80
	ds_write_b32 v236, v32 offset:49212
	s_mov_b64 exec, 4
	global_store_dword v1, v32, s[72:73]
	s_mov_b64 exec, 8
	global_store_dword v1, v32, s[74:75]
	s_mov_b64 exec, -1
.Lrp_noprep:
	s_cmpk_lt_i32 s0, 2
	s_cbranch_scc1 .Lrp_noyout
	ds_read_b32 v238, v237 offset:0
	ds_read_b32 v239, v237 offset:256
	s_sub_i32 s12, s0, 2
	s_lshl_b32 s12, s12, 5
	s_lshl_b32 s13, s17, 3
	s_add_i32 s12, s12, s13
	s_add_i32 s12, s12, 0
	s_sub_i32 s67, 0xfff, s12
	s_cmp_eq_u32 s16, 0
	s_cselect_b32 s13, s12, s67
	s_add_i32 s13, s13, s5
	s_lshl_b32 s13, s13, 11
	s_add_u32 s72, s20, s13
	s_addc_u32 s73, s21, 0
	s_add_i32 s12, s12, 1
	s_sub_i32 s67, 0xfff, s12
	s_cmp_eq_u32 s16, 0
	s_cselect_b32 s13, s12, s67
	s_add_i32 s13, s13, s5
	s_lshl_b32 s13, s13, 11
	s_add_u32 s74, s20, s13
	s_addc_u32 s75, s21, 0
	s_waitcnt lgkmcnt(0)
	v_cvt_pk_bf16_f32 v240, v238, v239
	global_store_short v63, v240, s[72:73]
	global_store_short_d16_hi v63, v240, s[74:75]
	ds_read_b32 v238, v237 offset:512
	ds_read_b32 v239, v237 offset:768
	s_sub_i32 s12, s0, 2
	s_lshl_b32 s12, s12, 5
	s_lshl_b32 s13, s17, 3
	s_add_i32 s12, s12, s13
	s_add_i32 s12, s12, 2
	s_sub_i32 s67, 0xfff, s12
	s_cmp_eq_u32 s16, 0
	s_cselect_b32 s13, s12, s67
	s_add_i32 s13, s13, s5
	s_lshl_b32 s13, s13, 11
	s_add_u32 s72, s20, s13
	s_addc_u32 s73, s21, 0
	s_add_i32 s12, s12, 1
	s_sub_i32 s67, 0xfff, s12
	s_cmp_eq_u32 s16, 0
	s_cselect_b32 s13, s12, s67
	s_add_i32 s13, s13, s5
	s_lshl_b32 s13, s13, 11
	s_add_u32 s74, s20, s13
	s_addc_u32 s75, s21, 0
	s_waitcnt lgkmcnt(0)
	v_cvt_pk_bf16_f32 v240, v238, v239
	global_store_short v63, v240, s[72:73]
	global_store_short_d16_hi v63, v240, s[74:75]
	ds_read_b32 v238, v237 offset:1024
	ds_read_b32 v239, v237 offset:1280
	s_sub_i32 s12, s0, 2
	s_lshl_b32 s12, s12, 5
	s_lshl_b32 s13, s17, 3
	s_add_i32 s12, s12, s13
	s_add_i32 s12, s12, 4
	s_sub_i32 s67, 0xfff, s12
	s_cmp_eq_u32 s16, 0
	s_cselect_b32 s13, s12, s67
	s_add_i32 s13, s13, s5
	s_lshl_b32 s13, s13, 11
	s_add_u32 s72, s20, s13
	s_addc_u32 s73, s21, 0
	s_add_i32 s12, s12, 1
	s_sub_i32 s67, 0xfff, s12
	s_cmp_eq_u32 s16, 0
	s_cselect_b32 s13, s12, s67
	s_add_i32 s13, s13, s5
	s_lshl_b32 s13, s13, 11
	s_add_u32 s74, s20, s13
	s_addc_u32 s75, s21, 0
	s_waitcnt lgkmcnt(0)
	v_cvt_pk_bf16_f32 v240, v238, v239
	global_store_short v63, v240, s[72:73]
	global_store_short_d16_hi v63, v240, s[74:75]
	ds_read_b32 v238, v237 offset:1536
	ds_read_b32 v239, v237 offset:1792
	s_sub_i32 s12, s0, 2
	s_lshl_b32 s12, s12, 5
	s_lshl_b32 s13, s17, 3
	s_add_i32 s12, s12, s13
	s_add_i32 s12, s12, 6
	s_sub_i32 s67, 0xfff, s12
	s_cmp_eq_u32 s16, 0
	s_cselect_b32 s13, s12, s67
	s_add_i32 s13, s13, s5
	s_lshl_b32 s13, s13, 11
	s_add_u32 s72, s20, s13
	s_addc_u32 s73, s21, 0
	s_add_i32 s12, s12, 1
	s_sub_i32 s67, 0xfff, s12
	s_cmp_eq_u32 s16, 0
	s_cselect_b32 s13, s12, s67
	s_add_i32 s13, s13, s5
	s_lshl_b32 s13, s13, 11
	s_add_u32 s74, s20, s13
	s_addc_u32 s75, s21, 0
	s_waitcnt lgkmcnt(0)
	v_cvt_pk_bf16_f32 v240, v238, v239
	global_store_short v63, v240, s[72:73]
	global_store_short_d16_hi v63, v240, s[74:75]
; __device__ __forceinline__ void phase_rwkv_scan(const Params& p, int l, const int tidx) {
;     ...
;       if (it >= 1) {
;         const float* py = sbuf + ((it - 1) & 1) * BUFSZ + 5 * VSZ;
; #pragma unroll
;         for (int q = 0; q < TPW; q++) {
;           int s = pw * TPW + q;
;           int tau = (it - 1) * RTC + s;
;           int t = dir ? (4095 - tau) : tau;
;           Y[(size_t)(b * SEQ + t) * 1024 + h * 64 + j] = f2bf(py[s * 64 + j]);
;         }
;       }
;       __syncthreads();
;     }
;     ...
;     {
;       const float* py = sbuf + ((NCH - 1) & 1) * BUFSZ + 5 * VSZ;
; #pragma unroll
;       for (int q = 0; q < TPW; q++) {
;         int s = pw * TPW + q;
;         int tau = (NCH - 1) * RTC + s;
;         int t = dir ? (4095 - tau) : tau;
;         Y[(size_t)(b * SEQ + t) * 1024 + h * 64 + j] = f2bf(py[s * 64 + j]);
;       }
;     }
.Lrp_noyout:
	s_add_i32 s0, s0, 1
	s_cmpk_eq_i32 s0, 0x81
	s_waitcnt lgkmcnt(0)
	s_barrier
	s_cbranch_scc0 .Lrp_loop
	s_lshl_b32 s12, s17, 11
	s_add_u32 s12, s12, 0xc100
	v_add_u32_e32 v237, s12, v64
	v_add_u32_e32 v237, 0xa000, v237
	ds_read_b32 v238, v237 offset:0
	ds_read_b32 v239, v237 offset:256
	s_sub_i32 s12, s0, 2
	s_lshl_b32 s12, s12, 5
	s_lshl_b32 s13, s17, 3
	s_add_i32 s12, s12, s13
	s_add_i32 s12, s12, 0
	s_sub_i32 s67, 0xfff, s12
	s_cmp_eq_u32 s16, 0
	s_cselect_b32 s13, s12, s67
	s_add_i32 s13, s13, s5
	s_lshl_b32 s13, s13, 11
	s_add_u32 s72, s20, s13
	s_addc_u32 s73, s21, 0
	s_add_i32 s12, s12, 1
	s_sub_i32 s67, 0xfff, s12
	s_cmp_eq_u32 s16, 0
	s_cselect_b32 s13, s12, s67
	s_add_i32 s13, s13, s5
	s_lshl_b32 s13, s13, 11
	s_add_u32 s74, s20, s13
	s_addc_u32 s75, s21, 0
	s_waitcnt lgkmcnt(0)
	v_cvt_pk_bf16_f32 v240, v238, v239
	global_store_short v63, v240, s[72:73]
	global_store_short_d16_hi v63, v240, s[74:75]
	ds_read_b32 v238, v237 offset:512
	ds_read_b32 v239, v237 offset:768
	s_sub_i32 s12, s0, 2
	s_lshl_b32 s12, s12, 5
	s_lshl_b32 s13, s17, 3
	s_add_i32 s12, s12, s13
	s_add_i32 s12, s12, 2
	s_sub_i32 s67, 0xfff, s12
	s_cmp_eq_u32 s16, 0
	s_cselect_b32 s13, s12, s67
	s_add_i32 s13, s13, s5
	s_lshl_b32 s13, s13, 11
	s_add_u32 s72, s20, s13
	s_addc_u32 s73, s21, 0
	s_add_i32 s12, s12, 1
	s_sub_i32 s67, 0xfff, s12
	s_cmp_eq_u32 s16, 0
	s_cselect_b32 s13, s12, s67
	s_add_i32 s13, s13, s5
	s_lshl_b32 s13, s13, 11
	s_add_u32 s74, s20, s13
	s_addc_u32 s75, s21, 0
	s_waitcnt lgkmcnt(0)
	v_cvt_pk_bf16_f32 v240, v238, v239
	global_store_short v63, v240, s[72:73]
	global_store_short_d16_hi v63, v240, s[74:75]
	ds_read_b32 v238, v237 offset:1024
	ds_read_b32 v239, v237 offset:1280
	s_sub_i32 s12, s0, 2
	s_lshl_b32 s12, s12, 5
	s_lshl_b32 s13, s17, 3
	s_add_i32 s12, s12, s13
	s_add_i32 s12, s12, 4
	s_sub_i32 s67, 0xfff, s12
	s_cmp_eq_u32 s16, 0
	s_cselect_b32 s13, s12, s67
	s_add_i32 s13, s13, s5
	s_lshl_b32 s13, s13, 11
	s_add_u32 s72, s20, s13
	s_addc_u32 s73, s21, 0
	s_add_i32 s12, s12, 1
	s_sub_i32 s67, 0xfff, s12
	s_cmp_eq_u32 s16, 0
	s_cselect_b32 s13, s12, s67
	s_add_i32 s13, s13, s5
	s_lshl_b32 s13, s13, 11
	s_add_u32 s74, s20, s13
	s_addc_u32 s75, s21, 0
	s_waitcnt lgkmcnt(0)
	v_cvt_pk_bf16_f32 v240, v238, v239
	global_store_short v63, v240, s[72:73]
	global_store_short_d16_hi v63, v240, s[74:75]
	ds_read_b32 v238, v237 offset:1536
	ds_read_b32 v239, v237 offset:1792
	s_sub_i32 s12, s0, 2
	s_lshl_b32 s12, s12, 5
	s_lshl_b32 s13, s17, 3
	s_add_i32 s12, s12, s13
	s_add_i32 s12, s12, 6
	s_sub_i32 s67, 0xfff, s12
	s_cmp_eq_u32 s16, 0
	s_cselect_b32 s13, s12, s67
	s_add_i32 s13, s13, s5
	s_lshl_b32 s13, s13, 11
	s_add_u32 s72, s20, s13
	s_addc_u32 s73, s21, 0
	s_add_i32 s12, s12, 1
	s_sub_i32 s67, 0xfff, s12
	s_cmp_eq_u32 s16, 0
	s_cselect_b32 s13, s12, s67
	s_add_i32 s13, s13, s5
	s_lshl_b32 s13, s13, 11
	s_add_u32 s74, s20, s13
	s_addc_u32 s75, s21, 0
	s_waitcnt lgkmcnt(0)
	v_cvt_pk_bf16_f32 v240, v238, v239
	global_store_short v63, v240, s[72:73]
	global_store_short_d16_hi v63, v240, s[74:75]

; __device__ __forceinline__ void phase_rwkv_scan(const Params& p, int l, const int tidx) {
;     ...
;       for (int s = 0; s < RTC; s++) {
;         const bf16x8 A0 = nA0, A1 = nA1;
;         const float wA[8] = {nw0.x, nw0.y, nw0.z, nw0.w, nw1.x, nw1.y, nw1.z, nw1.w};
;         const float wB[8] = {nw2.x, nw2.y, nw2.z, nw2.w, nw3.x, nw3.y, nw3.z, nw3.w};
;         const float kaA[8] = {nka0.x, nka0.y, nka0.z, nka0.w, nka1.x, nka1.y, nka1.z, nka1.w};
;         const float kaB[8] = {nka2.x, nka2.y, nka2.z, nka2.w, nka3.x, nka3.y, nka3.z, nka3.w};
;         const float kdA[8] = {nkd0.x, nkd0.y, nkd0.z, nkd0.w, nkd1.x, nkd1.y, nkd1.z, nkd1.w};
;         const float kdB[8] = {nkd2.x, nkd2.y, nkd2.z, nkd2.w, nkd3.x, nkd3.y, nkd3.z, nkd3.w};
;         const float v = nv;
;         float c1 = nc.x, c2 = nc.y;
;         asm volatile("" : "+v"(c1), "+v"(c2));
;         if (s + 1 < RTC) RW_LD(s + 1);
;         u32x4 pa = {pack2(Sa[0], Sa[1]), pack2(Sa[2], Sa[3]), pack2(Sa[4], Sa[5]), pack2(Sa[6], Sa[7])};
;         u32x4 pb = {pack2(Sb[0], Sb[1]), pack2(Sb[2], Sb[3]), pack2(Sb[4], Sb[5]), pack2(Sb[6], Sb[7])};
;         f32x4 acc = {0.f, 0.f, 0.f, 0.f};
;         acc = __builtin_amdgcn_mfma_f32_16x16x32_bf16(A0, __builtin_bit_cast(bf16x8, pa), acc, 0, 0, 0);
;         acc = __builtin_amdgcn_mfma_f32_16x16x32_bf16(A1, __builtin_bit_cast(bf16x8, pb), acc, 0, 0, 0);
;         float tA[8], tB[8];
; #pragma unroll
;         for (int c = 0; c < 8; c++) { tA[c] = Sa[c] * wA[c] + v * kdA[c]; tB[c] = Sb[c] * wB[c] + v * kdB[c]; }
;         const float sa = -acc[0];
;         const float yq = acc[1];
; #pragma unroll
;         for (int c = 0; c < 8; c++) { Sa[c] = tA[c] + sa * kaA[c]; Sb[c] = tB[c] + sa * kaB[c]; }
;         const float y = yq + sa * c1 + v * c2;
;         if (quad == 0) by[s * 64 + row] = y;
;       }
.Lrw_chunk:
	s_bitcmp1_b32 s0, 0
	s_cselect_b32 s10, 0xc100, 0
	v_add_u32_e32 v104, s10, v100
	v_add_u32_e32 v105, s10, v101
	v_add_u32_e32 v106, s10, v102
	v_add_u32_e32 v107, s10, v103
	v_mov_b32_e32 v108, s10
	ds_read_b128 v[40:43], v104 offset:0
	ds_read_b128 v[44:47], v104 offset:16
	ds_read_b32 v65, v105 offset:16384
	ds_read_b32 v66, v107 offset:0
	ds_read_b32 v48, v105 offset:8192
	ds_read_b64 v[68:69], v108 offset:49152
	v_cvt_pk_bf16_f32 v24, v8, v9
	v_cvt_pk_bf16_f32 v25, v10, v11
	v_cvt_pk_bf16_f32 v26, v12, v13
	v_cvt_pk_bf16_f32 v27, v14, v15
	v_cvt_pk_bf16_f32 v28, v16, v17
	v_cvt_pk_bf16_f32 v29, v18, v19
	s_waitcnt lgkmcnt(5)
	v_mfma_f32_16x16x32_bf16 v[32:35], v[40:43], v[24:27], 0
	v_cvt_pk_bf16_f32 v30, v20, v21
	v_cvt_pk_bf16_f32 v31, v22, v23
	s_waitcnt lgkmcnt(2)
	v_fmac_f32_dpp v8, v65, v66 row_newbcast:0 row_mask:0xf bank_mask:0xf
	v_fmac_f32_dpp v9, v65, v66 row_newbcast:1 row_mask:0xf bank_mask:0xf
	v_mfma_f32_16x16x32_bf16 v[32:35], v[44:47], v[28:31], v[32:35]
	v_fmac_f32_dpp v10, v65, v66 row_newbcast:2 row_mask:0xf bank_mask:0xf
	v_fmac_f32_dpp v11, v65, v66 row_newbcast:3 row_mask:0xf bank_mask:0xf
	ds_read_b128 v[70:73], v104 offset:256
	v_fmac_f32_dpp v12, v65, v66 row_newbcast:4 row_mask:0xf bank_mask:0xf
	v_fmac_f32_dpp v13, v65, v66 row_newbcast:5 row_mask:0xf bank_mask:0xf
	ds_read_b128 v[74:77], v104 offset:272
	v_fmac_f32_dpp v14, v65, v66 row_newbcast:6 row_mask:0xf bank_mask:0xf
	v_fmac_f32_dpp v15, v65, v66 row_newbcast:7 row_mask:0xf bank_mask:0xf
	ds_read_b32 v95, v105 offset:16640
	v_fmac_f32_dpp v16, v65, v66 row_newbcast:8 row_mask:0xf bank_mask:0xf
	v_fmac_f32_dpp v17, v65, v66 row_newbcast:9 row_mask:0xf bank_mask:0xf
	ds_read_b32 v96, v107 offset:256
	v_fmac_f32_dpp v18, v65, v66 row_newbcast:10 row_mask:0xf bank_mask:0xf
	v_fmac_f32_dpp v19, v65, v66 row_newbcast:11 row_mask:0xf bank_mask:0xf
	ds_read_b32 v78, v105 offset:8448
	v_fmac_f32_dpp v20, v65, v66 row_newbcast:12 row_mask:0xf bank_mask:0xf
	v_fmac_f32_dpp v21, v65, v66 row_newbcast:13 row_mask:0xf bank_mask:0xf
	ds_read_b64 v[98:99], v108 offset:49160
	v_fmac_f32_dpp v22, v65, v66 row_newbcast:14 row_mask:0xf bank_mask:0xf
	v_fmac_f32_dpp v23, v65, v66 row_newbcast:15 row_mask:0xf bank_mask:0xf
	s_waitcnt lgkmcnt(7)
	s_waitcnt lgkmcnt(6)
	v_xor_b32_e32 v110, 0x80000000, v32
	v_fma_f32 v109, -v32, v68, v33
	v_fma_f32 v109, v66, v69, v109
	v_fmac_f32_dpp v8, v48, v110 row_newbcast:0 row_mask:0xf bank_mask:0xf
	v_fmac_f32_dpp v9, v48, v110 row_newbcast:1 row_mask:0xf bank_mask:0xf
	v_fmac_f32_dpp v10, v48, v110 row_newbcast:2 row_mask:0xf bank_mask:0xf
	v_fmac_f32_dpp v11, v48, v110 row_newbcast:3 row_mask:0xf bank_mask:0xf
	v_fmac_f32_dpp v12, v48, v110 row_newbcast:4 row_mask:0xf bank_mask:0xf
	v_fmac_f32_dpp v13, v48, v110 row_newbcast:5 row_mask:0xf bank_mask:0xf
	v_fmac_f32_dpp v14, v48, v110 row_newbcast:6 row_mask:0xf bank_mask:0xf
	v_fmac_f32_dpp v15, v48, v110 row_newbcast:7 row_mask:0xf bank_mask:0xf
	v_fmac_f32_dpp v16, v48, v110 row_newbcast:8 row_mask:0xf bank_mask:0xf
	v_fmac_f32_dpp v17, v48, v110 row_newbcast:9 row_mask:0xf bank_mask:0xf
	v_fmac_f32_dpp v18, v48, v110 row_newbcast:10 row_mask:0xf bank_mask:0xf
	v_fmac_f32_dpp v19, v48, v110 row_newbcast:11 row_mask:0xf bank_mask:0xf
	v_fmac_f32_dpp v20, v48, v110 row_newbcast:12 row_mask:0xf bank_mask:0xf
	v_fmac_f32_dpp v21, v48, v110 row_newbcast:13 row_mask:0xf bank_mask:0xf
	v_fmac_f32_dpp v22, v48, v110 row_newbcast:14 row_mask:0xf bank_mask:0xf
	v_fmac_f32_dpp v23, v48, v110 row_newbcast:15 row_mask:0xf bank_mask:0xf
	ds_write_b32 v107, v109 offset:8192
	v_cvt_pk_bf16_f32 v24, v8, v9
	v_cvt_pk_bf16_f32 v25, v10, v11
	v_cvt_pk_bf16_f32 v26, v12, v13
	v_cvt_pk_bf16_f32 v27, v14, v15
	v_cvt_pk_bf16_f32 v28, v16, v17
	v_cvt_pk_bf16_f32 v29, v18, v19
	s_waitcnt lgkmcnt(6)
	v_mfma_f32_16x16x32_bf16 v[32:35], v[70:73], v[24:27], 0
	v_cvt_pk_bf16_f32 v30, v20, v21
	v_cvt_pk_bf16_f32 v31, v22, v23
	s_waitcnt lgkmcnt(3)
	v_fmac_f32_dpp v8, v95, v96 row_newbcast:0 row_mask:0xf bank_mask:0xf
	v_fmac_f32_dpp v9, v95, v96 row_newbcast:1 row_mask:0xf bank_mask:0xf
	v_mfma_f32_16x16x32_bf16 v[32:35], v[74:77], v[28:31], v[32:35]
	v_fmac_f32_dpp v10, v95, v96 row_newbcast:2 row_mask:0xf bank_mask:0xf
	v_fmac_f32_dpp v11, v95, v96 row_newbcast:3 row_mask:0xf bank_mask:0xf
	ds_read_b128 v[40:43], v104 offset:512
	v_fmac_f32_dpp v12, v95, v96 row_newbcast:4 row_mask:0xf bank_mask:0xf
	v_fmac_f32_dpp v13, v95, v96 row_newbcast:5 row_mask:0xf bank_mask:0xf
	ds_read_b128 v[44:47], v104 offset:528
	v_fmac_f32_dpp v14, v95, v96 row_newbcast:6 row_mask:0xf bank_mask:0xf
	v_fmac_f32_dpp v15, v95, v96 row_newbcast:7 row_mask:0xf bank_mask:0xf
	ds_read_b32 v65, v105 offset:16896
	v_fmac_f32_dpp v16, v95, v96 row_newbcast:8 row_mask:0xf bank_mask:0xf
	v_fmac_f32_dpp v17, v95, v96 row_newbcast:9 row_mask:0xf bank_mask:0xf
	ds_read_b32 v66, v107 offset:512
	v_fmac_f32_dpp v18, v95, v96 row_newbcast:10 row_mask:0xf bank_mask:0xf
	v_fmac_f32_dpp v19, v95, v96 row_newbcast:11 row_mask:0xf bank_mask:0xf
	ds_read_b32 v48, v105 offset:8704
	v_fmac_f32_dpp v20, v95, v96 row_newbcast:12 row_mask:0xf bank_mask:0xf
	v_fmac_f32_dpp v21, v95, v96 row_newbcast:13 row_mask:0xf bank_mask:0xf
	ds_read_b64 v[68:69], v108 offset:49168
	v_fmac_f32_dpp v22, v95, v96 row_newbcast:14 row_mask:0xf bank_mask:0xf
	v_fmac_f32_dpp v23, v95, v96 row_newbcast:15 row_mask:0xf bank_mask:0xf
	s_waitcnt lgkmcnt(8)
	s_waitcnt lgkmcnt(7)
; __device__ __forceinline__ void phase_rwkv_scan(const Params& p, int l, const int tidx) {
;     ...
;       for (int s = 0; s < RTC; s++) {
;         const bf16x8 A0 = nA0, A1 = nA1;
;         const float wA[8] = {nw0.x, nw0.y, nw0.z, nw0.w, nw1.x, nw1.y, nw1.z, nw1.w};
;         const float wB[8] = {nw2.x, nw2.y, nw2.z, nw2.w, nw3.x, nw3.y, nw3.z, nw3.w};
;         const float kaA[8] = {nka0.x, nka0.y, nka0.z, nka0.w, nka1.x, nka1.y, nka1.z, nka1.w};
;         const float kaB[8] = {nka2.x, nka2.y, nka2.z, nka2.w, nka3.x, nka3.y, nka3.z, nka3.w};
;         const float kdA[8] = {nkd0.x, nkd0.y, nkd0.z, nkd0.w, nkd1.x, nkd1.y, nkd1.z, nkd1.w};
;         const float kdB[8] = {nkd2.x, nkd2.y, nkd2.z, nkd2.w, nkd3.x, nkd3.y, nkd3.z, nkd3.w};
;         const float v = nv;
;         float c1 = nc.x, c2 = nc.y;
;         asm volatile("" : "+v"(c1), "+v"(c2));
;         if (s + 1 < RTC) RW_LD(s + 1);
;         u32x4 pa = {pack2(Sa[0], Sa[1]), pack2(Sa[2], Sa[3]), pack2(Sa[4], Sa[5]), pack2(Sa[6], Sa[7])};
;         u32x4 pb = {pack2(Sb[0], Sb[1]), pack2(Sb[2], Sb[3]), pack2(Sb[4], Sb[5]), pack2(Sb[6], Sb[7])};
;         f32x4 acc = {0.f, 0.f, 0.f, 0.f};
;         acc = __builtin_amdgcn_mfma_f32_16x16x32_bf16(A0, __builtin_bit_cast(bf16x8, pa), acc, 0, 0, 0);
;         acc = __builtin_amdgcn_mfma_f32_16x16x32_bf16(A1, __builtin_bit_cast(bf16x8, pb), acc, 0, 0, 0);
;         float tA[8], tB[8];
; #pragma unroll
;         for (int c = 0; c < 8; c++) { tA[c] = Sa[c] * wA[c] + v * kdA[c]; tB[c] = Sb[c] * wB[c] + v * kdB[c]; }
;         const float sa = -acc[0];
;         const float yq = acc[1];
; #pragma unroll
;         for (int c = 0; c < 8; c++) { Sa[c] = tA[c] + sa * kaA[c]; Sb[c] = tB[c] + sa * kaB[c]; }
;         const float y = yq + sa * c1 + v * c2;
;         if (quad == 0) by[s * 64 + row] = y;
;       }
	v_xor_b32_e32 v110, 0x80000000, v32
	v_fma_f32 v109, -v32, v98, v33
	v_fma_f32 v109, v96, v99, v109
	v_fmac_f32_dpp v8, v78, v110 row_newbcast:0 row_mask:0xf bank_mask:0xf
	v_fmac_f32_dpp v9, v78, v110 row_newbcast:1 row_mask:0xf bank_mask:0xf
	v_fmac_f32_dpp v10, v78, v110 row_newbcast:2 row_mask:0xf bank_mask:0xf
	v_fmac_f32_dpp v11, v78, v110 row_newbcast:3 row_mask:0xf bank_mask:0xf
	v_fmac_f32_dpp v12, v78, v110 row_newbcast:4 row_mask:0xf bank_mask:0xf
	v_fmac_f32_dpp v13, v78, v110 row_newbcast:5 row_mask:0xf bank_mask:0xf
	v_fmac_f32_dpp v14, v78, v110 row_newbcast:6 row_mask:0xf bank_mask:0xf
	v_fmac_f32_dpp v15, v78, v110 row_newbcast:7 row_mask:0xf bank_mask:0xf
	v_fmac_f32_dpp v16, v78, v110 row_newbcast:8 row_mask:0xf bank_mask:0xf
	v_fmac_f32_dpp v17, v78, v110 row_newbcast:9 row_mask:0xf bank_mask:0xf
	v_fmac_f32_dpp v18, v78, v110 row_newbcast:10 row_mask:0xf bank_mask:0xf
	v_fmac_f32_dpp v19, v78, v110 row_newbcast:11 row_mask:0xf bank_mask:0xf
	v_fmac_f32_dpp v20, v78, v110 row_newbcast:12 row_mask:0xf bank_mask:0xf
	v_fmac_f32_dpp v21, v78, v110 row_newbcast:13 row_mask:0xf bank_mask:0xf
	v_fmac_f32_dpp v22, v78, v110 row_newbcast:14 row_mask:0xf bank_mask:0xf
	v_fmac_f32_dpp v23, v78, v110 row_newbcast:15 row_mask:0xf bank_mask:0xf
	ds_write_b32 v107, v109 offset:8448
	v_cvt_pk_bf16_f32 v24, v8, v9
	v_cvt_pk_bf16_f32 v25, v10, v11
	v_cvt_pk_bf16_f32 v26, v12, v13
	v_cvt_pk_bf16_f32 v27, v14, v15
	v_cvt_pk_bf16_f32 v28, v16, v17
	v_cvt_pk_bf16_f32 v29, v18, v19
	s_waitcnt lgkmcnt(6)
	v_mfma_f32_16x16x32_bf16 v[32:35], v[40:43], v[24:27], 0
	v_cvt_pk_bf16_f32 v30, v20, v21
	v_cvt_pk_bf16_f32 v31, v22, v23
	s_waitcnt lgkmcnt(3)
	v_fmac_f32_dpp v8, v65, v66 row_newbcast:0 row_mask:0xf bank_mask:0xf
	v_fmac_f32_dpp v9, v65, v66 row_newbcast:1 row_mask:0xf bank_mask:0xf
	v_mfma_f32_16x16x32_bf16 v[32:35], v[44:47], v[28:31], v[32:35]
	v_fmac_f32_dpp v10, v65, v66 row_newbcast:2 row_mask:0xf bank_mask:0xf
	v_fmac_f32_dpp v11, v65, v66 row_newbcast:3 row_mask:0xf bank_mask:0xf
	ds_read_b128 v[70:73], v104 offset:768
	v_fmac_f32_dpp v12, v65, v66 row_newbcast:4 row_mask:0xf bank_mask:0xf
	v_fmac_f32_dpp v13, v65, v66 row_newbcast:5 row_mask:0xf bank_mask:0xf
	ds_read_b128 v[74:77], v104 offset:784
	v_fmac_f32_dpp v14, v65, v66 row_newbcast:6 row_mask:0xf bank_mask:0xf
	v_fmac_f32_dpp v15, v65, v66 row_newbcast:7 row_mask:0xf bank_mask:0xf
	ds_read_b32 v95, v105 offset:17152
	v_fmac_f32_dpp v16, v65, v66 row_newbcast:8 row_mask:0xf bank_mask:0xf
	v_fmac_f32_dpp v17, v65, v66 row_newbcast:9 row_mask:0xf bank_mask:0xf
	ds_read_b32 v96, v107 offset:768
	v_fmac_f32_dpp v18, v65, v66 row_newbcast:10 row_mask:0xf bank_mask:0xf
	v_fmac_f32_dpp v19, v65, v66 row_newbcast:11 row_mask:0xf bank_mask:0xf
	ds_read_b32 v78, v105 offset:8960
	v_fmac_f32_dpp v20, v65, v66 row_newbcast:12 row_mask:0xf bank_mask:0xf
	v_fmac_f32_dpp v21, v65, v66 row_newbcast:13 row_mask:0xf bank_mask:0xf
	ds_read_b64 v[98:99], v108 offset:49176
	v_fmac_f32_dpp v22, v65, v66 row_newbcast:14 row_mask:0xf bank_mask:0xf
	v_fmac_f32_dpp v23, v65, v66 row_newbcast:15 row_mask:0xf bank_mask:0xf
	s_waitcnt lgkmcnt(8)
	s_waitcnt lgkmcnt(7)
	v_xor_b32_e32 v110, 0x80000000, v32
	v_fma_f32 v109, -v32, v68, v33
	v_fma_f32 v109, v66, v69, v109
	v_fmac_f32_dpp v8, v48, v110 row_newbcast:0 row_mask:0xf bank_mask:0xf
	v_fmac_f32_dpp v9, v48, v110 row_newbcast:1 row_mask:0xf bank_mask:0xf
	v_fmac_f32_dpp v10, v48, v110 row_newbcast:2 row_mask:0xf bank_mask:0xf
	v_fmac_f32_dpp v11, v48, v110 row_newbcast:3 row_mask:0xf bank_mask:0xf
	v_fmac_f32_dpp v12, v48, v110 row_newbcast:4 row_mask:0xf bank_mask:0xf
	v_fmac_f32_dpp v13, v48, v110 row_newbcast:5 row_mask:0xf bank_mask:0xf
	v_fmac_f32_dpp v14, v48, v110 row_newbcast:6 row_mask:0xf bank_mask:0xf
	v_fmac_f32_dpp v15, v48, v110 row_newbcast:7 row_mask:0xf bank_mask:0xf
	v_fmac_f32_dpp v16, v48, v110 row_newbcast:8 row_mask:0xf bank_mask:0xf
	v_fmac_f32_dpp v17, v48, v110 row_newbcast:9 row_mask:0xf bank_mask:0xf
	v_fmac_f32_dpp v18, v48, v110 row_newbcast:10 row_mask:0xf bank_mask:0xf
	v_fmac_f32_dpp v19, v48, v110 row_newbcast:11 row_mask:0xf bank_mask:0xf
	v_fmac_f32_dpp v20, v48, v110 row_newbcast:12 row_mask:0xf bank_mask:0xf
	v_fmac_f32_dpp v21, v48, v110 row_newbcast:13 row_mask:0xf bank_mask:0xf
	v_fmac_f32_dpp v22, v48, v110 row_newbcast:14 row_mask:0xf bank_mask:0xf
	v_fmac_f32_dpp v23, v48, v110 row_newbcast:15 row_mask:0xf bank_mask:0xf
	ds_write_b32 v107, v109 offset:8704
	v_cvt_pk_bf16_f32 v24, v8, v9
	v_cvt_pk_bf16_f32 v25, v10, v11
	v_cvt_pk_bf16_f32 v26, v12, v13
	v_cvt_pk_bf16_f32 v27, v14, v15
	v_cvt_pk_bf16_f32 v28, v16, v17
	v_cvt_pk_bf16_f32 v29, v18, v19
	s_waitcnt lgkmcnt(6)
	v_mfma_f32_16x16x32_bf16 v[32:35], v[70:73], v[24:27], 0
	v_cvt_pk_bf16_f32 v30, v20, v21
	v_cvt_pk_bf16_f32 v31, v22, v23
	s_waitcnt lgkmcnt(3)
	v_fmac_f32_dpp v8, v95, v96 row_newbcast:0 row_mask:0xf bank_mask:0xf
	v_fmac_f32_dpp v9, v95, v96 row_newbcast:1 row_mask:0xf bank_mask:0xf
	v_mfma_f32_16x16x32_bf16 v[32:35], v[74:77], v[28:31], v[32:35]
	v_fmac_f32_dpp v10, v95, v96 row_newbcast:2 row_mask:0xf bank_mask:0xf
	v_fmac_f32_dpp v11, v95, v96 row_newbcast:3 row_mask:0xf bank_mask:0xf
	ds_read_b128 v[40:43], v104 offset:1024
	v_fmac_f32_dpp v12, v95, v96 row_newbcast:4 row_mask:0xf bank_mask:0xf
	v_fmac_f32_dpp v13, v95, v96 row_newbcast:5 row_mask:0xf bank_mask:0xf
	ds_read_b128 v[44:47], v104 offset:1040
	v_fmac_f32_dpp v14, v95, v96 row_newbcast:6 row_mask:0xf bank_mask:0xf
	v_fmac_f32_dpp v15, v95, v96 row_newbcast:7 row_mask:0xf bank_mask:0xf
	ds_read_b32 v65, v105 offset:17408
	v_fmac_f32_dpp v16, v95, v96 row_newbcast:8 row_mask:0xf bank_mask:0xf
	v_fmac_f32_dpp v17, v95, v96 row_newbcast:9 row_mask:0xf bank_mask:0xf
	ds_read_b32 v66, v107 offset:1024
	v_fmac_f32_dpp v18, v95, v96 row_newbcast:10 row_mask:0xf bank_mask:0xf
	v_fmac_f32_dpp v19, v95, v96 row_newbcast:11 row_mask:0xf bank_mask:0xf
	ds_read_b32 v48, v105 offset:9216
	v_fmac_f32_dpp v20, v95, v96 row_newbcast:12 row_mask:0xf bank_mask:0xf
	v_fmac_f32_dpp v21, v95, v96 row_newbcast:13 row_mask:0xf bank_mask:0xf
	ds_read_b64 v[68:69], v108 offset:49184
	v_fmac_f32_dpp v22, v95, v96 row_newbcast:14 row_mask:0xf bank_mask:0xf
	v_fmac_f32_dpp v23, v95, v96 row_newbcast:15 row_mask:0xf bank_mask:0xf
	s_waitcnt lgkmcnt(8)
; __device__ __forceinline__ void phase_rwkv_scan(const Params& p, int l, const int tidx) {
;     ...
;       for (int s = 0; s < RTC; s++) {
;         const bf16x8 A0 = nA0, A1 = nA1;
;         const float wA[8] = {nw0.x, nw0.y, nw0.z, nw0.w, nw1.x, nw1.y, nw1.z, nw1.w};
;         const float wB[8] = {nw2.x, nw2.y, nw2.z, nw2.w, nw3.x, nw3.y, nw3.z, nw3.w};
;         const float kaA[8] = {nka0.x, nka0.y, nka0.z, nka0.w, nka1.x, nka1.y, nka1.z, nka1.w};
;         const float kaB[8] = {nka2.x, nka2.y, nka2.z, nka2.w, nka3.x, nka3.y, nka3.z, nka3.w};
;         const float kdA[8] = {nkd0.x, nkd0.y, nkd0.z, nkd0.w, nkd1.x, nkd1.y, nkd1.z, nkd1.w};
;         const float kdB[8] = {nkd2.x, nkd2.y, nkd2.z, nkd2.w, nkd3.x, nkd3.y, nkd3.z, nkd3.w};
;         const float v = nv;
;         float c1 = nc.x, c2 = nc.y;
;         asm volatile("" : "+v"(c1), "+v"(c2));
;         if (s + 1 < RTC) RW_LD(s + 1);
;         u32x4 pa = {pack2(Sa[0], Sa[1]), pack2(Sa[2], Sa[3]), pack2(Sa[4], Sa[5]), pack2(Sa[6], Sa[7])};
;         u32x4 pb = {pack2(Sb[0], Sb[1]), pack2(Sb[2], Sb[3]), pack2(Sb[4], Sb[5]), pack2(Sb[6], Sb[7])};
;         f32x4 acc = {0.f, 0.f, 0.f, 0.f};
;         acc = __builtin_amdgcn_mfma_f32_16x16x32_bf16(A0, __builtin_bit_cast(bf16x8, pa), acc, 0, 0, 0);
;         acc = __builtin_amdgcn_mfma_f32_16x16x32_bf16(A1, __builtin_bit_cast(bf16x8, pb), acc, 0, 0, 0);
;         float tA[8], tB[8];
; #pragma unroll
;         for (int c = 0; c < 8; c++) { tA[c] = Sa[c] * wA[c] + v * kdA[c]; tB[c] = Sb[c] * wB[c] + v * kdB[c]; }
;         const float sa = -acc[0];
;         const float yq = acc[1];
; #pragma unroll
;         for (int c = 0; c < 8; c++) { Sa[c] = tA[c] + sa * kaA[c]; Sb[c] = tB[c] + sa * kaB[c]; }
;         const float y = yq + sa * c1 + v * c2;
;         if (quad == 0) by[s * 64 + row] = y;
;       }
	s_waitcnt lgkmcnt(7)
	v_xor_b32_e32 v110, 0x80000000, v32
	v_fma_f32 v109, -v32, v98, v33
	v_fma_f32 v109, v96, v99, v109
	v_fmac_f32_dpp v8, v78, v110 row_newbcast:0 row_mask:0xf bank_mask:0xf
	v_fmac_f32_dpp v9, v78, v110 row_newbcast:1 row_mask:0xf bank_mask:0xf
	v_fmac_f32_dpp v10, v78, v110 row_newbcast:2 row_mask:0xf bank_mask:0xf
	v_fmac_f32_dpp v11, v78, v110 row_newbcast:3 row_mask:0xf bank_mask:0xf
	v_fmac_f32_dpp v12, v78, v110 row_newbcast:4 row_mask:0xf bank_mask:0xf
	v_fmac_f32_dpp v13, v78, v110 row_newbcast:5 row_mask:0xf bank_mask:0xf
	v_fmac_f32_dpp v14, v78, v110 row_newbcast:6 row_mask:0xf bank_mask:0xf
	v_fmac_f32_dpp v15, v78, v110 row_newbcast:7 row_mask:0xf bank_mask:0xf
	v_fmac_f32_dpp v16, v78, v110 row_newbcast:8 row_mask:0xf bank_mask:0xf
	v_fmac_f32_dpp v17, v78, v110 row_newbcast:9 row_mask:0xf bank_mask:0xf
	v_fmac_f32_dpp v18, v78, v110 row_newbcast:10 row_mask:0xf bank_mask:0xf
	v_fmac_f32_dpp v19, v78, v110 row_newbcast:11 row_mask:0xf bank_mask:0xf
	v_fmac_f32_dpp v20, v78, v110 row_newbcast:12 row_mask:0xf bank_mask:0xf
	v_fmac_f32_dpp v21, v78, v110 row_newbcast:13 row_mask:0xf bank_mask:0xf
	v_fmac_f32_dpp v22, v78, v110 row_newbcast:14 row_mask:0xf bank_mask:0xf
	v_fmac_f32_dpp v23, v78, v110 row_newbcast:15 row_mask:0xf bank_mask:0xf
	ds_write_b32 v107, v109 offset:8960
	v_cvt_pk_bf16_f32 v24, v8, v9
	v_cvt_pk_bf16_f32 v25, v10, v11
	v_cvt_pk_bf16_f32 v26, v12, v13
	v_cvt_pk_bf16_f32 v27, v14, v15
	v_cvt_pk_bf16_f32 v28, v16, v17
	v_cvt_pk_bf16_f32 v29, v18, v19
	s_waitcnt lgkmcnt(6)
	v_mfma_f32_16x16x32_bf16 v[32:35], v[40:43], v[24:27], 0
	v_cvt_pk_bf16_f32 v30, v20, v21
	v_cvt_pk_bf16_f32 v31, v22, v23
	s_waitcnt lgkmcnt(3)
	v_fmac_f32_dpp v8, v65, v66 row_newbcast:0 row_mask:0xf bank_mask:0xf
	v_fmac_f32_dpp v9, v65, v66 row_newbcast:1 row_mask:0xf bank_mask:0xf
	v_mfma_f32_16x16x32_bf16 v[32:35], v[44:47], v[28:31], v[32:35]
	v_fmac_f32_dpp v10, v65, v66 row_newbcast:2 row_mask:0xf bank_mask:0xf
	v_fmac_f32_dpp v11, v65, v66 row_newbcast:3 row_mask:0xf bank_mask:0xf
	ds_read_b128 v[70:73], v104 offset:1280
	v_fmac_f32_dpp v12, v65, v66 row_newbcast:4 row_mask:0xf bank_mask:0xf
	v_fmac_f32_dpp v13, v65, v66 row_newbcast:5 row_mask:0xf bank_mask:0xf
	ds_read_b128 v[74:77], v104 offset:1296
	v_fmac_f32_dpp v14, v65, v66 row_newbcast:6 row_mask:0xf bank_mask:0xf
	v_fmac_f32_dpp v15, v65, v66 row_newbcast:7 row_mask:0xf bank_mask:0xf
	ds_read_b32 v95, v105 offset:17664
	v_fmac_f32_dpp v16, v65, v66 row_newbcast:8 row_mask:0xf bank_mask:0xf
	v_fmac_f32_dpp v17, v65, v66 row_newbcast:9 row_mask:0xf bank_mask:0xf
	ds_read_b32 v96, v107 offset:1280
	v_fmac_f32_dpp v18, v65, v66 row_newbcast:10 row_mask:0xf bank_mask:0xf
	v_fmac_f32_dpp v19, v65, v66 row_newbcast:11 row_mask:0xf bank_mask:0xf
	ds_read_b32 v78, v105 offset:9472
	v_fmac_f32_dpp v20, v65, v66 row_newbcast:12 row_mask:0xf bank_mask:0xf
	v_fmac_f32_dpp v21, v65, v66 row_newbcast:13 row_mask:0xf bank_mask:0xf
	ds_read_b64 v[98:99], v108 offset:49192
	v_fmac_f32_dpp v22, v65, v66 row_newbcast:14 row_mask:0xf bank_mask:0xf
	v_fmac_f32_dpp v23, v65, v66 row_newbcast:15 row_mask:0xf bank_mask:0xf
	s_waitcnt lgkmcnt(8)
	s_waitcnt lgkmcnt(7)
	v_xor_b32_e32 v110, 0x80000000, v32
	v_fma_f32 v109, -v32, v68, v33
	v_fma_f32 v109, v66, v69, v109
	v_fmac_f32_dpp v8, v48, v110 row_newbcast:0 row_mask:0xf bank_mask:0xf
	v_fmac_f32_dpp v9, v48, v110 row_newbcast:1 row_mask:0xf bank_mask:0xf
	v_fmac_f32_dpp v10, v48, v110 row_newbcast:2 row_mask:0xf bank_mask:0xf
	v_fmac_f32_dpp v11, v48, v110 row_newbcast:3 row_mask:0xf bank_mask:0xf
	v_fmac_f32_dpp v12, v48, v110 row_newbcast:4 row_mask:0xf bank_mask:0xf
	v_fmac_f32_dpp v13, v48, v110 row_newbcast:5 row_mask:0xf bank_mask:0xf
	v_fmac_f32_dpp v14, v48, v110 row_newbcast:6 row_mask:0xf bank_mask:0xf
	v_fmac_f32_dpp v15, v48, v110 row_newbcast:7 row_mask:0xf bank_mask:0xf
	v_fmac_f32_dpp v16, v48, v110 row_newbcast:8 row_mask:0xf bank_mask:0xf
	v_fmac_f32_dpp v17, v48, v110 row_newbcast:9 row_mask:0xf bank_mask:0xf
	v_fmac_f32_dpp v18, v48, v110 row_newbcast:10 row_mask:0xf bank_mask:0xf
	v_fmac_f32_dpp v19, v48, v110 row_newbcast:11 row_mask:0xf bank_mask:0xf
	v_fmac_f32_dpp v20, v48, v110 row_newbcast:12 row_mask:0xf bank_mask:0xf
	v_fmac_f32_dpp v21, v48, v110 row_newbcast:13 row_mask:0xf bank_mask:0xf
	v_fmac_f32_dpp v22, v48, v110 row_newbcast:14 row_mask:0xf bank_mask:0xf
	v_fmac_f32_dpp v23, v48, v110 row_newbcast:15 row_mask:0xf bank_mask:0xf
	ds_write_b32 v107, v109 offset:9216
	v_cvt_pk_bf16_f32 v24, v8, v9
	v_cvt_pk_bf16_f32 v25, v10, v11
	v_cvt_pk_bf16_f32 v26, v12, v13
	v_cvt_pk_bf16_f32 v27, v14, v15
	v_cvt_pk_bf16_f32 v28, v16, v17
	v_cvt_pk_bf16_f32 v29, v18, v19
	s_waitcnt lgkmcnt(6)
	v_mfma_f32_16x16x32_bf16 v[32:35], v[70:73], v[24:27], 0
	v_cvt_pk_bf16_f32 v30, v20, v21
	v_cvt_pk_bf16_f32 v31, v22, v23
	s_waitcnt lgkmcnt(3)
	v_fmac_f32_dpp v8, v95, v96 row_newbcast:0 row_mask:0xf bank_mask:0xf
	v_fmac_f32_dpp v9, v95, v96 row_newbcast:1 row_mask:0xf bank_mask:0xf
	v_mfma_f32_16x16x32_bf16 v[32:35], v[74:77], v[28:31], v[32:35]
	v_fmac_f32_dpp v10, v95, v96 row_newbcast:2 row_mask:0xf bank_mask:0xf
	v_fmac_f32_dpp v11, v95, v96 row_newbcast:3 row_mask:0xf bank_mask:0xf
	ds_read_b128 v[40:43], v104 offset:1536
	v_fmac_f32_dpp v12, v95, v96 row_newbcast:4 row_mask:0xf bank_mask:0xf
	v_fmac_f32_dpp v13, v95, v96 row_newbcast:5 row_mask:0xf bank_mask:0xf
	ds_read_b128 v[44:47], v104 offset:1552
	v_fmac_f32_dpp v14, v95, v96 row_newbcast:6 row_mask:0xf bank_mask:0xf
	v_fmac_f32_dpp v15, v95, v96 row_newbcast:7 row_mask:0xf bank_mask:0xf
	ds_read_b32 v65, v105 offset:17920
	v_fmac_f32_dpp v16, v95, v96 row_newbcast:8 row_mask:0xf bank_mask:0xf
	v_fmac_f32_dpp v17, v95, v96 row_newbcast:9 row_mask:0xf bank_mask:0xf
	ds_read_b32 v66, v107 offset:1536
	v_fmac_f32_dpp v18, v95, v96 row_newbcast:10 row_mask:0xf bank_mask:0xf
	v_fmac_f32_dpp v19, v95, v96 row_newbcast:11 row_mask:0xf bank_mask:0xf
	ds_read_b32 v48, v105 offset:9728
	v_fmac_f32_dpp v20, v95, v96 row_newbcast:12 row_mask:0xf bank_mask:0xf
	v_fmac_f32_dpp v21, v95, v96 row_newbcast:13 row_mask:0xf bank_mask:0xf
	ds_read_b64 v[68:69], v108 offset:49200
	v_fmac_f32_dpp v22, v95, v96 row_newbcast:14 row_mask:0xf bank_mask:0xf
	v_fmac_f32_dpp v23, v95, v96 row_newbcast:15 row_mask:0xf bank_mask:0xf
	s_waitcnt lgkmcnt(8)
; __device__ __forceinline__ void phase_rwkv_scan(const Params& p, int l, const int tidx) {
;     ...
;       for (int s = 0; s < RTC; s++) {
;         const bf16x8 A0 = nA0, A1 = nA1;
;         const float wA[8] = {nw0.x, nw0.y, nw0.z, nw0.w, nw1.x, nw1.y, nw1.z, nw1.w};
;         const float wB[8] = {nw2.x, nw2.y, nw2.z, nw2.w, nw3.x, nw3.y, nw3.z, nw3.w};
;         const float kaA[8] = {nka0.x, nka0.y, nka0.z, nka0.w, nka1.x, nka1.y, nka1.z, nka1.w};
;         const float kaB[8] = {nka2.x, nka2.y, nka2.z, nka2.w, nka3.x, nka3.y, nka3.z, nka3.w};
;         const float kdA[8] = {nkd0.x, nkd0.y, nkd0.z, nkd0.w, nkd1.x, nkd1.y, nkd1.z, nkd1.w};
;         const float kdB[8] = {nkd2.x, nkd2.y, nkd2.z, nkd2.w, nkd3.x, nkd3.y, nkd3.z, nkd3.w};
;         const float v = nv;
;         float c1 = nc.x, c2 = nc.y;
;         asm volatile("" : "+v"(c1), "+v"(c2));
;         if (s + 1 < RTC) RW_LD(s + 1);
;         u32x4 pa = {pack2(Sa[0], Sa[1]), pack2(Sa[2], Sa[3]), pack2(Sa[4], Sa[5]), pack2(Sa[6], Sa[7])};
;         u32x4 pb = {pack2(Sb[0], Sb[1]), pack2(Sb[2], Sb[3]), pack2(Sb[4], Sb[5]), pack2(Sb[6], Sb[7])};
;         f32x4 acc = {0.f, 0.f, 0.f, 0.f};
;         acc = __builtin_amdgcn_mfma_f32_16x16x32_bf16(A0, __builtin_bit_cast(bf16x8, pa), acc, 0, 0, 0);
;         acc = __builtin_amdgcn_mfma_f32_16x16x32_bf16(A1, __builtin_bit_cast(bf16x8, pb), acc, 0, 0, 0);
;         float tA[8], tB[8];
; #pragma unroll
;         for (int c = 0; c < 8; c++) { tA[c] = Sa[c] * wA[c] + v * kdA[c]; tB[c] = Sb[c] * wB[c] + v * kdB[c]; }
;         const float sa = -acc[0];
;         const float yq = acc[1];
; #pragma unroll
;         for (int c = 0; c < 8; c++) { Sa[c] = tA[c] + sa * kaA[c]; Sb[c] = tB[c] + sa * kaB[c]; }
;         const float y = yq + sa * c1 + v * c2;
;         if (quad == 0) by[s * 64 + row] = y;
;       }
	s_waitcnt lgkmcnt(7)
	v_xor_b32_e32 v110, 0x80000000, v32
	v_fma_f32 v109, -v32, v98, v33
	v_fma_f32 v109, v96, v99, v109
	v_fmac_f32_dpp v8, v78, v110 row_newbcast:0 row_mask:0xf bank_mask:0xf
	v_fmac_f32_dpp v9, v78, v110 row_newbcast:1 row_mask:0xf bank_mask:0xf
	v_fmac_f32_dpp v10, v78, v110 row_newbcast:2 row_mask:0xf bank_mask:0xf
	v_fmac_f32_dpp v11, v78, v110 row_newbcast:3 row_mask:0xf bank_mask:0xf
	v_fmac_f32_dpp v12, v78, v110 row_newbcast:4 row_mask:0xf bank_mask:0xf
	v_fmac_f32_dpp v13, v78, v110 row_newbcast:5 row_mask:0xf bank_mask:0xf
	v_fmac_f32_dpp v14, v78, v110 row_newbcast:6 row_mask:0xf bank_mask:0xf
	v_fmac_f32_dpp v15, v78, v110 row_newbcast:7 row_mask:0xf bank_mask:0xf
	v_fmac_f32_dpp v16, v78, v110 row_newbcast:8 row_mask:0xf bank_mask:0xf
	v_fmac_f32_dpp v17, v78, v110 row_newbcast:9 row_mask:0xf bank_mask:0xf
	v_fmac_f32_dpp v18, v78, v110 row_newbcast:10 row_mask:0xf bank_mask:0xf
	v_fmac_f32_dpp v19, v78, v110 row_newbcast:11 row_mask:0xf bank_mask:0xf
	v_fmac_f32_dpp v20, v78, v110 row_newbcast:12 row_mask:0xf bank_mask:0xf
	v_fmac_f32_dpp v21, v78, v110 row_newbcast:13 row_mask:0xf bank_mask:0xf
	v_fmac_f32_dpp v22, v78, v110 row_newbcast:14 row_mask:0xf bank_mask:0xf
	v_fmac_f32_dpp v23, v78, v110 row_newbcast:15 row_mask:0xf bank_mask:0xf
	ds_write_b32 v107, v109 offset:9472
	v_cvt_pk_bf16_f32 v24, v8, v9
	v_cvt_pk_bf16_f32 v25, v10, v11
	v_cvt_pk_bf16_f32 v26, v12, v13
	v_cvt_pk_bf16_f32 v27, v14, v15
	v_cvt_pk_bf16_f32 v28, v16, v17
	v_cvt_pk_bf16_f32 v29, v18, v19
	s_waitcnt lgkmcnt(6)
	v_mfma_f32_16x16x32_bf16 v[32:35], v[40:43], v[24:27], 0
	v_cvt_pk_bf16_f32 v30, v20, v21
	v_cvt_pk_bf16_f32 v31, v22, v23
	s_waitcnt lgkmcnt(3)
	v_fmac_f32_dpp v8, v65, v66 row_newbcast:0 row_mask:0xf bank_mask:0xf
	v_fmac_f32_dpp v9, v65, v66 row_newbcast:1 row_mask:0xf bank_mask:0xf
	v_mfma_f32_16x16x32_bf16 v[32:35], v[44:47], v[28:31], v[32:35]
	v_fmac_f32_dpp v10, v65, v66 row_newbcast:2 row_mask:0xf bank_mask:0xf
	v_fmac_f32_dpp v11, v65, v66 row_newbcast:3 row_mask:0xf bank_mask:0xf
	ds_read_b128 v[70:73], v104 offset:1792
	v_fmac_f32_dpp v12, v65, v66 row_newbcast:4 row_mask:0xf bank_mask:0xf
	v_fmac_f32_dpp v13, v65, v66 row_newbcast:5 row_mask:0xf bank_mask:0xf
	ds_read_b128 v[74:77], v104 offset:1808
	v_fmac_f32_dpp v14, v65, v66 row_newbcast:6 row_mask:0xf bank_mask:0xf
	v_fmac_f32_dpp v15, v65, v66 row_newbcast:7 row_mask:0xf bank_mask:0xf
	ds_read_b32 v94, v105 offset:1792
	v_fmac_f32_dpp v16, v65, v66 row_newbcast:8 row_mask:0xf bank_mask:0xf
	v_fmac_f32_dpp v17, v65, v66 row_newbcast:9 row_mask:0xf bank_mask:0xf
	ds_read_b32 v95, v105 offset:18176
	v_fmac_f32_dpp v18, v65, v66 row_newbcast:10 row_mask:0xf bank_mask:0xf
	v_fmac_f32_dpp v19, v65, v66 row_newbcast:11 row_mask:0xf bank_mask:0xf
	ds_read_b32 v96, v107 offset:1792
	v_fmac_f32_dpp v20, v65, v66 row_newbcast:12 row_mask:0xf bank_mask:0xf
	v_fmac_f32_dpp v21, v65, v66 row_newbcast:13 row_mask:0xf bank_mask:0xf
	ds_read_b32 v78, v105 offset:9984
	v_fmac_f32_dpp v22, v65, v66 row_newbcast:14 row_mask:0xf bank_mask:0xf
	v_fmac_f32_dpp v23, v65, v66 row_newbcast:15 row_mask:0xf bank_mask:0xf
	ds_read_b64 v[98:99], v108 offset:49208
	s_waitcnt lgkmcnt(9)
	s_waitcnt lgkmcnt(8)
	v_xor_b32_e32 v110, 0x80000000, v32
	v_fma_f32 v109, -v32, v68, v33
	v_fma_f32 v109, v66, v69, v109
	v_fmac_f32_dpp v8, v48, v110 row_newbcast:0 row_mask:0xf bank_mask:0xf
	v_fmac_f32_dpp v9, v48, v110 row_newbcast:1 row_mask:0xf bank_mask:0xf
	v_fmac_f32_dpp v10, v48, v110 row_newbcast:2 row_mask:0xf bank_mask:0xf
	v_fmac_f32_dpp v11, v48, v110 row_newbcast:3 row_mask:0xf bank_mask:0xf
	v_fmac_f32_dpp v12, v48, v110 row_newbcast:4 row_mask:0xf bank_mask:0xf
	v_fmac_f32_dpp v13, v48, v110 row_newbcast:5 row_mask:0xf bank_mask:0xf
	v_fmac_f32_dpp v14, v48, v110 row_newbcast:6 row_mask:0xf bank_mask:0xf
	v_fmac_f32_dpp v15, v48, v110 row_newbcast:7 row_mask:0xf bank_mask:0xf
	v_fmac_f32_dpp v16, v48, v110 row_newbcast:8 row_mask:0xf bank_mask:0xf
	v_fmac_f32_dpp v17, v48, v110 row_newbcast:9 row_mask:0xf bank_mask:0xf
	v_fmac_f32_dpp v18, v48, v110 row_newbcast:10 row_mask:0xf bank_mask:0xf
	v_fmac_f32_dpp v19, v48, v110 row_newbcast:11 row_mask:0xf bank_mask:0xf
	v_fmac_f32_dpp v20, v48, v110 row_newbcast:12 row_mask:0xf bank_mask:0xf
	v_fmac_f32_dpp v21, v48, v110 row_newbcast:13 row_mask:0xf bank_mask:0xf
	v_fmac_f32_dpp v22, v48, v110 row_newbcast:14 row_mask:0xf bank_mask:0xf
	v_fmac_f32_dpp v23, v48, v110 row_newbcast:15 row_mask:0xf bank_mask:0xf
	ds_write_b32 v107, v109 offset:9728
	v_cvt_pk_bf16_f32 v24, v8, v9
	v_cvt_pk_bf16_f32 v25, v10, v11
	v_cvt_pk_bf16_f32 v26, v12, v13
	v_cvt_pk_bf16_f32 v27, v14, v15
	v_cvt_pk_bf16_f32 v28, v16, v17
	v_cvt_pk_bf16_f32 v29, v18, v19
	s_waitcnt lgkmcnt(7)
	v_mfma_f32_16x16x32_bf16 v[32:35], v[70:73], v[24:27], 0
	v_cvt_pk_bf16_f32 v30, v20, v21
	v_cvt_pk_bf16_f32 v31, v22, v23
	s_waitcnt lgkmcnt(3)
	v_fmac_f32_dpp v8, v95, v96 row_newbcast:0 row_mask:0xf bank_mask:0xf
	v_fmac_f32_dpp v9, v95, v96 row_newbcast:1 row_mask:0xf bank_mask:0xf
	v_mfma_f32_16x16x32_bf16 v[32:35], v[74:77], v[28:31], v[32:35]
	v_fmac_f32_dpp v10, v95, v96 row_newbcast:2 row_mask:0xf bank_mask:0xf
	v_fmac_f32_dpp v11, v95, v96 row_newbcast:3 row_mask:0xf bank_mask:0xf
	ds_read_b128 v[40:43], v104 offset:2048
	v_fmac_f32_dpp v12, v95, v96 row_newbcast:4 row_mask:0xf bank_mask:0xf
	v_fmac_f32_dpp v13, v95, v96 row_newbcast:5 row_mask:0xf bank_mask:0xf
	ds_read_b128 v[44:47], v104 offset:2064
	v_fmac_f32_dpp v14, v95, v96 row_newbcast:6 row_mask:0xf bank_mask:0xf
	v_fmac_f32_dpp v15, v95, v96 row_newbcast:7 row_mask:0xf bank_mask:0xf
	ds_read_b32 v65, v105 offset:18432
	v_fmac_f32_dpp v16, v95, v96 row_newbcast:8 row_mask:0xf bank_mask:0xf
	v_fmac_f32_dpp v17, v95, v96 row_newbcast:9 row_mask:0xf bank_mask:0xf
	ds_read_b32 v66, v107 offset:2048
	v_fmac_f32_dpp v18, v95, v96 row_newbcast:10 row_mask:0xf bank_mask:0xf
	v_fmac_f32_dpp v19, v95, v96 row_newbcast:11 row_mask:0xf bank_mask:0xf
	ds_read_b32 v48, v105 offset:10240
	v_fmac_f32_dpp v20, v95, v96 row_newbcast:12 row_mask:0xf bank_mask:0xf
	v_fmac_f32_dpp v21, v95, v96 row_newbcast:13 row_mask:0xf bank_mask:0xf
	ds_read_b64 v[68:69], v108 offset:49216
	v_fmac_f32_dpp v22, v95, v96 row_newbcast:14 row_mask:0xf bank_mask:0xf
	v_fmac_f32_dpp v23, v95, v96 row_newbcast:15 row_mask:0xf bank_mask:0xf
	s_waitcnt lgkmcnt(8)
; __device__ __forceinline__ void phase_rwkv_scan(const Params& p, int l, const int tidx) {
;     ...
;       for (int s = 0; s < RTC; s++) {
;         const bf16x8 A0 = nA0, A1 = nA1;
;         const float wA[8] = {nw0.x, nw0.y, nw0.z, nw0.w, nw1.x, nw1.y, nw1.z, nw1.w};
;         const float wB[8] = {nw2.x, nw2.y, nw2.z, nw2.w, nw3.x, nw3.y, nw3.z, nw3.w};
;         const float kaA[8] = {nka0.x, nka0.y, nka0.z, nka0.w, nka1.x, nka1.y, nka1.z, nka1.w};
;         const float kaB[8] = {nka2.x, nka2.y, nka2.z, nka2.w, nka3.x, nka3.y, nka3.z, nka3.w};
;         const float kdA[8] = {nkd0.x, nkd0.y, nkd0.z, nkd0.w, nkd1.x, nkd1.y, nkd1.z, nkd1.w};
;         const float kdB[8] = {nkd2.x, nkd2.y, nkd2.z, nkd2.w, nkd3.x, nkd3.y, nkd3.z, nkd3.w};
;         const float v = nv;
;         float c1 = nc.x, c2 = nc.y;
;         asm volatile("" : "+v"(c1), "+v"(c2));
;         if (s + 1 < RTC) RW_LD(s + 1);
;         u32x4 pa = {pack2(Sa[0], Sa[1]), pack2(Sa[2], Sa[3]), pack2(Sa[4], Sa[5]), pack2(Sa[6], Sa[7])};
;         u32x4 pb = {pack2(Sb[0], Sb[1]), pack2(Sb[2], Sb[3]), pack2(Sb[4], Sb[5]), pack2(Sb[6], Sb[7])};
;         f32x4 acc = {0.f, 0.f, 0.f, 0.f};
;         acc = __builtin_amdgcn_mfma_f32_16x16x32_bf16(A0, __builtin_bit_cast(bf16x8, pa), acc, 0, 0, 0);
;         acc = __builtin_amdgcn_mfma_f32_16x16x32_bf16(A1, __builtin_bit_cast(bf16x8, pb), acc, 0, 0, 0);
;         float tA[8], tB[8];
; #pragma unroll
;         for (int c = 0; c < 8; c++) { tA[c] = Sa[c] * wA[c] + v * kdA[c]; tB[c] = Sb[c] * wB[c] + v * kdB[c]; }
;         const float sa = -acc[0];
;         const float yq = acc[1];
; #pragma unroll
;         for (int c = 0; c < 8; c++) { Sa[c] = tA[c] + sa * kaA[c]; Sb[c] = tB[c] + sa * kaB[c]; }
;         const float y = yq + sa * c1 + v * c2;
;         if (quad == 0) by[s * 64 + row] = y;
;       }
	s_waitcnt lgkmcnt(7)
	v_xor_b32_e32 v110, 0x80000000, v32
	v_fma_f32 v109, -v32, v98, v33
	v_fma_f32 v109, v96, v99, v109
	v_fmac_f32_dpp v8, v78, v110 row_newbcast:0 row_mask:0xf bank_mask:0xf
	v_fmac_f32_dpp v9, v78, v110 row_newbcast:1 row_mask:0xf bank_mask:0xf
	v_fmac_f32_dpp v10, v78, v110 row_newbcast:2 row_mask:0xf bank_mask:0xf
	v_fmac_f32_dpp v11, v78, v110 row_newbcast:3 row_mask:0xf bank_mask:0xf
	v_fmac_f32_dpp v12, v78, v110 row_newbcast:4 row_mask:0xf bank_mask:0xf
	v_fmac_f32_dpp v13, v78, v110 row_newbcast:5 row_mask:0xf bank_mask:0xf
	v_fmac_f32_dpp v14, v78, v110 row_newbcast:6 row_mask:0xf bank_mask:0xf
	v_fmac_f32_dpp v15, v78, v110 row_newbcast:7 row_mask:0xf bank_mask:0xf
	v_fmac_f32_dpp v16, v78, v110 row_newbcast:8 row_mask:0xf bank_mask:0xf
	v_fmac_f32_dpp v17, v78, v110 row_newbcast:9 row_mask:0xf bank_mask:0xf
	v_fmac_f32_dpp v18, v78, v110 row_newbcast:10 row_mask:0xf bank_mask:0xf
	v_fmac_f32_dpp v19, v78, v110 row_newbcast:11 row_mask:0xf bank_mask:0xf
	v_fmac_f32_dpp v20, v78, v110 row_newbcast:12 row_mask:0xf bank_mask:0xf
	v_fmac_f32_dpp v21, v78, v110 row_newbcast:13 row_mask:0xf bank_mask:0xf
	v_fmac_f32_dpp v22, v78, v110 row_newbcast:14 row_mask:0xf bank_mask:0xf
	v_fmac_f32_dpp v23, v78, v110 row_newbcast:15 row_mask:0xf bank_mask:0xf
	v_mul_f32_dpp v8, v94, v8 row_newbcast:0 row_mask:0xf bank_mask:0xf
	v_mul_f32_dpp v9, v94, v9 row_newbcast:1 row_mask:0xf bank_mask:0xf
	v_mul_f32_dpp v10, v94, v10 row_newbcast:2 row_mask:0xf bank_mask:0xf
	v_mul_f32_dpp v11, v94, v11 row_newbcast:3 row_mask:0xf bank_mask:0xf
	v_mul_f32_dpp v12, v94, v12 row_newbcast:4 row_mask:0xf bank_mask:0xf
	v_mul_f32_dpp v13, v94, v13 row_newbcast:5 row_mask:0xf bank_mask:0xf
	v_mul_f32_dpp v14, v94, v14 row_newbcast:6 row_mask:0xf bank_mask:0xf
	v_mul_f32_dpp v15, v94, v15 row_newbcast:7 row_mask:0xf bank_mask:0xf
	v_mul_f32_dpp v16, v94, v16 row_newbcast:8 row_mask:0xf bank_mask:0xf
	v_mul_f32_dpp v17, v94, v17 row_newbcast:9 row_mask:0xf bank_mask:0xf
	v_mul_f32_dpp v18, v94, v18 row_newbcast:10 row_mask:0xf bank_mask:0xf
	v_mul_f32_dpp v19, v94, v19 row_newbcast:11 row_mask:0xf bank_mask:0xf
	v_mul_f32_dpp v20, v94, v20 row_newbcast:12 row_mask:0xf bank_mask:0xf
	v_mul_f32_dpp v21, v94, v21 row_newbcast:13 row_mask:0xf bank_mask:0xf
	v_mul_f32_dpp v22, v94, v22 row_newbcast:14 row_mask:0xf bank_mask:0xf
	v_mul_f32_dpp v23, v94, v23 row_newbcast:15 row_mask:0xf bank_mask:0xf
	ds_write_b32 v107, v109 offset:9984
	v_cvt_pk_bf16_f32 v24, v8, v9
	v_cvt_pk_bf16_f32 v25, v10, v11
	v_cvt_pk_bf16_f32 v26, v12, v13
	v_cvt_pk_bf16_f32 v27, v14, v15
	v_cvt_pk_bf16_f32 v28, v16, v17
	v_cvt_pk_bf16_f32 v29, v18, v19
	s_waitcnt lgkmcnt(6)
	v_mfma_f32_16x16x32_bf16 v[32:35], v[40:43], v[24:27], 0
	v_cvt_pk_bf16_f32 v30, v20, v21
	v_cvt_pk_bf16_f32 v31, v22, v23
	s_waitcnt lgkmcnt(3)
	v_fmac_f32_dpp v8, v65, v66 row_newbcast:0 row_mask:0xf bank_mask:0xf
	v_fmac_f32_dpp v9, v65, v66 row_newbcast:1 row_mask:0xf bank_mask:0xf
	v_mfma_f32_16x16x32_bf16 v[32:35], v[44:47], v[28:31], v[32:35]
	v_fmac_f32_dpp v10, v65, v66 row_newbcast:2 row_mask:0xf bank_mask:0xf
	v_fmac_f32_dpp v11, v65, v66 row_newbcast:3 row_mask:0xf bank_mask:0xf
	ds_read_b128 v[70:73], v104 offset:2304
	v_fmac_f32_dpp v12, v65, v66 row_newbcast:4 row_mask:0xf bank_mask:0xf
	v_fmac_f32_dpp v13, v65, v66 row_newbcast:5 row_mask:0xf bank_mask:0xf
	ds_read_b128 v[74:77], v104 offset:2320
	v_fmac_f32_dpp v14, v65, v66 row_newbcast:6 row_mask:0xf bank_mask:0xf
	v_fmac_f32_dpp v15, v65, v66 row_newbcast:7 row_mask:0xf bank_mask:0xf
	ds_read_b32 v95, v105 offset:18688
	v_fmac_f32_dpp v16, v65, v66 row_newbcast:8 row_mask:0xf bank_mask:0xf
	v_fmac_f32_dpp v17, v65, v66 row_newbcast:9 row_mask:0xf bank_mask:0xf
	ds_read_b32 v96, v107 offset:2304
	v_fmac_f32_dpp v18, v65, v66 row_newbcast:10 row_mask:0xf bank_mask:0xf
	v_fmac_f32_dpp v19, v65, v66 row_newbcast:11 row_mask:0xf bank_mask:0xf
	ds_read_b32 v78, v105 offset:10496
	v_fmac_f32_dpp v20, v65, v66 row_newbcast:12 row_mask:0xf bank_mask:0xf
	v_fmac_f32_dpp v21, v65, v66 row_newbcast:13 row_mask:0xf bank_mask:0xf
	ds_read_b64 v[98:99], v108 offset:49224
	v_fmac_f32_dpp v22, v65, v66 row_newbcast:14 row_mask:0xf bank_mask:0xf
	v_fmac_f32_dpp v23, v65, v66 row_newbcast:15 row_mask:0xf bank_mask:0xf
	s_waitcnt lgkmcnt(8)
	s_waitcnt lgkmcnt(7)
	v_xor_b32_e32 v110, 0x80000000, v32
	v_fma_f32 v109, -v32, v68, v33
	v_fma_f32 v109, v66, v69, v109
	v_fmac_f32_dpp v8, v48, v110 row_newbcast:0 row_mask:0xf bank_mask:0xf
	v_fmac_f32_dpp v9, v48, v110 row_newbcast:1 row_mask:0xf bank_mask:0xf
	v_fmac_f32_dpp v10, v48, v110 row_newbcast:2 row_mask:0xf bank_mask:0xf
	v_fmac_f32_dpp v11, v48, v110 row_newbcast:3 row_mask:0xf bank_mask:0xf
	v_fmac_f32_dpp v12, v48, v110 row_newbcast:4 row_mask:0xf bank_mask:0xf
	v_fmac_f32_dpp v13, v48, v110 row_newbcast:5 row_mask:0xf bank_mask:0xf
	v_fmac_f32_dpp v14, v48, v110 row_newbcast:6 row_mask:0xf bank_mask:0xf
	v_fmac_f32_dpp v15, v48, v110 row_newbcast:7 row_mask:0xf bank_mask:0xf
	v_fmac_f32_dpp v16, v48, v110 row_newbcast:8 row_mask:0xf bank_mask:0xf
	v_fmac_f32_dpp v17, v48, v110 row_newbcast:9 row_mask:0xf bank_mask:0xf
	v_fmac_f32_dpp v18, v48, v110 row_newbcast:10 row_mask:0xf bank_mask:0xf
	v_fmac_f32_dpp v19, v48, v110 row_newbcast:11 row_mask:0xf bank_mask:0xf
	v_fmac_f32_dpp v20, v48, v110 row_newbcast:12 row_mask:0xf bank_mask:0xf
	v_fmac_f32_dpp v21, v48, v110 row_newbcast:13 row_mask:0xf bank_mask:0xf
	v_fmac_f32_dpp v22, v48, v110 row_newbcast:14 row_mask:0xf bank_mask:0xf
	v_fmac_f32_dpp v23, v48, v110 row_newbcast:15 row_mask:0xf bank_mask:0xf
	ds_write_b32 v107, v109 offset:10240
	v_cvt_pk_bf16_f32 v24, v8, v9
	v_cvt_pk_bf16_f32 v25, v10, v11
	v_cvt_pk_bf16_f32 v26, v12, v13
	v_cvt_pk_bf16_f32 v27, v14, v15
	v_cvt_pk_bf16_f32 v28, v16, v17
	v_cvt_pk_bf16_f32 v29, v18, v19
	s_waitcnt lgkmcnt(6)
; __device__ __forceinline__ void phase_rwkv_scan(const Params& p, int l, const int tidx) {
;     ...
;       for (int s = 0; s < RTC; s++) {
;         const bf16x8 A0 = nA0, A1 = nA1;
;         const float wA[8] = {nw0.x, nw0.y, nw0.z, nw0.w, nw1.x, nw1.y, nw1.z, nw1.w};
;         const float wB[8] = {nw2.x, nw2.y, nw2.z, nw2.w, nw3.x, nw3.y, nw3.z, nw3.w};
;         const float kaA[8] = {nka0.x, nka0.y, nka0.z, nka0.w, nka1.x, nka1.y, nka1.z, nka1.w};
;         const float kaB[8] = {nka2.x, nka2.y, nka2.z, nka2.w, nka3.x, nka3.y, nka3.z, nka3.w};
;         const float kdA[8] = {nkd0.x, nkd0.y, nkd0.z, nkd0.w, nkd1.x, nkd1.y, nkd1.z, nkd1.w};
;         const float kdB[8] = {nkd2.x, nkd2.y, nkd2.z, nkd2.w, nkd3.x, nkd3.y, nkd3.z, nkd3.w};
;         const float v = nv;
;         float c1 = nc.x, c2 = nc.y;
;         asm volatile("" : "+v"(c1), "+v"(c2));
;         if (s + 1 < RTC) RW_LD(s + 1);
;         u32x4 pa = {pack2(Sa[0], Sa[1]), pack2(Sa[2], Sa[3]), pack2(Sa[4], Sa[5]), pack2(Sa[6], Sa[7])};
;         u32x4 pb = {pack2(Sb[0], Sb[1]), pack2(Sb[2], Sb[3]), pack2(Sb[4], Sb[5]), pack2(Sb[6], Sb[7])};
;         f32x4 acc = {0.f, 0.f, 0.f, 0.f};
;         acc = __builtin_amdgcn_mfma_f32_16x16x32_bf16(A0, __builtin_bit_cast(bf16x8, pa), acc, 0, 0, 0);
;         acc = __builtin_amdgcn_mfma_f32_16x16x32_bf16(A1, __builtin_bit_cast(bf16x8, pb), acc, 0, 0, 0);
;         float tA[8], tB[8];
; #pragma unroll
;         for (int c = 0; c < 8; c++) { tA[c] = Sa[c] * wA[c] + v * kdA[c]; tB[c] = Sb[c] * wB[c] + v * kdB[c]; }
;         const float sa = -acc[0];
;         const float yq = acc[1];
; #pragma unroll
;         for (int c = 0; c < 8; c++) { Sa[c] = tA[c] + sa * kaA[c]; Sb[c] = tB[c] + sa * kaB[c]; }
;         const float y = yq + sa * c1 + v * c2;
;         if (quad == 0) by[s * 64 + row] = y;
;       }
	v_mfma_f32_16x16x32_bf16 v[32:35], v[70:73], v[24:27], 0
	v_cvt_pk_bf16_f32 v30, v20, v21
	v_cvt_pk_bf16_f32 v31, v22, v23
	s_waitcnt lgkmcnt(3)
	v_fmac_f32_dpp v8, v95, v96 row_newbcast:0 row_mask:0xf bank_mask:0xf
	v_fmac_f32_dpp v9, v95, v96 row_newbcast:1 row_mask:0xf bank_mask:0xf
	v_mfma_f32_16x16x32_bf16 v[32:35], v[74:77], v[28:31], v[32:35]
	v_fmac_f32_dpp v10, v95, v96 row_newbcast:2 row_mask:0xf bank_mask:0xf
	v_fmac_f32_dpp v11, v95, v96 row_newbcast:3 row_mask:0xf bank_mask:0xf
	ds_read_b128 v[40:43], v104 offset:2560
	v_fmac_f32_dpp v12, v95, v96 row_newbcast:4 row_mask:0xf bank_mask:0xf
	v_fmac_f32_dpp v13, v95, v96 row_newbcast:5 row_mask:0xf bank_mask:0xf
	ds_read_b128 v[44:47], v104 offset:2576
	v_fmac_f32_dpp v14, v95, v96 row_newbcast:6 row_mask:0xf bank_mask:0xf
	v_fmac_f32_dpp v15, v95, v96 row_newbcast:7 row_mask:0xf bank_mask:0xf
	ds_read_b32 v65, v105 offset:18944
	v_fmac_f32_dpp v16, v95, v96 row_newbcast:8 row_mask:0xf bank_mask:0xf
	v_fmac_f32_dpp v17, v95, v96 row_newbcast:9 row_mask:0xf bank_mask:0xf
	ds_read_b32 v66, v107 offset:2560
	v_fmac_f32_dpp v18, v95, v96 row_newbcast:10 row_mask:0xf bank_mask:0xf
	v_fmac_f32_dpp v19, v95, v96 row_newbcast:11 row_mask:0xf bank_mask:0xf
	ds_read_b32 v48, v105 offset:10752
	v_fmac_f32_dpp v20, v95, v96 row_newbcast:12 row_mask:0xf bank_mask:0xf
	v_fmac_f32_dpp v21, v95, v96 row_newbcast:13 row_mask:0xf bank_mask:0xf
	ds_read_b64 v[68:69], v108 offset:49232
	v_fmac_f32_dpp v22, v95, v96 row_newbcast:14 row_mask:0xf bank_mask:0xf
	v_fmac_f32_dpp v23, v95, v96 row_newbcast:15 row_mask:0xf bank_mask:0xf
	s_waitcnt lgkmcnt(8)
	s_waitcnt lgkmcnt(7)
	v_xor_b32_e32 v110, 0x80000000, v32
	v_fma_f32 v109, -v32, v98, v33
	v_fma_f32 v109, v96, v99, v109
	v_fmac_f32_dpp v8, v78, v110 row_newbcast:0 row_mask:0xf bank_mask:0xf
	v_fmac_f32_dpp v9, v78, v110 row_newbcast:1 row_mask:0xf bank_mask:0xf
	v_fmac_f32_dpp v10, v78, v110 row_newbcast:2 row_mask:0xf bank_mask:0xf
	v_fmac_f32_dpp v11, v78, v110 row_newbcast:3 row_mask:0xf bank_mask:0xf
	v_fmac_f32_dpp v12, v78, v110 row_newbcast:4 row_mask:0xf bank_mask:0xf
	v_fmac_f32_dpp v13, v78, v110 row_newbcast:5 row_mask:0xf bank_mask:0xf
	v_fmac_f32_dpp v14, v78, v110 row_newbcast:6 row_mask:0xf bank_mask:0xf
	v_fmac_f32_dpp v15, v78, v110 row_newbcast:7 row_mask:0xf bank_mask:0xf
	v_fmac_f32_dpp v16, v78, v110 row_newbcast:8 row_mask:0xf bank_mask:0xf
	v_fmac_f32_dpp v17, v78, v110 row_newbcast:9 row_mask:0xf bank_mask:0xf
	v_fmac_f32_dpp v18, v78, v110 row_newbcast:10 row_mask:0xf bank_mask:0xf
	v_fmac_f32_dpp v19, v78, v110 row_newbcast:11 row_mask:0xf bank_mask:0xf
	v_fmac_f32_dpp v20, v78, v110 row_newbcast:12 row_mask:0xf bank_mask:0xf
	v_fmac_f32_dpp v21, v78, v110 row_newbcast:13 row_mask:0xf bank_mask:0xf
	v_fmac_f32_dpp v22, v78, v110 row_newbcast:14 row_mask:0xf bank_mask:0xf
	v_fmac_f32_dpp v23, v78, v110 row_newbcast:15 row_mask:0xf bank_mask:0xf
	ds_write_b32 v107, v109 offset:10496
	v_cvt_pk_bf16_f32 v24, v8, v9
	v_cvt_pk_bf16_f32 v25, v10, v11
	v_cvt_pk_bf16_f32 v26, v12, v13
	v_cvt_pk_bf16_f32 v27, v14, v15
	v_cvt_pk_bf16_f32 v28, v16, v17
	v_cvt_pk_bf16_f32 v29, v18, v19
	s_waitcnt lgkmcnt(6)
	v_mfma_f32_16x16x32_bf16 v[32:35], v[40:43], v[24:27], 0
	v_cvt_pk_bf16_f32 v30, v20, v21
	v_cvt_pk_bf16_f32 v31, v22, v23
	s_waitcnt lgkmcnt(3)
	v_fmac_f32_dpp v8, v65, v66 row_newbcast:0 row_mask:0xf bank_mask:0xf
	v_fmac_f32_dpp v9, v65, v66 row_newbcast:1 row_mask:0xf bank_mask:0xf
	v_mfma_f32_16x16x32_bf16 v[32:35], v[44:47], v[28:31], v[32:35]
	v_fmac_f32_dpp v10, v65, v66 row_newbcast:2 row_mask:0xf bank_mask:0xf
	v_fmac_f32_dpp v11, v65, v66 row_newbcast:3 row_mask:0xf bank_mask:0xf
	ds_read_b128 v[70:73], v104 offset:2816
	v_fmac_f32_dpp v12, v65, v66 row_newbcast:4 row_mask:0xf bank_mask:0xf
	v_fmac_f32_dpp v13, v65, v66 row_newbcast:5 row_mask:0xf bank_mask:0xf
	ds_read_b128 v[74:77], v104 offset:2832
	v_fmac_f32_dpp v14, v65, v66 row_newbcast:6 row_mask:0xf bank_mask:0xf
	v_fmac_f32_dpp v15, v65, v66 row_newbcast:7 row_mask:0xf bank_mask:0xf
	ds_read_b32 v95, v105 offset:19200
	v_fmac_f32_dpp v16, v65, v66 row_newbcast:8 row_mask:0xf bank_mask:0xf
	v_fmac_f32_dpp v17, v65, v66 row_newbcast:9 row_mask:0xf bank_mask:0xf
	ds_read_b32 v96, v107 offset:2816
	v_fmac_f32_dpp v18, v65, v66 row_newbcast:10 row_mask:0xf bank_mask:0xf
	v_fmac_f32_dpp v19, v65, v66 row_newbcast:11 row_mask:0xf bank_mask:0xf
	ds_read_b32 v78, v105 offset:11008
	v_fmac_f32_dpp v20, v65, v66 row_newbcast:12 row_mask:0xf bank_mask:0xf
	v_fmac_f32_dpp v21, v65, v66 row_newbcast:13 row_mask:0xf bank_mask:0xf
	ds_read_b64 v[98:99], v108 offset:49240
	v_fmac_f32_dpp v22, v65, v66 row_newbcast:14 row_mask:0xf bank_mask:0xf
	v_fmac_f32_dpp v23, v65, v66 row_newbcast:15 row_mask:0xf bank_mask:0xf
	s_waitcnt lgkmcnt(8)
	s_waitcnt lgkmcnt(7)
	v_xor_b32_e32 v110, 0x80000000, v32
	v_fma_f32 v109, -v32, v68, v33
	v_fma_f32 v109, v66, v69, v109
	v_fmac_f32_dpp v8, v48, v110 row_newbcast:0 row_mask:0xf bank_mask:0xf
	v_fmac_f32_dpp v9, v48, v110 row_newbcast:1 row_mask:0xf bank_mask:0xf
	v_fmac_f32_dpp v10, v48, v110 row_newbcast:2 row_mask:0xf bank_mask:0xf
	v_fmac_f32_dpp v11, v48, v110 row_newbcast:3 row_mask:0xf bank_mask:0xf
	v_fmac_f32_dpp v12, v48, v110 row_newbcast:4 row_mask:0xf bank_mask:0xf
	v_fmac_f32_dpp v13, v48, v110 row_newbcast:5 row_mask:0xf bank_mask:0xf
	v_fmac_f32_dpp v14, v48, v110 row_newbcast:6 row_mask:0xf bank_mask:0xf
	v_fmac_f32_dpp v15, v48, v110 row_newbcast:7 row_mask:0xf bank_mask:0xf
	v_fmac_f32_dpp v16, v48, v110 row_newbcast:8 row_mask:0xf bank_mask:0xf
	v_fmac_f32_dpp v17, v48, v110 row_newbcast:9 row_mask:0xf bank_mask:0xf
	v_fmac_f32_dpp v18, v48, v110 row_newbcast:10 row_mask:0xf bank_mask:0xf
	v_fmac_f32_dpp v19, v48, v110 row_newbcast:11 row_mask:0xf bank_mask:0xf
	v_fmac_f32_dpp v20, v48, v110 row_newbcast:12 row_mask:0xf bank_mask:0xf
	v_fmac_f32_dpp v21, v48, v110 row_newbcast:13 row_mask:0xf bank_mask:0xf
	v_fmac_f32_dpp v22, v48, v110 row_newbcast:14 row_mask:0xf bank_mask:0xf
	v_fmac_f32_dpp v23, v48, v110 row_newbcast:15 row_mask:0xf bank_mask:0xf
	ds_write_b32 v107, v109 offset:10752
	v_cvt_pk_bf16_f32 v24, v8, v9
	v_cvt_pk_bf16_f32 v25, v10, v11
	v_cvt_pk_bf16_f32 v26, v12, v13
	v_cvt_pk_bf16_f32 v27, v14, v15
	v_cvt_pk_bf16_f32 v28, v16, v17
	v_cvt_pk_bf16_f32 v29, v18, v19
	s_waitcnt lgkmcnt(6)
; __device__ __forceinline__ void phase_rwkv_scan(const Params& p, int l, const int tidx) {
;     ...
;       for (int s = 0; s < RTC; s++) {
;         const bf16x8 A0 = nA0, A1 = nA1;
;         const float wA[8] = {nw0.x, nw0.y, nw0.z, nw0.w, nw1.x, nw1.y, nw1.z, nw1.w};
;         const float wB[8] = {nw2.x, nw2.y, nw2.z, nw2.w, nw3.x, nw3.y, nw3.z, nw3.w};
;         const float kaA[8] = {nka0.x, nka0.y, nka0.z, nka0.w, nka1.x, nka1.y, nka1.z, nka1.w};
;         const float kaB[8] = {nka2.x, nka2.y, nka2.z, nka2.w, nka3.x, nka3.y, nka3.z, nka3.w};
;         const float kdA[8] = {nkd0.x, nkd0.y, nkd0.z, nkd0.w, nkd1.x, nkd1.y, nkd1.z, nkd1.w};
;         const float kdB[8] = {nkd2.x, nkd2.y, nkd2.z, nkd2.w, nkd3.x, nkd3.y, nkd3.z, nkd3.w};
;         const float v = nv;
;         float c1 = nc.x, c2 = nc.y;
;         asm volatile("" : "+v"(c1), "+v"(c2));
;         if (s + 1 < RTC) RW_LD(s + 1);
;         u32x4 pa = {pack2(Sa[0], Sa[1]), pack2(Sa[2], Sa[3]), pack2(Sa[4], Sa[5]), pack2(Sa[6], Sa[7])};
;         u32x4 pb = {pack2(Sb[0], Sb[1]), pack2(Sb[2], Sb[3]), pack2(Sb[4], Sb[5]), pack2(Sb[6], Sb[7])};
;         f32x4 acc = {0.f, 0.f, 0.f, 0.f};
;         acc = __builtin_amdgcn_mfma_f32_16x16x32_bf16(A0, __builtin_bit_cast(bf16x8, pa), acc, 0, 0, 0);
;         acc = __builtin_amdgcn_mfma_f32_16x16x32_bf16(A1, __builtin_bit_cast(bf16x8, pb), acc, 0, 0, 0);
;         float tA[8], tB[8];
; #pragma unroll
;         for (int c = 0; c < 8; c++) { tA[c] = Sa[c] * wA[c] + v * kdA[c]; tB[c] = Sb[c] * wB[c] + v * kdB[c]; }
;         const float sa = -acc[0];
;         const float yq = acc[1];
; #pragma unroll
;         for (int c = 0; c < 8; c++) { Sa[c] = tA[c] + sa * kaA[c]; Sb[c] = tB[c] + sa * kaB[c]; }
;         const float y = yq + sa * c1 + v * c2;
;         if (quad == 0) by[s * 64 + row] = y;
;       }
	v_mfma_f32_16x16x32_bf16 v[32:35], v[70:73], v[24:27], 0
	v_cvt_pk_bf16_f32 v30, v20, v21
	v_cvt_pk_bf16_f32 v31, v22, v23
	s_waitcnt lgkmcnt(3)
	v_fmac_f32_dpp v8, v95, v96 row_newbcast:0 row_mask:0xf bank_mask:0xf
	v_fmac_f32_dpp v9, v95, v96 row_newbcast:1 row_mask:0xf bank_mask:0xf
	v_mfma_f32_16x16x32_bf16 v[32:35], v[74:77], v[28:31], v[32:35]
	v_fmac_f32_dpp v10, v95, v96 row_newbcast:2 row_mask:0xf bank_mask:0xf
	v_fmac_f32_dpp v11, v95, v96 row_newbcast:3 row_mask:0xf bank_mask:0xf
	ds_read_b128 v[40:43], v104 offset:3072
	v_fmac_f32_dpp v12, v95, v96 row_newbcast:4 row_mask:0xf bank_mask:0xf
	v_fmac_f32_dpp v13, v95, v96 row_newbcast:5 row_mask:0xf bank_mask:0xf
	ds_read_b128 v[44:47], v104 offset:3088
	v_fmac_f32_dpp v14, v95, v96 row_newbcast:6 row_mask:0xf bank_mask:0xf
	v_fmac_f32_dpp v15, v95, v96 row_newbcast:7 row_mask:0xf bank_mask:0xf
	ds_read_b32 v65, v105 offset:19456
	v_fmac_f32_dpp v16, v95, v96 row_newbcast:8 row_mask:0xf bank_mask:0xf
	v_fmac_f32_dpp v17, v95, v96 row_newbcast:9 row_mask:0xf bank_mask:0xf
	ds_read_b32 v66, v107 offset:3072
	v_fmac_f32_dpp v18, v95, v96 row_newbcast:10 row_mask:0xf bank_mask:0xf
	v_fmac_f32_dpp v19, v95, v96 row_newbcast:11 row_mask:0xf bank_mask:0xf
	ds_read_b32 v48, v105 offset:11264
	v_fmac_f32_dpp v20, v95, v96 row_newbcast:12 row_mask:0xf bank_mask:0xf
	v_fmac_f32_dpp v21, v95, v96 row_newbcast:13 row_mask:0xf bank_mask:0xf
	ds_read_b64 v[68:69], v108 offset:49248
	v_fmac_f32_dpp v22, v95, v96 row_newbcast:14 row_mask:0xf bank_mask:0xf
	v_fmac_f32_dpp v23, v95, v96 row_newbcast:15 row_mask:0xf bank_mask:0xf
	s_waitcnt lgkmcnt(8)
	s_waitcnt lgkmcnt(7)
	v_xor_b32_e32 v110, 0x80000000, v32
	v_fma_f32 v109, -v32, v98, v33
	v_fma_f32 v109, v96, v99, v109
	v_fmac_f32_dpp v8, v78, v110 row_newbcast:0 row_mask:0xf bank_mask:0xf
	v_fmac_f32_dpp v9, v78, v110 row_newbcast:1 row_mask:0xf bank_mask:0xf
	v_fmac_f32_dpp v10, v78, v110 row_newbcast:2 row_mask:0xf bank_mask:0xf
	v_fmac_f32_dpp v11, v78, v110 row_newbcast:3 row_mask:0xf bank_mask:0xf
	v_fmac_f32_dpp v12, v78, v110 row_newbcast:4 row_mask:0xf bank_mask:0xf
	v_fmac_f32_dpp v13, v78, v110 row_newbcast:5 row_mask:0xf bank_mask:0xf
	v_fmac_f32_dpp v14, v78, v110 row_newbcast:6 row_mask:0xf bank_mask:0xf
	v_fmac_f32_dpp v15, v78, v110 row_newbcast:7 row_mask:0xf bank_mask:0xf
	v_fmac_f32_dpp v16, v78, v110 row_newbcast:8 row_mask:0xf bank_mask:0xf
	v_fmac_f32_dpp v17, v78, v110 row_newbcast:9 row_mask:0xf bank_mask:0xf
	v_fmac_f32_dpp v18, v78, v110 row_newbcast:10 row_mask:0xf bank_mask:0xf
	v_fmac_f32_dpp v19, v78, v110 row_newbcast:11 row_mask:0xf bank_mask:0xf
	v_fmac_f32_dpp v20, v78, v110 row_newbcast:12 row_mask:0xf bank_mask:0xf
	v_fmac_f32_dpp v21, v78, v110 row_newbcast:13 row_mask:0xf bank_mask:0xf
	v_fmac_f32_dpp v22, v78, v110 row_newbcast:14 row_mask:0xf bank_mask:0xf
	v_fmac_f32_dpp v23, v78, v110 row_newbcast:15 row_mask:0xf bank_mask:0xf
	ds_write_b32 v107, v109 offset:11008
	v_cvt_pk_bf16_f32 v24, v8, v9
	v_cvt_pk_bf16_f32 v25, v10, v11
	v_cvt_pk_bf16_f32 v26, v12, v13
	v_cvt_pk_bf16_f32 v27, v14, v15
	v_cvt_pk_bf16_f32 v28, v16, v17
	v_cvt_pk_bf16_f32 v29, v18, v19
	s_waitcnt lgkmcnt(6)
	v_mfma_f32_16x16x32_bf16 v[32:35], v[40:43], v[24:27], 0
	v_cvt_pk_bf16_f32 v30, v20, v21
	v_cvt_pk_bf16_f32 v31, v22, v23
	s_waitcnt lgkmcnt(3)
	v_fmac_f32_dpp v8, v65, v66 row_newbcast:0 row_mask:0xf bank_mask:0xf
	v_fmac_f32_dpp v9, v65, v66 row_newbcast:1 row_mask:0xf bank_mask:0xf
	v_mfma_f32_16x16x32_bf16 v[32:35], v[44:47], v[28:31], v[32:35]
	v_fmac_f32_dpp v10, v65, v66 row_newbcast:2 row_mask:0xf bank_mask:0xf
	v_fmac_f32_dpp v11, v65, v66 row_newbcast:3 row_mask:0xf bank_mask:0xf
	ds_read_b128 v[70:73], v104 offset:3328
	v_fmac_f32_dpp v12, v65, v66 row_newbcast:4 row_mask:0xf bank_mask:0xf
	v_fmac_f32_dpp v13, v65, v66 row_newbcast:5 row_mask:0xf bank_mask:0xf
	ds_read_b128 v[74:77], v104 offset:3344
	v_fmac_f32_dpp v14, v65, v66 row_newbcast:6 row_mask:0xf bank_mask:0xf
	v_fmac_f32_dpp v15, v65, v66 row_newbcast:7 row_mask:0xf bank_mask:0xf
	ds_read_b32 v95, v105 offset:19712
	v_fmac_f32_dpp v16, v65, v66 row_newbcast:8 row_mask:0xf bank_mask:0xf
	v_fmac_f32_dpp v17, v65, v66 row_newbcast:9 row_mask:0xf bank_mask:0xf
	ds_read_b32 v96, v107 offset:3328
	v_fmac_f32_dpp v18, v65, v66 row_newbcast:10 row_mask:0xf bank_mask:0xf
	v_fmac_f32_dpp v19, v65, v66 row_newbcast:11 row_mask:0xf bank_mask:0xf
	ds_read_b32 v78, v105 offset:11520
	v_fmac_f32_dpp v20, v65, v66 row_newbcast:12 row_mask:0xf bank_mask:0xf
	v_fmac_f32_dpp v21, v65, v66 row_newbcast:13 row_mask:0xf bank_mask:0xf
	ds_read_b64 v[98:99], v108 offset:49256
	v_fmac_f32_dpp v22, v65, v66 row_newbcast:14 row_mask:0xf bank_mask:0xf
	v_fmac_f32_dpp v23, v65, v66 row_newbcast:15 row_mask:0xf bank_mask:0xf
	s_waitcnt lgkmcnt(8)
	s_waitcnt lgkmcnt(7)
	v_xor_b32_e32 v110, 0x80000000, v32
	v_fma_f32 v109, -v32, v68, v33
	v_fma_f32 v109, v66, v69, v109
	v_fmac_f32_dpp v8, v48, v110 row_newbcast:0 row_mask:0xf bank_mask:0xf
	v_fmac_f32_dpp v9, v48, v110 row_newbcast:1 row_mask:0xf bank_mask:0xf
	v_fmac_f32_dpp v10, v48, v110 row_newbcast:2 row_mask:0xf bank_mask:0xf
	v_fmac_f32_dpp v11, v48, v110 row_newbcast:3 row_mask:0xf bank_mask:0xf
	v_fmac_f32_dpp v12, v48, v110 row_newbcast:4 row_mask:0xf bank_mask:0xf
	v_fmac_f32_dpp v13, v48, v110 row_newbcast:5 row_mask:0xf bank_mask:0xf
	v_fmac_f32_dpp v14, v48, v110 row_newbcast:6 row_mask:0xf bank_mask:0xf
	v_fmac_f32_dpp v15, v48, v110 row_newbcast:7 row_mask:0xf bank_mask:0xf
	v_fmac_f32_dpp v16, v48, v110 row_newbcast:8 row_mask:0xf bank_mask:0xf
	v_fmac_f32_dpp v17, v48, v110 row_newbcast:9 row_mask:0xf bank_mask:0xf
	v_fmac_f32_dpp v18, v48, v110 row_newbcast:10 row_mask:0xf bank_mask:0xf
	v_fmac_f32_dpp v19, v48, v110 row_newbcast:11 row_mask:0xf bank_mask:0xf
	v_fmac_f32_dpp v20, v48, v110 row_newbcast:12 row_mask:0xf bank_mask:0xf
	v_fmac_f32_dpp v21, v48, v110 row_newbcast:13 row_mask:0xf bank_mask:0xf
	v_fmac_f32_dpp v22, v48, v110 row_newbcast:14 row_mask:0xf bank_mask:0xf
	v_fmac_f32_dpp v23, v48, v110 row_newbcast:15 row_mask:0xf bank_mask:0xf
	ds_write_b32 v107, v109 offset:11264
	v_cvt_pk_bf16_f32 v24, v8, v9
	v_cvt_pk_bf16_f32 v25, v10, v11
	v_cvt_pk_bf16_f32 v26, v12, v13
	v_cvt_pk_bf16_f32 v27, v14, v15
	v_cvt_pk_bf16_f32 v28, v16, v17
	v_cvt_pk_bf16_f32 v29, v18, v19
	s_waitcnt lgkmcnt(6)
; __device__ __forceinline__ void phase_rwkv_scan(const Params& p, int l, const int tidx) {
;     ...
;       for (int s = 0; s < RTC; s++) {
;         const bf16x8 A0 = nA0, A1 = nA1;
;         const float wA[8] = {nw0.x, nw0.y, nw0.z, nw0.w, nw1.x, nw1.y, nw1.z, nw1.w};
;         const float wB[8] = {nw2.x, nw2.y, nw2.z, nw2.w, nw3.x, nw3.y, nw3.z, nw3.w};
;         const float kaA[8] = {nka0.x, nka0.y, nka0.z, nka0.w, nka1.x, nka1.y, nka1.z, nka1.w};
;         const float kaB[8] = {nka2.x, nka2.y, nka2.z, nka2.w, nka3.x, nka3.y, nka3.z, nka3.w};
;         const float kdA[8] = {nkd0.x, nkd0.y, nkd0.z, nkd0.w, nkd1.x, nkd1.y, nkd1.z, nkd1.w};
;         const float kdB[8] = {nkd2.x, nkd2.y, nkd2.z, nkd2.w, nkd3.x, nkd3.y, nkd3.z, nkd3.w};
;         const float v = nv;
;         float c1 = nc.x, c2 = nc.y;
;         asm volatile("" : "+v"(c1), "+v"(c2));
;         if (s + 1 < RTC) RW_LD(s + 1);
;         u32x4 pa = {pack2(Sa[0], Sa[1]), pack2(Sa[2], Sa[3]), pack2(Sa[4], Sa[5]), pack2(Sa[6], Sa[7])};
;         u32x4 pb = {pack2(Sb[0], Sb[1]), pack2(Sb[2], Sb[3]), pack2(Sb[4], Sb[5]), pack2(Sb[6], Sb[7])};
;         f32x4 acc = {0.f, 0.f, 0.f, 0.f};
;         acc = __builtin_amdgcn_mfma_f32_16x16x32_bf16(A0, __builtin_bit_cast(bf16x8, pa), acc, 0, 0, 0);
;         acc = __builtin_amdgcn_mfma_f32_16x16x32_bf16(A1, __builtin_bit_cast(bf16x8, pb), acc, 0, 0, 0);
;         float tA[8], tB[8];
; #pragma unroll
;         for (int c = 0; c < 8; c++) { tA[c] = Sa[c] * wA[c] + v * kdA[c]; tB[c] = Sb[c] * wB[c] + v * kdB[c]; }
;         const float sa = -acc[0];
;         const float yq = acc[1];
; #pragma unroll
;         for (int c = 0; c < 8; c++) { Sa[c] = tA[c] + sa * kaA[c]; Sb[c] = tB[c] + sa * kaB[c]; }
;         const float y = yq + sa * c1 + v * c2;
;         if (quad == 0) by[s * 64 + row] = y;
;       }
	v_mfma_f32_16x16x32_bf16 v[32:35], v[70:73], v[24:27], 0
	v_cvt_pk_bf16_f32 v30, v20, v21
	v_cvt_pk_bf16_f32 v31, v22, v23
	s_waitcnt lgkmcnt(3)
	v_fmac_f32_dpp v8, v95, v96 row_newbcast:0 row_mask:0xf bank_mask:0xf
	v_fmac_f32_dpp v9, v95, v96 row_newbcast:1 row_mask:0xf bank_mask:0xf
	v_mfma_f32_16x16x32_bf16 v[32:35], v[74:77], v[28:31], v[32:35]
	v_fmac_f32_dpp v10, v95, v96 row_newbcast:2 row_mask:0xf bank_mask:0xf
	v_fmac_f32_dpp v11, v95, v96 row_newbcast:3 row_mask:0xf bank_mask:0xf
	ds_read_b128 v[40:43], v104 offset:3584
	v_fmac_f32_dpp v12, v95, v96 row_newbcast:4 row_mask:0xf bank_mask:0xf
	v_fmac_f32_dpp v13, v95, v96 row_newbcast:5 row_mask:0xf bank_mask:0xf
	ds_read_b128 v[44:47], v104 offset:3600
	v_fmac_f32_dpp v14, v95, v96 row_newbcast:6 row_mask:0xf bank_mask:0xf
	v_fmac_f32_dpp v15, v95, v96 row_newbcast:7 row_mask:0xf bank_mask:0xf
	ds_read_b32 v65, v105 offset:19968
	v_fmac_f32_dpp v16, v95, v96 row_newbcast:8 row_mask:0xf bank_mask:0xf
	v_fmac_f32_dpp v17, v95, v96 row_newbcast:9 row_mask:0xf bank_mask:0xf
	ds_read_b32 v66, v107 offset:3584
	v_fmac_f32_dpp v18, v95, v96 row_newbcast:10 row_mask:0xf bank_mask:0xf
	v_fmac_f32_dpp v19, v95, v96 row_newbcast:11 row_mask:0xf bank_mask:0xf
	ds_read_b32 v48, v105 offset:11776
	v_fmac_f32_dpp v20, v95, v96 row_newbcast:12 row_mask:0xf bank_mask:0xf
	v_fmac_f32_dpp v21, v95, v96 row_newbcast:13 row_mask:0xf bank_mask:0xf
	ds_read_b64 v[68:69], v108 offset:49264
	v_fmac_f32_dpp v22, v95, v96 row_newbcast:14 row_mask:0xf bank_mask:0xf
	v_fmac_f32_dpp v23, v95, v96 row_newbcast:15 row_mask:0xf bank_mask:0xf
	s_waitcnt lgkmcnt(8)
	s_waitcnt lgkmcnt(7)
	v_xor_b32_e32 v110, 0x80000000, v32
	v_fma_f32 v109, -v32, v98, v33
	v_fma_f32 v109, v96, v99, v109
	v_fmac_f32_dpp v8, v78, v110 row_newbcast:0 row_mask:0xf bank_mask:0xf
	v_fmac_f32_dpp v9, v78, v110 row_newbcast:1 row_mask:0xf bank_mask:0xf
	v_fmac_f32_dpp v10, v78, v110 row_newbcast:2 row_mask:0xf bank_mask:0xf
	v_fmac_f32_dpp v11, v78, v110 row_newbcast:3 row_mask:0xf bank_mask:0xf
	v_fmac_f32_dpp v12, v78, v110 row_newbcast:4 row_mask:0xf bank_mask:0xf
	v_fmac_f32_dpp v13, v78, v110 row_newbcast:5 row_mask:0xf bank_mask:0xf
	v_fmac_f32_dpp v14, v78, v110 row_newbcast:6 row_mask:0xf bank_mask:0xf
	v_fmac_f32_dpp v15, v78, v110 row_newbcast:7 row_mask:0xf bank_mask:0xf
	v_fmac_f32_dpp v16, v78, v110 row_newbcast:8 row_mask:0xf bank_mask:0xf
	v_fmac_f32_dpp v17, v78, v110 row_newbcast:9 row_mask:0xf bank_mask:0xf
	v_fmac_f32_dpp v18, v78, v110 row_newbcast:10 row_mask:0xf bank_mask:0xf
	v_fmac_f32_dpp v19, v78, v110 row_newbcast:11 row_mask:0xf bank_mask:0xf
	v_fmac_f32_dpp v20, v78, v110 row_newbcast:12 row_mask:0xf bank_mask:0xf
	v_fmac_f32_dpp v21, v78, v110 row_newbcast:13 row_mask:0xf bank_mask:0xf
	v_fmac_f32_dpp v22, v78, v110 row_newbcast:14 row_mask:0xf bank_mask:0xf
	v_fmac_f32_dpp v23, v78, v110 row_newbcast:15 row_mask:0xf bank_mask:0xf
	ds_write_b32 v107, v109 offset:11520
	v_cvt_pk_bf16_f32 v24, v8, v9
	v_cvt_pk_bf16_f32 v25, v10, v11
	v_cvt_pk_bf16_f32 v26, v12, v13
	v_cvt_pk_bf16_f32 v27, v14, v15
	v_cvt_pk_bf16_f32 v28, v16, v17
	v_cvt_pk_bf16_f32 v29, v18, v19
	s_waitcnt lgkmcnt(6)
	v_mfma_f32_16x16x32_bf16 v[32:35], v[40:43], v[24:27], 0
	v_cvt_pk_bf16_f32 v30, v20, v21
	v_cvt_pk_bf16_f32 v31, v22, v23
	s_waitcnt lgkmcnt(3)
	v_fmac_f32_dpp v8, v65, v66 row_newbcast:0 row_mask:0xf bank_mask:0xf
	v_fmac_f32_dpp v9, v65, v66 row_newbcast:1 row_mask:0xf bank_mask:0xf
	v_mfma_f32_16x16x32_bf16 v[32:35], v[44:47], v[28:31], v[32:35]
	v_fmac_f32_dpp v10, v65, v66 row_newbcast:2 row_mask:0xf bank_mask:0xf
	v_fmac_f32_dpp v11, v65, v66 row_newbcast:3 row_mask:0xf bank_mask:0xf
	ds_read_b128 v[70:73], v104 offset:3840
	v_fmac_f32_dpp v12, v65, v66 row_newbcast:4 row_mask:0xf bank_mask:0xf
	v_fmac_f32_dpp v13, v65, v66 row_newbcast:5 row_mask:0xf bank_mask:0xf
	ds_read_b128 v[74:77], v104 offset:3856
	v_fmac_f32_dpp v14, v65, v66 row_newbcast:6 row_mask:0xf bank_mask:0xf
	v_fmac_f32_dpp v15, v65, v66 row_newbcast:7 row_mask:0xf bank_mask:0xf
	ds_read_b32 v94, v105 offset:3840
	v_fmac_f32_dpp v16, v65, v66 row_newbcast:8 row_mask:0xf bank_mask:0xf
	v_fmac_f32_dpp v17, v65, v66 row_newbcast:9 row_mask:0xf bank_mask:0xf
	ds_read_b32 v95, v105 offset:20224
	v_fmac_f32_dpp v18, v65, v66 row_newbcast:10 row_mask:0xf bank_mask:0xf
	v_fmac_f32_dpp v19, v65, v66 row_newbcast:11 row_mask:0xf bank_mask:0xf
	ds_read_b32 v96, v107 offset:3840
	v_fmac_f32_dpp v20, v65, v66 row_newbcast:12 row_mask:0xf bank_mask:0xf
	v_fmac_f32_dpp v21, v65, v66 row_newbcast:13 row_mask:0xf bank_mask:0xf
	ds_read_b32 v78, v105 offset:12032
	v_fmac_f32_dpp v22, v65, v66 row_newbcast:14 row_mask:0xf bank_mask:0xf
	v_fmac_f32_dpp v23, v65, v66 row_newbcast:15 row_mask:0xf bank_mask:0xf
	ds_read_b64 v[98:99], v108 offset:49272
	s_waitcnt lgkmcnt(9)
	s_waitcnt lgkmcnt(8)
	v_xor_b32_e32 v110, 0x80000000, v32
	v_fma_f32 v109, -v32, v68, v33
	v_fma_f32 v109, v66, v69, v109
	v_fmac_f32_dpp v8, v48, v110 row_newbcast:0 row_mask:0xf bank_mask:0xf
	v_fmac_f32_dpp v9, v48, v110 row_newbcast:1 row_mask:0xf bank_mask:0xf
	v_fmac_f32_dpp v10, v48, v110 row_newbcast:2 row_mask:0xf bank_mask:0xf
	v_fmac_f32_dpp v11, v48, v110 row_newbcast:3 row_mask:0xf bank_mask:0xf
	v_fmac_f32_dpp v12, v48, v110 row_newbcast:4 row_mask:0xf bank_mask:0xf
	v_fmac_f32_dpp v13, v48, v110 row_newbcast:5 row_mask:0xf bank_mask:0xf
	v_fmac_f32_dpp v14, v48, v110 row_newbcast:6 row_mask:0xf bank_mask:0xf
	v_fmac_f32_dpp v15, v48, v110 row_newbcast:7 row_mask:0xf bank_mask:0xf
	v_fmac_f32_dpp v16, v48, v110 row_newbcast:8 row_mask:0xf bank_mask:0xf
	v_fmac_f32_dpp v17, v48, v110 row_newbcast:9 row_mask:0xf bank_mask:0xf
	v_fmac_f32_dpp v18, v48, v110 row_newbcast:10 row_mask:0xf bank_mask:0xf
	v_fmac_f32_dpp v19, v48, v110 row_newbcast:11 row_mask:0xf bank_mask:0xf
	v_fmac_f32_dpp v20, v48, v110 row_newbcast:12 row_mask:0xf bank_mask:0xf
	v_fmac_f32_dpp v21, v48, v110 row_newbcast:13 row_mask:0xf bank_mask:0xf
	v_fmac_f32_dpp v22, v48, v110 row_newbcast:14 row_mask:0xf bank_mask:0xf
	v_fmac_f32_dpp v23, v48, v110 row_newbcast:15 row_mask:0xf bank_mask:0xf
	ds_write_b32 v107, v109 offset:11776
	v_cvt_pk_bf16_f32 v24, v8, v9
	v_cvt_pk_bf16_f32 v25, v10, v11
	v_cvt_pk_bf16_f32 v26, v12, v13
	v_cvt_pk_bf16_f32 v27, v14, v15
	v_cvt_pk_bf16_f32 v28, v16, v17
	v_cvt_pk_bf16_f32 v29, v18, v19
	s_waitcnt lgkmcnt(7)
; __device__ __forceinline__ void phase_rwkv_scan(const Params& p, int l, const int tidx) {
;     ...
;       for (int s = 0; s < RTC; s++) {
;         const bf16x8 A0 = nA0, A1 = nA1;
;         const float wA[8] = {nw0.x, nw0.y, nw0.z, nw0.w, nw1.x, nw1.y, nw1.z, nw1.w};
;         const float wB[8] = {nw2.x, nw2.y, nw2.z, nw2.w, nw3.x, nw3.y, nw3.z, nw3.w};
;         const float kaA[8] = {nka0.x, nka0.y, nka0.z, nka0.w, nka1.x, nka1.y, nka1.z, nka1.w};
;         const float kaB[8] = {nka2.x, nka2.y, nka2.z, nka2.w, nka3.x, nka3.y, nka3.z, nka3.w};
;         const float kdA[8] = {nkd0.x, nkd0.y, nkd0.z, nkd0.w, nkd1.x, nkd1.y, nkd1.z, nkd1.w};
;         const float kdB[8] = {nkd2.x, nkd2.y, nkd2.z, nkd2.w, nkd3.x, nkd3.y, nkd3.z, nkd3.w};
;         const float v = nv;
;         float c1 = nc.x, c2 = nc.y;
;         asm volatile("" : "+v"(c1), "+v"(c2));
;         if (s + 1 < RTC) RW_LD(s + 1);
;         u32x4 pa = {pack2(Sa[0], Sa[1]), pack2(Sa[2], Sa[3]), pack2(Sa[4], Sa[5]), pack2(Sa[6], Sa[7])};
;         u32x4 pb = {pack2(Sb[0], Sb[1]), pack2(Sb[2], Sb[3]), pack2(Sb[4], Sb[5]), pack2(Sb[6], Sb[7])};
;         f32x4 acc = {0.f, 0.f, 0.f, 0.f};
;         acc = __builtin_amdgcn_mfma_f32_16x16x32_bf16(A0, __builtin_bit_cast(bf16x8, pa), acc, 0, 0, 0);
;         acc = __builtin_amdgcn_mfma_f32_16x16x32_bf16(A1, __builtin_bit_cast(bf16x8, pb), acc, 0, 0, 0);
;         float tA[8], tB[8];
; #pragma unroll
;         for (int c = 0; c < 8; c++) { tA[c] = Sa[c] * wA[c] + v * kdA[c]; tB[c] = Sb[c] * wB[c] + v * kdB[c]; }
;         const float sa = -acc[0];
;         const float yq = acc[1];
; #pragma unroll
;         for (int c = 0; c < 8; c++) { Sa[c] = tA[c] + sa * kaA[c]; Sb[c] = tB[c] + sa * kaB[c]; }
;         const float y = yq + sa * c1 + v * c2;
;         if (quad == 0) by[s * 64 + row] = y;
;       }
	v_mfma_f32_16x16x32_bf16 v[32:35], v[70:73], v[24:27], 0
	v_cvt_pk_bf16_f32 v30, v20, v21
	v_cvt_pk_bf16_f32 v31, v22, v23
	s_waitcnt lgkmcnt(3)
	v_fmac_f32_dpp v8, v95, v96 row_newbcast:0 row_mask:0xf bank_mask:0xf
	v_fmac_f32_dpp v9, v95, v96 row_newbcast:1 row_mask:0xf bank_mask:0xf
	v_mfma_f32_16x16x32_bf16 v[32:35], v[74:77], v[28:31], v[32:35]
	v_fmac_f32_dpp v10, v95, v96 row_newbcast:2 row_mask:0xf bank_mask:0xf
	v_fmac_f32_dpp v11, v95, v96 row_newbcast:3 row_mask:0xf bank_mask:0xf
	ds_read_b128 v[40:43], v104 offset:4096
	v_fmac_f32_dpp v12, v95, v96 row_newbcast:4 row_mask:0xf bank_mask:0xf
	v_fmac_f32_dpp v13, v95, v96 row_newbcast:5 row_mask:0xf bank_mask:0xf
	ds_read_b128 v[44:47], v104 offset:4112
	v_fmac_f32_dpp v14, v95, v96 row_newbcast:6 row_mask:0xf bank_mask:0xf
	v_fmac_f32_dpp v15, v95, v96 row_newbcast:7 row_mask:0xf bank_mask:0xf
	ds_read_b32 v65, v105 offset:20480
	v_fmac_f32_dpp v16, v95, v96 row_newbcast:8 row_mask:0xf bank_mask:0xf
	v_fmac_f32_dpp v17, v95, v96 row_newbcast:9 row_mask:0xf bank_mask:0xf
	ds_read_b32 v66, v107 offset:4096
	v_fmac_f32_dpp v18, v95, v96 row_newbcast:10 row_mask:0xf bank_mask:0xf
	v_fmac_f32_dpp v19, v95, v96 row_newbcast:11 row_mask:0xf bank_mask:0xf
	ds_read_b32 v48, v105 offset:12288
	v_fmac_f32_dpp v20, v95, v96 row_newbcast:12 row_mask:0xf bank_mask:0xf
	v_fmac_f32_dpp v21, v95, v96 row_newbcast:13 row_mask:0xf bank_mask:0xf
	ds_read_b64 v[68:69], v108 offset:49280
	v_fmac_f32_dpp v22, v95, v96 row_newbcast:14 row_mask:0xf bank_mask:0xf
	v_fmac_f32_dpp v23, v95, v96 row_newbcast:15 row_mask:0xf bank_mask:0xf
	s_waitcnt lgkmcnt(8)
	s_waitcnt lgkmcnt(7)
	v_xor_b32_e32 v110, 0x80000000, v32
	v_fma_f32 v109, -v32, v98, v33
	v_fma_f32 v109, v96, v99, v109
	v_fmac_f32_dpp v8, v78, v110 row_newbcast:0 row_mask:0xf bank_mask:0xf
	v_fmac_f32_dpp v9, v78, v110 row_newbcast:1 row_mask:0xf bank_mask:0xf
	v_fmac_f32_dpp v10, v78, v110 row_newbcast:2 row_mask:0xf bank_mask:0xf
	v_fmac_f32_dpp v11, v78, v110 row_newbcast:3 row_mask:0xf bank_mask:0xf
	v_fmac_f32_dpp v12, v78, v110 row_newbcast:4 row_mask:0xf bank_mask:0xf
	v_fmac_f32_dpp v13, v78, v110 row_newbcast:5 row_mask:0xf bank_mask:0xf
	v_fmac_f32_dpp v14, v78, v110 row_newbcast:6 row_mask:0xf bank_mask:0xf
	v_fmac_f32_dpp v15, v78, v110 row_newbcast:7 row_mask:0xf bank_mask:0xf
	v_fmac_f32_dpp v16, v78, v110 row_newbcast:8 row_mask:0xf bank_mask:0xf
	v_fmac_f32_dpp v17, v78, v110 row_newbcast:9 row_mask:0xf bank_mask:0xf
	v_fmac_f32_dpp v18, v78, v110 row_newbcast:10 row_mask:0xf bank_mask:0xf
	v_fmac_f32_dpp v19, v78, v110 row_newbcast:11 row_mask:0xf bank_mask:0xf
	v_fmac_f32_dpp v20, v78, v110 row_newbcast:12 row_mask:0xf bank_mask:0xf
	v_fmac_f32_dpp v21, v78, v110 row_newbcast:13 row_mask:0xf bank_mask:0xf
	v_fmac_f32_dpp v22, v78, v110 row_newbcast:14 row_mask:0xf bank_mask:0xf
	v_fmac_f32_dpp v23, v78, v110 row_newbcast:15 row_mask:0xf bank_mask:0xf
	v_mul_f32_dpp v8, v94, v8 row_newbcast:0 row_mask:0xf bank_mask:0xf
	v_mul_f32_dpp v9, v94, v9 row_newbcast:1 row_mask:0xf bank_mask:0xf
	v_mul_f32_dpp v10, v94, v10 row_newbcast:2 row_mask:0xf bank_mask:0xf
	v_mul_f32_dpp v11, v94, v11 row_newbcast:3 row_mask:0xf bank_mask:0xf
	v_mul_f32_dpp v12, v94, v12 row_newbcast:4 row_mask:0xf bank_mask:0xf
	v_mul_f32_dpp v13, v94, v13 row_newbcast:5 row_mask:0xf bank_mask:0xf
	v_mul_f32_dpp v14, v94, v14 row_newbcast:6 row_mask:0xf bank_mask:0xf
	v_mul_f32_dpp v15, v94, v15 row_newbcast:7 row_mask:0xf bank_mask:0xf
	v_mul_f32_dpp v16, v94, v16 row_newbcast:8 row_mask:0xf bank_mask:0xf
	v_mul_f32_dpp v17, v94, v17 row_newbcast:9 row_mask:0xf bank_mask:0xf
	v_mul_f32_dpp v18, v94, v18 row_newbcast:10 row_mask:0xf bank_mask:0xf
	v_mul_f32_dpp v19, v94, v19 row_newbcast:11 row_mask:0xf bank_mask:0xf
	v_mul_f32_dpp v20, v94, v20 row_newbcast:12 row_mask:0xf bank_mask:0xf
	v_mul_f32_dpp v21, v94, v21 row_newbcast:13 row_mask:0xf bank_mask:0xf
	v_mul_f32_dpp v22, v94, v22 row_newbcast:14 row_mask:0xf bank_mask:0xf
	v_mul_f32_dpp v23, v94, v23 row_newbcast:15 row_mask:0xf bank_mask:0xf
	ds_write_b32 v107, v109 offset:12032
	v_cvt_pk_bf16_f32 v24, v8, v9
	v_cvt_pk_bf16_f32 v25, v10, v11
	v_cvt_pk_bf16_f32 v26, v12, v13
	v_cvt_pk_bf16_f32 v27, v14, v15
	v_cvt_pk_bf16_f32 v28, v16, v17
	v_cvt_pk_bf16_f32 v29, v18, v19
	s_waitcnt lgkmcnt(6)
	v_mfma_f32_16x16x32_bf16 v[32:35], v[40:43], v[24:27], 0
	v_cvt_pk_bf16_f32 v30, v20, v21
	v_cvt_pk_bf16_f32 v31, v22, v23
	s_waitcnt lgkmcnt(3)
	v_fmac_f32_dpp v8, v65, v66 row_newbcast:0 row_mask:0xf bank_mask:0xf
	v_fmac_f32_dpp v9, v65, v66 row_newbcast:1 row_mask:0xf bank_mask:0xf
	v_mfma_f32_16x16x32_bf16 v[32:35], v[44:47], v[28:31], v[32:35]
	v_fmac_f32_dpp v10, v65, v66 row_newbcast:2 row_mask:0xf bank_mask:0xf
	v_fmac_f32_dpp v11, v65, v66 row_newbcast:3 row_mask:0xf bank_mask:0xf
	ds_read_b128 v[70:73], v104 offset:4352
	v_fmac_f32_dpp v12, v65, v66 row_newbcast:4 row_mask:0xf bank_mask:0xf
	v_fmac_f32_dpp v13, v65, v66 row_newbcast:5 row_mask:0xf bank_mask:0xf
	ds_read_b128 v[74:77], v104 offset:4368
	v_fmac_f32_dpp v14, v65, v66 row_newbcast:6 row_mask:0xf bank_mask:0xf
	v_fmac_f32_dpp v15, v65, v66 row_newbcast:7 row_mask:0xf bank_mask:0xf
	ds_read_b32 v95, v105 offset:20736
	v_fmac_f32_dpp v16, v65, v66 row_newbcast:8 row_mask:0xf bank_mask:0xf
	v_fmac_f32_dpp v17, v65, v66 row_newbcast:9 row_mask:0xf bank_mask:0xf
	ds_read_b32 v96, v107 offset:4352
	v_fmac_f32_dpp v18, v65, v66 row_newbcast:10 row_mask:0xf bank_mask:0xf
	v_fmac_f32_dpp v19, v65, v66 row_newbcast:11 row_mask:0xf bank_mask:0xf
	ds_read_b32 v78, v105 offset:12544
	v_fmac_f32_dpp v20, v65, v66 row_newbcast:12 row_mask:0xf bank_mask:0xf
	v_fmac_f32_dpp v21, v65, v66 row_newbcast:13 row_mask:0xf bank_mask:0xf
	ds_read_b64 v[98:99], v108 offset:49288
	v_fmac_f32_dpp v22, v65, v66 row_newbcast:14 row_mask:0xf bank_mask:0xf
	v_fmac_f32_dpp v23, v65, v66 row_newbcast:15 row_mask:0xf bank_mask:0xf
	s_waitcnt lgkmcnt(8)
; __device__ __forceinline__ void phase_rwkv_scan(const Params& p, int l, const int tidx) {
;     ...
;       for (int s = 0; s < RTC; s++) {
;         const bf16x8 A0 = nA0, A1 = nA1;
;         const float wA[8] = {nw0.x, nw0.y, nw0.z, nw0.w, nw1.x, nw1.y, nw1.z, nw1.w};
;         const float wB[8] = {nw2.x, nw2.y, nw2.z, nw2.w, nw3.x, nw3.y, nw3.z, nw3.w};
;         const float kaA[8] = {nka0.x, nka0.y, nka0.z, nka0.w, nka1.x, nka1.y, nka1.z, nka1.w};
;         const float kaB[8] = {nka2.x, nka2.y, nka2.z, nka2.w, nka3.x, nka3.y, nka3.z, nka3.w};
;         const float kdA[8] = {nkd0.x, nkd0.y, nkd0.z, nkd0.w, nkd1.x, nkd1.y, nkd1.z, nkd1.w};
;         const float kdB[8] = {nkd2.x, nkd2.y, nkd2.z, nkd2.w, nkd3.x, nkd3.y, nkd3.z, nkd3.w};
;         const float v = nv;
;         float c1 = nc.x, c2 = nc.y;
;         asm volatile("" : "+v"(c1), "+v"(c2));
;         if (s + 1 < RTC) RW_LD(s + 1);
;         u32x4 pa = {pack2(Sa[0], Sa[1]), pack2(Sa[2], Sa[3]), pack2(Sa[4], Sa[5]), pack2(Sa[6], Sa[7])};
;         u32x4 pb = {pack2(Sb[0], Sb[1]), pack2(Sb[2], Sb[3]), pack2(Sb[4], Sb[5]), pack2(Sb[6], Sb[7])};
;         f32x4 acc = {0.f, 0.f, 0.f, 0.f};
;         acc = __builtin_amdgcn_mfma_f32_16x16x32_bf16(A0, __builtin_bit_cast(bf16x8, pa), acc, 0, 0, 0);
;         acc = __builtin_amdgcn_mfma_f32_16x16x32_bf16(A1, __builtin_bit_cast(bf16x8, pb), acc, 0, 0, 0);
;         float tA[8], tB[8];
; #pragma unroll
;         for (int c = 0; c < 8; c++) { tA[c] = Sa[c] * wA[c] + v * kdA[c]; tB[c] = Sb[c] * wB[c] + v * kdB[c]; }
;         const float sa = -acc[0];
;         const float yq = acc[1];
; #pragma unroll
;         for (int c = 0; c < 8; c++) { Sa[c] = tA[c] + sa * kaA[c]; Sb[c] = tB[c] + sa * kaB[c]; }
;         const float y = yq + sa * c1 + v * c2;
;         if (quad == 0) by[s * 64 + row] = y;
;       }
	s_waitcnt lgkmcnt(7)
	v_xor_b32_e32 v110, 0x80000000, v32
	v_fma_f32 v109, -v32, v68, v33
	v_fma_f32 v109, v66, v69, v109
	v_fmac_f32_dpp v8, v48, v110 row_newbcast:0 row_mask:0xf bank_mask:0xf
	v_fmac_f32_dpp v9, v48, v110 row_newbcast:1 row_mask:0xf bank_mask:0xf
	v_fmac_f32_dpp v10, v48, v110 row_newbcast:2 row_mask:0xf bank_mask:0xf
	v_fmac_f32_dpp v11, v48, v110 row_newbcast:3 row_mask:0xf bank_mask:0xf
	v_fmac_f32_dpp v12, v48, v110 row_newbcast:4 row_mask:0xf bank_mask:0xf
	v_fmac_f32_dpp v13, v48, v110 row_newbcast:5 row_mask:0xf bank_mask:0xf
	v_fmac_f32_dpp v14, v48, v110 row_newbcast:6 row_mask:0xf bank_mask:0xf
	v_fmac_f32_dpp v15, v48, v110 row_newbcast:7 row_mask:0xf bank_mask:0xf
	v_fmac_f32_dpp v16, v48, v110 row_newbcast:8 row_mask:0xf bank_mask:0xf
	v_fmac_f32_dpp v17, v48, v110 row_newbcast:9 row_mask:0xf bank_mask:0xf
	v_fmac_f32_dpp v18, v48, v110 row_newbcast:10 row_mask:0xf bank_mask:0xf
	v_fmac_f32_dpp v19, v48, v110 row_newbcast:11 row_mask:0xf bank_mask:0xf
	v_fmac_f32_dpp v20, v48, v110 row_newbcast:12 row_mask:0xf bank_mask:0xf
	v_fmac_f32_dpp v21, v48, v110 row_newbcast:13 row_mask:0xf bank_mask:0xf
	v_fmac_f32_dpp v22, v48, v110 row_newbcast:14 row_mask:0xf bank_mask:0xf
	v_fmac_f32_dpp v23, v48, v110 row_newbcast:15 row_mask:0xf bank_mask:0xf
	ds_write_b32 v107, v109 offset:12288
	v_cvt_pk_bf16_f32 v24, v8, v9
	v_cvt_pk_bf16_f32 v25, v10, v11
	v_cvt_pk_bf16_f32 v26, v12, v13
	v_cvt_pk_bf16_f32 v27, v14, v15
	v_cvt_pk_bf16_f32 v28, v16, v17
	v_cvt_pk_bf16_f32 v29, v18, v19
	s_waitcnt lgkmcnt(6)
	v_mfma_f32_16x16x32_bf16 v[32:35], v[70:73], v[24:27], 0
	v_cvt_pk_bf16_f32 v30, v20, v21
	v_cvt_pk_bf16_f32 v31, v22, v23
	s_waitcnt lgkmcnt(3)
	v_fmac_f32_dpp v8, v95, v96 row_newbcast:0 row_mask:0xf bank_mask:0xf
	v_fmac_f32_dpp v9, v95, v96 row_newbcast:1 row_mask:0xf bank_mask:0xf
	v_mfma_f32_16x16x32_bf16 v[32:35], v[74:77], v[28:31], v[32:35]
	v_fmac_f32_dpp v10, v95, v96 row_newbcast:2 row_mask:0xf bank_mask:0xf
	v_fmac_f32_dpp v11, v95, v96 row_newbcast:3 row_mask:0xf bank_mask:0xf
	ds_read_b128 v[40:43], v104 offset:4608
	v_fmac_f32_dpp v12, v95, v96 row_newbcast:4 row_mask:0xf bank_mask:0xf
	v_fmac_f32_dpp v13, v95, v96 row_newbcast:5 row_mask:0xf bank_mask:0xf
	ds_read_b128 v[44:47], v104 offset:4624
	v_fmac_f32_dpp v14, v95, v96 row_newbcast:6 row_mask:0xf bank_mask:0xf
	v_fmac_f32_dpp v15, v95, v96 row_newbcast:7 row_mask:0xf bank_mask:0xf
	ds_read_b32 v65, v105 offset:20992
	v_fmac_f32_dpp v16, v95, v96 row_newbcast:8 row_mask:0xf bank_mask:0xf
	v_fmac_f32_dpp v17, v95, v96 row_newbcast:9 row_mask:0xf bank_mask:0xf
	ds_read_b32 v66, v107 offset:4608
	v_fmac_f32_dpp v18, v95, v96 row_newbcast:10 row_mask:0xf bank_mask:0xf
	v_fmac_f32_dpp v19, v95, v96 row_newbcast:11 row_mask:0xf bank_mask:0xf
	ds_read_b32 v48, v105 offset:12800
	v_fmac_f32_dpp v20, v95, v96 row_newbcast:12 row_mask:0xf bank_mask:0xf
	v_fmac_f32_dpp v21, v95, v96 row_newbcast:13 row_mask:0xf bank_mask:0xf
	ds_read_b64 v[68:69], v108 offset:49296
	v_fmac_f32_dpp v22, v95, v96 row_newbcast:14 row_mask:0xf bank_mask:0xf
	v_fmac_f32_dpp v23, v95, v96 row_newbcast:15 row_mask:0xf bank_mask:0xf
	s_waitcnt lgkmcnt(8)
	s_waitcnt lgkmcnt(7)
	v_xor_b32_e32 v110, 0x80000000, v32
	v_fma_f32 v109, -v32, v98, v33
	v_fma_f32 v109, v96, v99, v109
	v_fmac_f32_dpp v8, v78, v110 row_newbcast:0 row_mask:0xf bank_mask:0xf
	v_fmac_f32_dpp v9, v78, v110 row_newbcast:1 row_mask:0xf bank_mask:0xf
	v_fmac_f32_dpp v10, v78, v110 row_newbcast:2 row_mask:0xf bank_mask:0xf
	v_fmac_f32_dpp v11, v78, v110 row_newbcast:3 row_mask:0xf bank_mask:0xf
	v_fmac_f32_dpp v12, v78, v110 row_newbcast:4 row_mask:0xf bank_mask:0xf
	v_fmac_f32_dpp v13, v78, v110 row_newbcast:5 row_mask:0xf bank_mask:0xf
	v_fmac_f32_dpp v14, v78, v110 row_newbcast:6 row_mask:0xf bank_mask:0xf
	v_fmac_f32_dpp v15, v78, v110 row_newbcast:7 row_mask:0xf bank_mask:0xf
	v_fmac_f32_dpp v16, v78, v110 row_newbcast:8 row_mask:0xf bank_mask:0xf
	v_fmac_f32_dpp v17, v78, v110 row_newbcast:9 row_mask:0xf bank_mask:0xf
	v_fmac_f32_dpp v18, v78, v110 row_newbcast:10 row_mask:0xf bank_mask:0xf
	v_fmac_f32_dpp v19, v78, v110 row_newbcast:11 row_mask:0xf bank_mask:0xf
	v_fmac_f32_dpp v20, v78, v110 row_newbcast:12 row_mask:0xf bank_mask:0xf
	v_fmac_f32_dpp v21, v78, v110 row_newbcast:13 row_mask:0xf bank_mask:0xf
	v_fmac_f32_dpp v22, v78, v110 row_newbcast:14 row_mask:0xf bank_mask:0xf
	v_fmac_f32_dpp v23, v78, v110 row_newbcast:15 row_mask:0xf bank_mask:0xf
	ds_write_b32 v107, v109 offset:12544
	v_cvt_pk_bf16_f32 v24, v8, v9
	v_cvt_pk_bf16_f32 v25, v10, v11
	v_cvt_pk_bf16_f32 v26, v12, v13
	v_cvt_pk_bf16_f32 v27, v14, v15
	v_cvt_pk_bf16_f32 v28, v16, v17
	v_cvt_pk_bf16_f32 v29, v18, v19
	s_waitcnt lgkmcnt(6)
	v_mfma_f32_16x16x32_bf16 v[32:35], v[40:43], v[24:27], 0
	v_cvt_pk_bf16_f32 v30, v20, v21
	v_cvt_pk_bf16_f32 v31, v22, v23
	s_waitcnt lgkmcnt(3)
	v_fmac_f32_dpp v8, v65, v66 row_newbcast:0 row_mask:0xf bank_mask:0xf
	v_fmac_f32_dpp v9, v65, v66 row_newbcast:1 row_mask:0xf bank_mask:0xf
	v_mfma_f32_16x16x32_bf16 v[32:35], v[44:47], v[28:31], v[32:35]
	v_fmac_f32_dpp v10, v65, v66 row_newbcast:2 row_mask:0xf bank_mask:0xf
	v_fmac_f32_dpp v11, v65, v66 row_newbcast:3 row_mask:0xf bank_mask:0xf
	ds_read_b128 v[70:73], v104 offset:4864
	v_fmac_f32_dpp v12, v65, v66 row_newbcast:4 row_mask:0xf bank_mask:0xf
	v_fmac_f32_dpp v13, v65, v66 row_newbcast:5 row_mask:0xf bank_mask:0xf
	ds_read_b128 v[74:77], v104 offset:4880
	v_fmac_f32_dpp v14, v65, v66 row_newbcast:6 row_mask:0xf bank_mask:0xf
	v_fmac_f32_dpp v15, v65, v66 row_newbcast:7 row_mask:0xf bank_mask:0xf
	ds_read_b32 v95, v105 offset:21248
	v_fmac_f32_dpp v16, v65, v66 row_newbcast:8 row_mask:0xf bank_mask:0xf
	v_fmac_f32_dpp v17, v65, v66 row_newbcast:9 row_mask:0xf bank_mask:0xf
	ds_read_b32 v96, v107 offset:4864
	v_fmac_f32_dpp v18, v65, v66 row_newbcast:10 row_mask:0xf bank_mask:0xf
	v_fmac_f32_dpp v19, v65, v66 row_newbcast:11 row_mask:0xf bank_mask:0xf
	ds_read_b32 v78, v105 offset:13056
	v_fmac_f32_dpp v20, v65, v66 row_newbcast:12 row_mask:0xf bank_mask:0xf
	v_fmac_f32_dpp v21, v65, v66 row_newbcast:13 row_mask:0xf bank_mask:0xf
	ds_read_b64 v[98:99], v108 offset:49304
	v_fmac_f32_dpp v22, v65, v66 row_newbcast:14 row_mask:0xf bank_mask:0xf
	v_fmac_f32_dpp v23, v65, v66 row_newbcast:15 row_mask:0xf bank_mask:0xf
	s_waitcnt lgkmcnt(8)
; __device__ __forceinline__ void phase_rwkv_scan(const Params& p, int l, const int tidx) {
;     ...
;       for (int s = 0; s < RTC; s++) {
;         const bf16x8 A0 = nA0, A1 = nA1;
;         const float wA[8] = {nw0.x, nw0.y, nw0.z, nw0.w, nw1.x, nw1.y, nw1.z, nw1.w};
;         const float wB[8] = {nw2.x, nw2.y, nw2.z, nw2.w, nw3.x, nw3.y, nw3.z, nw3.w};
;         const float kaA[8] = {nka0.x, nka0.y, nka0.z, nka0.w, nka1.x, nka1.y, nka1.z, nka1.w};
;         const float kaB[8] = {nka2.x, nka2.y, nka2.z, nka2.w, nka3.x, nka3.y, nka3.z, nka3.w};
;         const float kdA[8] = {nkd0.x, nkd0.y, nkd0.z, nkd0.w, nkd1.x, nkd1.y, nkd1.z, nkd1.w};
;         const float kdB[8] = {nkd2.x, nkd2.y, nkd2.z, nkd2.w, nkd3.x, nkd3.y, nkd3.z, nkd3.w};
;         const float v = nv;
;         float c1 = nc.x, c2 = nc.y;
;         asm volatile("" : "+v"(c1), "+v"(c2));
;         if (s + 1 < RTC) RW_LD(s + 1);
;         u32x4 pa = {pack2(Sa[0], Sa[1]), pack2(Sa[2], Sa[3]), pack2(Sa[4], Sa[5]), pack2(Sa[6], Sa[7])};
;         u32x4 pb = {pack2(Sb[0], Sb[1]), pack2(Sb[2], Sb[3]), pack2(Sb[4], Sb[5]), pack2(Sb[6], Sb[7])};
;         f32x4 acc = {0.f, 0.f, 0.f, 0.f};
;         acc = __builtin_amdgcn_mfma_f32_16x16x32_bf16(A0, __builtin_bit_cast(bf16x8, pa), acc, 0, 0, 0);
;         acc = __builtin_amdgcn_mfma_f32_16x16x32_bf16(A1, __builtin_bit_cast(bf16x8, pb), acc, 0, 0, 0);
;         float tA[8], tB[8];
; #pragma unroll
;         for (int c = 0; c < 8; c++) { tA[c] = Sa[c] * wA[c] + v * kdA[c]; tB[c] = Sb[c] * wB[c] + v * kdB[c]; }
;         const float sa = -acc[0];
;         const float yq = acc[1];
; #pragma unroll
;         for (int c = 0; c < 8; c++) { Sa[c] = tA[c] + sa * kaA[c]; Sb[c] = tB[c] + sa * kaB[c]; }
;         const float y = yq + sa * c1 + v * c2;
;         if (quad == 0) by[s * 64 + row] = y;
;       }
	s_waitcnt lgkmcnt(7)
	v_xor_b32_e32 v110, 0x80000000, v32
	v_fma_f32 v109, -v32, v68, v33
	v_fma_f32 v109, v66, v69, v109
	v_fmac_f32_dpp v8, v48, v110 row_newbcast:0 row_mask:0xf bank_mask:0xf
	v_fmac_f32_dpp v9, v48, v110 row_newbcast:1 row_mask:0xf bank_mask:0xf
	v_fmac_f32_dpp v10, v48, v110 row_newbcast:2 row_mask:0xf bank_mask:0xf
	v_fmac_f32_dpp v11, v48, v110 row_newbcast:3 row_mask:0xf bank_mask:0xf
	v_fmac_f32_dpp v12, v48, v110 row_newbcast:4 row_mask:0xf bank_mask:0xf
	v_fmac_f32_dpp v13, v48, v110 row_newbcast:5 row_mask:0xf bank_mask:0xf
	v_fmac_f32_dpp v14, v48, v110 row_newbcast:6 row_mask:0xf bank_mask:0xf
	v_fmac_f32_dpp v15, v48, v110 row_newbcast:7 row_mask:0xf bank_mask:0xf
	v_fmac_f32_dpp v16, v48, v110 row_newbcast:8 row_mask:0xf bank_mask:0xf
	v_fmac_f32_dpp v17, v48, v110 row_newbcast:9 row_mask:0xf bank_mask:0xf
	v_fmac_f32_dpp v18, v48, v110 row_newbcast:10 row_mask:0xf bank_mask:0xf
	v_fmac_f32_dpp v19, v48, v110 row_newbcast:11 row_mask:0xf bank_mask:0xf
	v_fmac_f32_dpp v20, v48, v110 row_newbcast:12 row_mask:0xf bank_mask:0xf
	v_fmac_f32_dpp v21, v48, v110 row_newbcast:13 row_mask:0xf bank_mask:0xf
	v_fmac_f32_dpp v22, v48, v110 row_newbcast:14 row_mask:0xf bank_mask:0xf
	v_fmac_f32_dpp v23, v48, v110 row_newbcast:15 row_mask:0xf bank_mask:0xf
	ds_write_b32 v107, v109 offset:12800
	v_cvt_pk_bf16_f32 v24, v8, v9
	v_cvt_pk_bf16_f32 v25, v10, v11
	v_cvt_pk_bf16_f32 v26, v12, v13
	v_cvt_pk_bf16_f32 v27, v14, v15
	v_cvt_pk_bf16_f32 v28, v16, v17
	v_cvt_pk_bf16_f32 v29, v18, v19
	s_waitcnt lgkmcnt(6)
	v_mfma_f32_16x16x32_bf16 v[32:35], v[70:73], v[24:27], 0
	v_cvt_pk_bf16_f32 v30, v20, v21
	v_cvt_pk_bf16_f32 v31, v22, v23
	s_waitcnt lgkmcnt(3)
	v_fmac_f32_dpp v8, v95, v96 row_newbcast:0 row_mask:0xf bank_mask:0xf
	v_fmac_f32_dpp v9, v95, v96 row_newbcast:1 row_mask:0xf bank_mask:0xf
	v_mfma_f32_16x16x32_bf16 v[32:35], v[74:77], v[28:31], v[32:35]
	v_fmac_f32_dpp v10, v95, v96 row_newbcast:2 row_mask:0xf bank_mask:0xf
	v_fmac_f32_dpp v11, v95, v96 row_newbcast:3 row_mask:0xf bank_mask:0xf
	ds_read_b128 v[40:43], v104 offset:5120
	v_fmac_f32_dpp v12, v95, v96 row_newbcast:4 row_mask:0xf bank_mask:0xf
	v_fmac_f32_dpp v13, v95, v96 row_newbcast:5 row_mask:0xf bank_mask:0xf
	ds_read_b128 v[44:47], v104 offset:5136
	v_fmac_f32_dpp v14, v95, v96 row_newbcast:6 row_mask:0xf bank_mask:0xf
	v_fmac_f32_dpp v15, v95, v96 row_newbcast:7 row_mask:0xf bank_mask:0xf
	ds_read_b32 v65, v105 offset:21504
	v_fmac_f32_dpp v16, v95, v96 row_newbcast:8 row_mask:0xf bank_mask:0xf
	v_fmac_f32_dpp v17, v95, v96 row_newbcast:9 row_mask:0xf bank_mask:0xf
	ds_read_b32 v66, v107 offset:5120
	v_fmac_f32_dpp v18, v95, v96 row_newbcast:10 row_mask:0xf bank_mask:0xf
	v_fmac_f32_dpp v19, v95, v96 row_newbcast:11 row_mask:0xf bank_mask:0xf
	ds_read_b32 v48, v105 offset:13312
	v_fmac_f32_dpp v20, v95, v96 row_newbcast:12 row_mask:0xf bank_mask:0xf
	v_fmac_f32_dpp v21, v95, v96 row_newbcast:13 row_mask:0xf bank_mask:0xf
	ds_read_b64 v[68:69], v108 offset:49312
	v_fmac_f32_dpp v22, v95, v96 row_newbcast:14 row_mask:0xf bank_mask:0xf
	v_fmac_f32_dpp v23, v95, v96 row_newbcast:15 row_mask:0xf bank_mask:0xf
	s_waitcnt lgkmcnt(8)
	s_waitcnt lgkmcnt(7)
	v_xor_b32_e32 v110, 0x80000000, v32
	v_fma_f32 v109, -v32, v98, v33
	v_fma_f32 v109, v96, v99, v109
	v_fmac_f32_dpp v8, v78, v110 row_newbcast:0 row_mask:0xf bank_mask:0xf
	v_fmac_f32_dpp v9, v78, v110 row_newbcast:1 row_mask:0xf bank_mask:0xf
	v_fmac_f32_dpp v10, v78, v110 row_newbcast:2 row_mask:0xf bank_mask:0xf
	v_fmac_f32_dpp v11, v78, v110 row_newbcast:3 row_mask:0xf bank_mask:0xf
	v_fmac_f32_dpp v12, v78, v110 row_newbcast:4 row_mask:0xf bank_mask:0xf
	v_fmac_f32_dpp v13, v78, v110 row_newbcast:5 row_mask:0xf bank_mask:0xf
	v_fmac_f32_dpp v14, v78, v110 row_newbcast:6 row_mask:0xf bank_mask:0xf
	v_fmac_f32_dpp v15, v78, v110 row_newbcast:7 row_mask:0xf bank_mask:0xf
	v_fmac_f32_dpp v16, v78, v110 row_newbcast:8 row_mask:0xf bank_mask:0xf
	v_fmac_f32_dpp v17, v78, v110 row_newbcast:9 row_mask:0xf bank_mask:0xf
	v_fmac_f32_dpp v18, v78, v110 row_newbcast:10 row_mask:0xf bank_mask:0xf
	v_fmac_f32_dpp v19, v78, v110 row_newbcast:11 row_mask:0xf bank_mask:0xf
	v_fmac_f32_dpp v20, v78, v110 row_newbcast:12 row_mask:0xf bank_mask:0xf
	v_fmac_f32_dpp v21, v78, v110 row_newbcast:13 row_mask:0xf bank_mask:0xf
	v_fmac_f32_dpp v22, v78, v110 row_newbcast:14 row_mask:0xf bank_mask:0xf
	v_fmac_f32_dpp v23, v78, v110 row_newbcast:15 row_mask:0xf bank_mask:0xf
	ds_write_b32 v107, v109 offset:13056
	v_cvt_pk_bf16_f32 v24, v8, v9
	v_cvt_pk_bf16_f32 v25, v10, v11
	v_cvt_pk_bf16_f32 v26, v12, v13
	v_cvt_pk_bf16_f32 v27, v14, v15
	v_cvt_pk_bf16_f32 v28, v16, v17
	v_cvt_pk_bf16_f32 v29, v18, v19
	s_waitcnt lgkmcnt(6)
	v_mfma_f32_16x16x32_bf16 v[32:35], v[40:43], v[24:27], 0
	v_cvt_pk_bf16_f32 v30, v20, v21
	v_cvt_pk_bf16_f32 v31, v22, v23
	s_waitcnt lgkmcnt(3)
	v_fmac_f32_dpp v8, v65, v66 row_newbcast:0 row_mask:0xf bank_mask:0xf
	v_fmac_f32_dpp v9, v65, v66 row_newbcast:1 row_mask:0xf bank_mask:0xf
	v_mfma_f32_16x16x32_bf16 v[32:35], v[44:47], v[28:31], v[32:35]
	v_fmac_f32_dpp v10, v65, v66 row_newbcast:2 row_mask:0xf bank_mask:0xf
	v_fmac_f32_dpp v11, v65, v66 row_newbcast:3 row_mask:0xf bank_mask:0xf
	ds_read_b128 v[70:73], v104 offset:5376
	v_fmac_f32_dpp v12, v65, v66 row_newbcast:4 row_mask:0xf bank_mask:0xf
	v_fmac_f32_dpp v13, v65, v66 row_newbcast:5 row_mask:0xf bank_mask:0xf
	ds_read_b128 v[74:77], v104 offset:5392
	v_fmac_f32_dpp v14, v65, v66 row_newbcast:6 row_mask:0xf bank_mask:0xf
	v_fmac_f32_dpp v15, v65, v66 row_newbcast:7 row_mask:0xf bank_mask:0xf
	ds_read_b32 v95, v105 offset:21760
	v_fmac_f32_dpp v16, v65, v66 row_newbcast:8 row_mask:0xf bank_mask:0xf
	v_fmac_f32_dpp v17, v65, v66 row_newbcast:9 row_mask:0xf bank_mask:0xf
	ds_read_b32 v96, v107 offset:5376
	v_fmac_f32_dpp v18, v65, v66 row_newbcast:10 row_mask:0xf bank_mask:0xf
	v_fmac_f32_dpp v19, v65, v66 row_newbcast:11 row_mask:0xf bank_mask:0xf
	ds_read_b32 v78, v105 offset:13568
	v_fmac_f32_dpp v20, v65, v66 row_newbcast:12 row_mask:0xf bank_mask:0xf
	v_fmac_f32_dpp v21, v65, v66 row_newbcast:13 row_mask:0xf bank_mask:0xf
	ds_read_b64 v[98:99], v108 offset:49320
	v_fmac_f32_dpp v22, v65, v66 row_newbcast:14 row_mask:0xf bank_mask:0xf
	v_fmac_f32_dpp v23, v65, v66 row_newbcast:15 row_mask:0xf bank_mask:0xf
	s_waitcnt lgkmcnt(8)
; __device__ __forceinline__ void phase_rwkv_scan(const Params& p, int l, const int tidx) {
;     ...
;       for (int s = 0; s < RTC; s++) {
;         const bf16x8 A0 = nA0, A1 = nA1;
;         const float wA[8] = {nw0.x, nw0.y, nw0.z, nw0.w, nw1.x, nw1.y, nw1.z, nw1.w};
;         const float wB[8] = {nw2.x, nw2.y, nw2.z, nw2.w, nw3.x, nw3.y, nw3.z, nw3.w};
;         const float kaA[8] = {nka0.x, nka0.y, nka0.z, nka0.w, nka1.x, nka1.y, nka1.z, nka1.w};
;         const float kaB[8] = {nka2.x, nka2.y, nka2.z, nka2.w, nka3.x, nka3.y, nka3.z, nka3.w};
;         const float kdA[8] = {nkd0.x, nkd0.y, nkd0.z, nkd0.w, nkd1.x, nkd1.y, nkd1.z, nkd1.w};
;         const float kdB[8] = {nkd2.x, nkd2.y, nkd2.z, nkd2.w, nkd3.x, nkd3.y, nkd3.z, nkd3.w};
;         const float v = nv;
;         float c1 = nc.x, c2 = nc.y;
;         asm volatile("" : "+v"(c1), "+v"(c2));
;         if (s + 1 < RTC) RW_LD(s + 1);
;         u32x4 pa = {pack2(Sa[0], Sa[1]), pack2(Sa[2], Sa[3]), pack2(Sa[4], Sa[5]), pack2(Sa[6], Sa[7])};
;         u32x4 pb = {pack2(Sb[0], Sb[1]), pack2(Sb[2], Sb[3]), pack2(Sb[4], Sb[5]), pack2(Sb[6], Sb[7])};
;         f32x4 acc = {0.f, 0.f, 0.f, 0.f};
;         acc = __builtin_amdgcn_mfma_f32_16x16x32_bf16(A0, __builtin_bit_cast(bf16x8, pa), acc, 0, 0, 0);
;         acc = __builtin_amdgcn_mfma_f32_16x16x32_bf16(A1, __builtin_bit_cast(bf16x8, pb), acc, 0, 0, 0);
;         float tA[8], tB[8];
; #pragma unroll
;         for (int c = 0; c < 8; c++) { tA[c] = Sa[c] * wA[c] + v * kdA[c]; tB[c] = Sb[c] * wB[c] + v * kdB[c]; }
;         const float sa = -acc[0];
;         const float yq = acc[1];
; #pragma unroll
;         for (int c = 0; c < 8; c++) { Sa[c] = tA[c] + sa * kaA[c]; Sb[c] = tB[c] + sa * kaB[c]; }
;         const float y = yq + sa * c1 + v * c2;
;         if (quad == 0) by[s * 64 + row] = y;
;       }
	s_waitcnt lgkmcnt(7)
	v_xor_b32_e32 v110, 0x80000000, v32
	v_fma_f32 v109, -v32, v68, v33
	v_fma_f32 v109, v66, v69, v109
	v_fmac_f32_dpp v8, v48, v110 row_newbcast:0 row_mask:0xf bank_mask:0xf
	v_fmac_f32_dpp v9, v48, v110 row_newbcast:1 row_mask:0xf bank_mask:0xf
	v_fmac_f32_dpp v10, v48, v110 row_newbcast:2 row_mask:0xf bank_mask:0xf
	v_fmac_f32_dpp v11, v48, v110 row_newbcast:3 row_mask:0xf bank_mask:0xf
	v_fmac_f32_dpp v12, v48, v110 row_newbcast:4 row_mask:0xf bank_mask:0xf
	v_fmac_f32_dpp v13, v48, v110 row_newbcast:5 row_mask:0xf bank_mask:0xf
	v_fmac_f32_dpp v14, v48, v110 row_newbcast:6 row_mask:0xf bank_mask:0xf
	v_fmac_f32_dpp v15, v48, v110 row_newbcast:7 row_mask:0xf bank_mask:0xf
	v_fmac_f32_dpp v16, v48, v110 row_newbcast:8 row_mask:0xf bank_mask:0xf
	v_fmac_f32_dpp v17, v48, v110 row_newbcast:9 row_mask:0xf bank_mask:0xf
	v_fmac_f32_dpp v18, v48, v110 row_newbcast:10 row_mask:0xf bank_mask:0xf
	v_fmac_f32_dpp v19, v48, v110 row_newbcast:11 row_mask:0xf bank_mask:0xf
	v_fmac_f32_dpp v20, v48, v110 row_newbcast:12 row_mask:0xf bank_mask:0xf
	v_fmac_f32_dpp v21, v48, v110 row_newbcast:13 row_mask:0xf bank_mask:0xf
	v_fmac_f32_dpp v22, v48, v110 row_newbcast:14 row_mask:0xf bank_mask:0xf
	v_fmac_f32_dpp v23, v48, v110 row_newbcast:15 row_mask:0xf bank_mask:0xf
	ds_write_b32 v107, v109 offset:13312
	v_cvt_pk_bf16_f32 v24, v8, v9
	v_cvt_pk_bf16_f32 v25, v10, v11
	v_cvt_pk_bf16_f32 v26, v12, v13
	v_cvt_pk_bf16_f32 v27, v14, v15
	v_cvt_pk_bf16_f32 v28, v16, v17
	v_cvt_pk_bf16_f32 v29, v18, v19
	s_waitcnt lgkmcnt(6)
	v_mfma_f32_16x16x32_bf16 v[32:35], v[70:73], v[24:27], 0
	v_cvt_pk_bf16_f32 v30, v20, v21
	v_cvt_pk_bf16_f32 v31, v22, v23
	s_waitcnt lgkmcnt(3)
	v_fmac_f32_dpp v8, v95, v96 row_newbcast:0 row_mask:0xf bank_mask:0xf
	v_fmac_f32_dpp v9, v95, v96 row_newbcast:1 row_mask:0xf bank_mask:0xf
	v_mfma_f32_16x16x32_bf16 v[32:35], v[74:77], v[28:31], v[32:35]
	v_fmac_f32_dpp v10, v95, v96 row_newbcast:2 row_mask:0xf bank_mask:0xf
	v_fmac_f32_dpp v11, v95, v96 row_newbcast:3 row_mask:0xf bank_mask:0xf
	ds_read_b128 v[40:43], v104 offset:5632
	v_fmac_f32_dpp v12, v95, v96 row_newbcast:4 row_mask:0xf bank_mask:0xf
	v_fmac_f32_dpp v13, v95, v96 row_newbcast:5 row_mask:0xf bank_mask:0xf
	ds_read_b128 v[44:47], v104 offset:5648
	v_fmac_f32_dpp v14, v95, v96 row_newbcast:6 row_mask:0xf bank_mask:0xf
	v_fmac_f32_dpp v15, v95, v96 row_newbcast:7 row_mask:0xf bank_mask:0xf
	ds_read_b32 v65, v105 offset:22016
	v_fmac_f32_dpp v16, v95, v96 row_newbcast:8 row_mask:0xf bank_mask:0xf
	v_fmac_f32_dpp v17, v95, v96 row_newbcast:9 row_mask:0xf bank_mask:0xf
	ds_read_b32 v66, v107 offset:5632
	v_fmac_f32_dpp v18, v95, v96 row_newbcast:10 row_mask:0xf bank_mask:0xf
	v_fmac_f32_dpp v19, v95, v96 row_newbcast:11 row_mask:0xf bank_mask:0xf
	ds_read_b32 v48, v105 offset:13824
	v_fmac_f32_dpp v20, v95, v96 row_newbcast:12 row_mask:0xf bank_mask:0xf
	v_fmac_f32_dpp v21, v95, v96 row_newbcast:13 row_mask:0xf bank_mask:0xf
	ds_read_b64 v[68:69], v108 offset:49328
	v_fmac_f32_dpp v22, v95, v96 row_newbcast:14 row_mask:0xf bank_mask:0xf
	v_fmac_f32_dpp v23, v95, v96 row_newbcast:15 row_mask:0xf bank_mask:0xf
	s_waitcnt lgkmcnt(8)
	s_waitcnt lgkmcnt(7)
	v_xor_b32_e32 v110, 0x80000000, v32
	v_fma_f32 v109, -v32, v98, v33
	v_fma_f32 v109, v96, v99, v109
	v_fmac_f32_dpp v8, v78, v110 row_newbcast:0 row_mask:0xf bank_mask:0xf
	v_fmac_f32_dpp v9, v78, v110 row_newbcast:1 row_mask:0xf bank_mask:0xf
	v_fmac_f32_dpp v10, v78, v110 row_newbcast:2 row_mask:0xf bank_mask:0xf
	v_fmac_f32_dpp v11, v78, v110 row_newbcast:3 row_mask:0xf bank_mask:0xf
	v_fmac_f32_dpp v12, v78, v110 row_newbcast:4 row_mask:0xf bank_mask:0xf
	v_fmac_f32_dpp v13, v78, v110 row_newbcast:5 row_mask:0xf bank_mask:0xf
	v_fmac_f32_dpp v14, v78, v110 row_newbcast:6 row_mask:0xf bank_mask:0xf
	v_fmac_f32_dpp v15, v78, v110 row_newbcast:7 row_mask:0xf bank_mask:0xf
	v_fmac_f32_dpp v16, v78, v110 row_newbcast:8 row_mask:0xf bank_mask:0xf
	v_fmac_f32_dpp v17, v78, v110 row_newbcast:9 row_mask:0xf bank_mask:0xf
	v_fmac_f32_dpp v18, v78, v110 row_newbcast:10 row_mask:0xf bank_mask:0xf
	v_fmac_f32_dpp v19, v78, v110 row_newbcast:11 row_mask:0xf bank_mask:0xf
	v_fmac_f32_dpp v20, v78, v110 row_newbcast:12 row_mask:0xf bank_mask:0xf
	v_fmac_f32_dpp v21, v78, v110 row_newbcast:13 row_mask:0xf bank_mask:0xf
	v_fmac_f32_dpp v22, v78, v110 row_newbcast:14 row_mask:0xf bank_mask:0xf
	v_fmac_f32_dpp v23, v78, v110 row_newbcast:15 row_mask:0xf bank_mask:0xf
	ds_write_b32 v107, v109 offset:13568
	v_cvt_pk_bf16_f32 v24, v8, v9
	v_cvt_pk_bf16_f32 v25, v10, v11
	v_cvt_pk_bf16_f32 v26, v12, v13
	v_cvt_pk_bf16_f32 v27, v14, v15
	v_cvt_pk_bf16_f32 v28, v16, v17
	v_cvt_pk_bf16_f32 v29, v18, v19
	s_waitcnt lgkmcnt(6)
	v_mfma_f32_16x16x32_bf16 v[32:35], v[40:43], v[24:27], 0
	v_cvt_pk_bf16_f32 v30, v20, v21
	v_cvt_pk_bf16_f32 v31, v22, v23
	s_waitcnt lgkmcnt(3)
	v_fmac_f32_dpp v8, v65, v66 row_newbcast:0 row_mask:0xf bank_mask:0xf
	v_fmac_f32_dpp v9, v65, v66 row_newbcast:1 row_mask:0xf bank_mask:0xf
	v_mfma_f32_16x16x32_bf16 v[32:35], v[44:47], v[28:31], v[32:35]
	v_fmac_f32_dpp v10, v65, v66 row_newbcast:2 row_mask:0xf bank_mask:0xf
	v_fmac_f32_dpp v11, v65, v66 row_newbcast:3 row_mask:0xf bank_mask:0xf
	ds_read_b128 v[70:73], v104 offset:5888
	v_fmac_f32_dpp v12, v65, v66 row_newbcast:4 row_mask:0xf bank_mask:0xf
	v_fmac_f32_dpp v13, v65, v66 row_newbcast:5 row_mask:0xf bank_mask:0xf
	ds_read_b128 v[74:77], v104 offset:5904
	v_fmac_f32_dpp v14, v65, v66 row_newbcast:6 row_mask:0xf bank_mask:0xf
	v_fmac_f32_dpp v15, v65, v66 row_newbcast:7 row_mask:0xf bank_mask:0xf
	ds_read_b32 v94, v105 offset:5888
	v_fmac_f32_dpp v16, v65, v66 row_newbcast:8 row_mask:0xf bank_mask:0xf
	v_fmac_f32_dpp v17, v65, v66 row_newbcast:9 row_mask:0xf bank_mask:0xf
	ds_read_b32 v95, v105 offset:22272
	v_fmac_f32_dpp v18, v65, v66 row_newbcast:10 row_mask:0xf bank_mask:0xf
	v_fmac_f32_dpp v19, v65, v66 row_newbcast:11 row_mask:0xf bank_mask:0xf
	ds_read_b32 v96, v107 offset:5888
	v_fmac_f32_dpp v20, v65, v66 row_newbcast:12 row_mask:0xf bank_mask:0xf
	v_fmac_f32_dpp v21, v65, v66 row_newbcast:13 row_mask:0xf bank_mask:0xf
	ds_read_b32 v78, v105 offset:14080
	v_fmac_f32_dpp v22, v65, v66 row_newbcast:14 row_mask:0xf bank_mask:0xf
	v_fmac_f32_dpp v23, v65, v66 row_newbcast:15 row_mask:0xf bank_mask:0xf
	ds_read_b64 v[98:99], v108 offset:49336
	s_waitcnt lgkmcnt(9)
; __device__ __forceinline__ void phase_rwkv_scan(const Params& p, int l, const int tidx) {
;     ...
;       for (int s = 0; s < RTC; s++) {
;         const bf16x8 A0 = nA0, A1 = nA1;
;         const float wA[8] = {nw0.x, nw0.y, nw0.z, nw0.w, nw1.x, nw1.y, nw1.z, nw1.w};
;         const float wB[8] = {nw2.x, nw2.y, nw2.z, nw2.w, nw3.x, nw3.y, nw3.z, nw3.w};
;         const float kaA[8] = {nka0.x, nka0.y, nka0.z, nka0.w, nka1.x, nka1.y, nka1.z, nka1.w};
;         const float kaB[8] = {nka2.x, nka2.y, nka2.z, nka2.w, nka3.x, nka3.y, nka3.z, nka3.w};
;         const float kdA[8] = {nkd0.x, nkd0.y, nkd0.z, nkd0.w, nkd1.x, nkd1.y, nkd1.z, nkd1.w};
;         const float kdB[8] = {nkd2.x, nkd2.y, nkd2.z, nkd2.w, nkd3.x, nkd3.y, nkd3.z, nkd3.w};
;         const float v = nv;
;         float c1 = nc.x, c2 = nc.y;
;         asm volatile("" : "+v"(c1), "+v"(c2));
;         if (s + 1 < RTC) RW_LD(s + 1);
;         u32x4 pa = {pack2(Sa[0], Sa[1]), pack2(Sa[2], Sa[3]), pack2(Sa[4], Sa[5]), pack2(Sa[6], Sa[7])};
;         u32x4 pb = {pack2(Sb[0], Sb[1]), pack2(Sb[2], Sb[3]), pack2(Sb[4], Sb[5]), pack2(Sb[6], Sb[7])};
;         f32x4 acc = {0.f, 0.f, 0.f, 0.f};
;         acc = __builtin_amdgcn_mfma_f32_16x16x32_bf16(A0, __builtin_bit_cast(bf16x8, pa), acc, 0, 0, 0);
;         acc = __builtin_amdgcn_mfma_f32_16x16x32_bf16(A1, __builtin_bit_cast(bf16x8, pb), acc, 0, 0, 0);
;         float tA[8], tB[8];
; #pragma unroll
;         for (int c = 0; c < 8; c++) { tA[c] = Sa[c] * wA[c] + v * kdA[c]; tB[c] = Sb[c] * wB[c] + v * kdB[c]; }
;         const float sa = -acc[0];
;         const float yq = acc[1];
; #pragma unroll
;         for (int c = 0; c < 8; c++) { Sa[c] = tA[c] + sa * kaA[c]; Sb[c] = tB[c] + sa * kaB[c]; }
;         const float y = yq + sa * c1 + v * c2;
;         if (quad == 0) by[s * 64 + row] = y;
;       }
	s_waitcnt lgkmcnt(8)
	v_xor_b32_e32 v110, 0x80000000, v32
	v_fma_f32 v109, -v32, v68, v33
	v_fma_f32 v109, v66, v69, v109
	v_fmac_f32_dpp v8, v48, v110 row_newbcast:0 row_mask:0xf bank_mask:0xf
	v_fmac_f32_dpp v9, v48, v110 row_newbcast:1 row_mask:0xf bank_mask:0xf
	v_fmac_f32_dpp v10, v48, v110 row_newbcast:2 row_mask:0xf bank_mask:0xf
	v_fmac_f32_dpp v11, v48, v110 row_newbcast:3 row_mask:0xf bank_mask:0xf
	v_fmac_f32_dpp v12, v48, v110 row_newbcast:4 row_mask:0xf bank_mask:0xf
	v_fmac_f32_dpp v13, v48, v110 row_newbcast:5 row_mask:0xf bank_mask:0xf
	v_fmac_f32_dpp v14, v48, v110 row_newbcast:6 row_mask:0xf bank_mask:0xf
	v_fmac_f32_dpp v15, v48, v110 row_newbcast:7 row_mask:0xf bank_mask:0xf
	v_fmac_f32_dpp v16, v48, v110 row_newbcast:8 row_mask:0xf bank_mask:0xf
	v_fmac_f32_dpp v17, v48, v110 row_newbcast:9 row_mask:0xf bank_mask:0xf
	v_fmac_f32_dpp v18, v48, v110 row_newbcast:10 row_mask:0xf bank_mask:0xf
	v_fmac_f32_dpp v19, v48, v110 row_newbcast:11 row_mask:0xf bank_mask:0xf
	v_fmac_f32_dpp v20, v48, v110 row_newbcast:12 row_mask:0xf bank_mask:0xf
	v_fmac_f32_dpp v21, v48, v110 row_newbcast:13 row_mask:0xf bank_mask:0xf
	v_fmac_f32_dpp v22, v48, v110 row_newbcast:14 row_mask:0xf bank_mask:0xf
	v_fmac_f32_dpp v23, v48, v110 row_newbcast:15 row_mask:0xf bank_mask:0xf
	ds_write_b32 v107, v109 offset:13824
	v_cvt_pk_bf16_f32 v24, v8, v9
	v_cvt_pk_bf16_f32 v25, v10, v11
	v_cvt_pk_bf16_f32 v26, v12, v13
	v_cvt_pk_bf16_f32 v27, v14, v15
	v_cvt_pk_bf16_f32 v28, v16, v17
	v_cvt_pk_bf16_f32 v29, v18, v19
	s_waitcnt lgkmcnt(7)
	v_mfma_f32_16x16x32_bf16 v[32:35], v[70:73], v[24:27], 0
	v_cvt_pk_bf16_f32 v30, v20, v21
	v_cvt_pk_bf16_f32 v31, v22, v23
	s_waitcnt lgkmcnt(3)
	v_fmac_f32_dpp v8, v95, v96 row_newbcast:0 row_mask:0xf bank_mask:0xf
	v_fmac_f32_dpp v9, v95, v96 row_newbcast:1 row_mask:0xf bank_mask:0xf
	v_mfma_f32_16x16x32_bf16 v[32:35], v[74:77], v[28:31], v[32:35]
	v_fmac_f32_dpp v10, v95, v96 row_newbcast:2 row_mask:0xf bank_mask:0xf
	v_fmac_f32_dpp v11, v95, v96 row_newbcast:3 row_mask:0xf bank_mask:0xf
	ds_read_b128 v[40:43], v104 offset:6144
	v_fmac_f32_dpp v12, v95, v96 row_newbcast:4 row_mask:0xf bank_mask:0xf
	v_fmac_f32_dpp v13, v95, v96 row_newbcast:5 row_mask:0xf bank_mask:0xf
	ds_read_b128 v[44:47], v104 offset:6160
	v_fmac_f32_dpp v14, v95, v96 row_newbcast:6 row_mask:0xf bank_mask:0xf
	v_fmac_f32_dpp v15, v95, v96 row_newbcast:7 row_mask:0xf bank_mask:0xf
	ds_read_b32 v65, v105 offset:22528
	v_fmac_f32_dpp v16, v95, v96 row_newbcast:8 row_mask:0xf bank_mask:0xf
	v_fmac_f32_dpp v17, v95, v96 row_newbcast:9 row_mask:0xf bank_mask:0xf
	ds_read_b32 v66, v107 offset:6144
	v_fmac_f32_dpp v18, v95, v96 row_newbcast:10 row_mask:0xf bank_mask:0xf
	v_fmac_f32_dpp v19, v95, v96 row_newbcast:11 row_mask:0xf bank_mask:0xf
	ds_read_b32 v48, v105 offset:14336
	v_fmac_f32_dpp v20, v95, v96 row_newbcast:12 row_mask:0xf bank_mask:0xf
	v_fmac_f32_dpp v21, v95, v96 row_newbcast:13 row_mask:0xf bank_mask:0xf
	ds_read_b64 v[68:69], v108 offset:49344
	v_fmac_f32_dpp v22, v95, v96 row_newbcast:14 row_mask:0xf bank_mask:0xf
	v_fmac_f32_dpp v23, v95, v96 row_newbcast:15 row_mask:0xf bank_mask:0xf
	s_waitcnt lgkmcnt(8)
	s_waitcnt lgkmcnt(7)
	v_xor_b32_e32 v110, 0x80000000, v32
	v_fma_f32 v109, -v32, v98, v33
	v_fma_f32 v109, v96, v99, v109
	v_fmac_f32_dpp v8, v78, v110 row_newbcast:0 row_mask:0xf bank_mask:0xf
	v_fmac_f32_dpp v9, v78, v110 row_newbcast:1 row_mask:0xf bank_mask:0xf
	v_fmac_f32_dpp v10, v78, v110 row_newbcast:2 row_mask:0xf bank_mask:0xf
	v_fmac_f32_dpp v11, v78, v110 row_newbcast:3 row_mask:0xf bank_mask:0xf
	v_fmac_f32_dpp v12, v78, v110 row_newbcast:4 row_mask:0xf bank_mask:0xf
	v_fmac_f32_dpp v13, v78, v110 row_newbcast:5 row_mask:0xf bank_mask:0xf
	v_fmac_f32_dpp v14, v78, v110 row_newbcast:6 row_mask:0xf bank_mask:0xf
	v_fmac_f32_dpp v15, v78, v110 row_newbcast:7 row_mask:0xf bank_mask:0xf
	v_fmac_f32_dpp v16, v78, v110 row_newbcast:8 row_mask:0xf bank_mask:0xf
	v_fmac_f32_dpp v17, v78, v110 row_newbcast:9 row_mask:0xf bank_mask:0xf
	v_fmac_f32_dpp v18, v78, v110 row_newbcast:10 row_mask:0xf bank_mask:0xf
	v_fmac_f32_dpp v19, v78, v110 row_newbcast:11 row_mask:0xf bank_mask:0xf
	v_fmac_f32_dpp v20, v78, v110 row_newbcast:12 row_mask:0xf bank_mask:0xf
	v_fmac_f32_dpp v21, v78, v110 row_newbcast:13 row_mask:0xf bank_mask:0xf
	v_fmac_f32_dpp v22, v78, v110 row_newbcast:14 row_mask:0xf bank_mask:0xf
	v_fmac_f32_dpp v23, v78, v110 row_newbcast:15 row_mask:0xf bank_mask:0xf
	v_mul_f32_dpp v8, v94, v8 row_newbcast:0 row_mask:0xf bank_mask:0xf
	v_mul_f32_dpp v9, v94, v9 row_newbcast:1 row_mask:0xf bank_mask:0xf
	v_mul_f32_dpp v10, v94, v10 row_newbcast:2 row_mask:0xf bank_mask:0xf
	v_mul_f32_dpp v11, v94, v11 row_newbcast:3 row_mask:0xf bank_mask:0xf
	v_mul_f32_dpp v12, v94, v12 row_newbcast:4 row_mask:0xf bank_mask:0xf
	v_mul_f32_dpp v13, v94, v13 row_newbcast:5 row_mask:0xf bank_mask:0xf
	v_mul_f32_dpp v14, v94, v14 row_newbcast:6 row_mask:0xf bank_mask:0xf
	v_mul_f32_dpp v15, v94, v15 row_newbcast:7 row_mask:0xf bank_mask:0xf
	v_mul_f32_dpp v16, v94, v16 row_newbcast:8 row_mask:0xf bank_mask:0xf
	v_mul_f32_dpp v17, v94, v17 row_newbcast:9 row_mask:0xf bank_mask:0xf
	v_mul_f32_dpp v18, v94, v18 row_newbcast:10 row_mask:0xf bank_mask:0xf
	v_mul_f32_dpp v19, v94, v19 row_newbcast:11 row_mask:0xf bank_mask:0xf
	v_mul_f32_dpp v20, v94, v20 row_newbcast:12 row_mask:0xf bank_mask:0xf
	v_mul_f32_dpp v21, v94, v21 row_newbcast:13 row_mask:0xf bank_mask:0xf
	v_mul_f32_dpp v22, v94, v22 row_newbcast:14 row_mask:0xf bank_mask:0xf
	v_mul_f32_dpp v23, v94, v23 row_newbcast:15 row_mask:0xf bank_mask:0xf
	ds_write_b32 v107, v109 offset:14080
	v_cvt_pk_bf16_f32 v24, v8, v9
	v_cvt_pk_bf16_f32 v25, v10, v11
	v_cvt_pk_bf16_f32 v26, v12, v13
	v_cvt_pk_bf16_f32 v27, v14, v15
	v_cvt_pk_bf16_f32 v28, v16, v17
	v_cvt_pk_bf16_f32 v29, v18, v19
	s_waitcnt lgkmcnt(6)
; __device__ __forceinline__ void phase_rwkv_scan(const Params& p, int l, const int tidx) {
;     ...
;       for (int s = 0; s < RTC; s++) {
;         const bf16x8 A0 = nA0, A1 = nA1;
;         const float wA[8] = {nw0.x, nw0.y, nw0.z, nw0.w, nw1.x, nw1.y, nw1.z, nw1.w};
;         const float wB[8] = {nw2.x, nw2.y, nw2.z, nw2.w, nw3.x, nw3.y, nw3.z, nw3.w};
;         const float kaA[8] = {nka0.x, nka0.y, nka0.z, nka0.w, nka1.x, nka1.y, nka1.z, nka1.w};
;         const float kaB[8] = {nka2.x, nka2.y, nka2.z, nka2.w, nka3.x, nka3.y, nka3.z, nka3.w};
;         const float kdA[8] = {nkd0.x, nkd0.y, nkd0.z, nkd0.w, nkd1.x, nkd1.y, nkd1.z, nkd1.w};
;         const float kdB[8] = {nkd2.x, nkd2.y, nkd2.z, nkd2.w, nkd3.x, nkd3.y, nkd3.z, nkd3.w};
;         const float v = nv;
;         float c1 = nc.x, c2 = nc.y;
;         asm volatile("" : "+v"(c1), "+v"(c2));
;         if (s + 1 < RTC) RW_LD(s + 1);
;         u32x4 pa = {pack2(Sa[0], Sa[1]), pack2(Sa[2], Sa[3]), pack2(Sa[4], Sa[5]), pack2(Sa[6], Sa[7])};
;         u32x4 pb = {pack2(Sb[0], Sb[1]), pack2(Sb[2], Sb[3]), pack2(Sb[4], Sb[5]), pack2(Sb[6], Sb[7])};
;         f32x4 acc = {0.f, 0.f, 0.f, 0.f};
;         acc = __builtin_amdgcn_mfma_f32_16x16x32_bf16(A0, __builtin_bit_cast(bf16x8, pa), acc, 0, 0, 0);
;         acc = __builtin_amdgcn_mfma_f32_16x16x32_bf16(A1, __builtin_bit_cast(bf16x8, pb), acc, 0, 0, 0);
;         float tA[8], tB[8];
; #pragma unroll
;         for (int c = 0; c < 8; c++) { tA[c] = Sa[c] * wA[c] + v * kdA[c]; tB[c] = Sb[c] * wB[c] + v * kdB[c]; }
;         const float sa = -acc[0];
;         const float yq = acc[1];
; #pragma unroll
;         for (int c = 0; c < 8; c++) { Sa[c] = tA[c] + sa * kaA[c]; Sb[c] = tB[c] + sa * kaB[c]; }
;         const float y = yq + sa * c1 + v * c2;
;         if (quad == 0) by[s * 64 + row] = y;
;       }
	v_mfma_f32_16x16x32_bf16 v[32:35], v[40:43], v[24:27], 0
	v_cvt_pk_bf16_f32 v30, v20, v21
	v_cvt_pk_bf16_f32 v31, v22, v23
	s_waitcnt lgkmcnt(3)
	v_fmac_f32_dpp v8, v65, v66 row_newbcast:0 row_mask:0xf bank_mask:0xf
	v_fmac_f32_dpp v9, v65, v66 row_newbcast:1 row_mask:0xf bank_mask:0xf
	v_mfma_f32_16x16x32_bf16 v[32:35], v[44:47], v[28:31], v[32:35]
	v_fmac_f32_dpp v10, v65, v66 row_newbcast:2 row_mask:0xf bank_mask:0xf
	v_fmac_f32_dpp v11, v65, v66 row_newbcast:3 row_mask:0xf bank_mask:0xf
	ds_read_b128 v[70:73], v104 offset:6400
	v_fmac_f32_dpp v12, v65, v66 row_newbcast:4 row_mask:0xf bank_mask:0xf
	v_fmac_f32_dpp v13, v65, v66 row_newbcast:5 row_mask:0xf bank_mask:0xf
	ds_read_b128 v[74:77], v104 offset:6416
	v_fmac_f32_dpp v14, v65, v66 row_newbcast:6 row_mask:0xf bank_mask:0xf
	v_fmac_f32_dpp v15, v65, v66 row_newbcast:7 row_mask:0xf bank_mask:0xf
	ds_read_b32 v95, v105 offset:22784
	v_fmac_f32_dpp v16, v65, v66 row_newbcast:8 row_mask:0xf bank_mask:0xf
	v_fmac_f32_dpp v17, v65, v66 row_newbcast:9 row_mask:0xf bank_mask:0xf
	ds_read_b32 v96, v107 offset:6400
	v_fmac_f32_dpp v18, v65, v66 row_newbcast:10 row_mask:0xf bank_mask:0xf
	v_fmac_f32_dpp v19, v65, v66 row_newbcast:11 row_mask:0xf bank_mask:0xf
	ds_read_b32 v78, v105 offset:14592
	v_fmac_f32_dpp v20, v65, v66 row_newbcast:12 row_mask:0xf bank_mask:0xf
	v_fmac_f32_dpp v21, v65, v66 row_newbcast:13 row_mask:0xf bank_mask:0xf
	ds_read_b64 v[98:99], v108 offset:49352
	v_fmac_f32_dpp v22, v65, v66 row_newbcast:14 row_mask:0xf bank_mask:0xf
	v_fmac_f32_dpp v23, v65, v66 row_newbcast:15 row_mask:0xf bank_mask:0xf
	s_waitcnt lgkmcnt(8)
	s_waitcnt lgkmcnt(7)
	v_xor_b32_e32 v110, 0x80000000, v32
	v_fma_f32 v109, -v32, v68, v33
	v_fma_f32 v109, v66, v69, v109
	v_fmac_f32_dpp v8, v48, v110 row_newbcast:0 row_mask:0xf bank_mask:0xf
	v_fmac_f32_dpp v9, v48, v110 row_newbcast:1 row_mask:0xf bank_mask:0xf
	v_fmac_f32_dpp v10, v48, v110 row_newbcast:2 row_mask:0xf bank_mask:0xf
	v_fmac_f32_dpp v11, v48, v110 row_newbcast:3 row_mask:0xf bank_mask:0xf
	v_fmac_f32_dpp v12, v48, v110 row_newbcast:4 row_mask:0xf bank_mask:0xf
	v_fmac_f32_dpp v13, v48, v110 row_newbcast:5 row_mask:0xf bank_mask:0xf
	v_fmac_f32_dpp v14, v48, v110 row_newbcast:6 row_mask:0xf bank_mask:0xf
	v_fmac_f32_dpp v15, v48, v110 row_newbcast:7 row_mask:0xf bank_mask:0xf
	v_fmac_f32_dpp v16, v48, v110 row_newbcast:8 row_mask:0xf bank_mask:0xf
	v_fmac_f32_dpp v17, v48, v110 row_newbcast:9 row_mask:0xf bank_mask:0xf
	v_fmac_f32_dpp v18, v48, v110 row_newbcast:10 row_mask:0xf bank_mask:0xf
	v_fmac_f32_dpp v19, v48, v110 row_newbcast:11 row_mask:0xf bank_mask:0xf
	v_fmac_f32_dpp v20, v48, v110 row_newbcast:12 row_mask:0xf bank_mask:0xf
	v_fmac_f32_dpp v21, v48, v110 row_newbcast:13 row_mask:0xf bank_mask:0xf
	v_fmac_f32_dpp v22, v48, v110 row_newbcast:14 row_mask:0xf bank_mask:0xf
	v_fmac_f32_dpp v23, v48, v110 row_newbcast:15 row_mask:0xf bank_mask:0xf
	ds_write_b32 v107, v109 offset:14336
	v_cvt_pk_bf16_f32 v24, v8, v9
	v_cvt_pk_bf16_f32 v25, v10, v11
	v_cvt_pk_bf16_f32 v26, v12, v13
	v_cvt_pk_bf16_f32 v27, v14, v15
	v_cvt_pk_bf16_f32 v28, v16, v17
	v_cvt_pk_bf16_f32 v29, v18, v19
	s_waitcnt lgkmcnt(6)
	v_mfma_f32_16x16x32_bf16 v[32:35], v[70:73], v[24:27], 0
	v_cvt_pk_bf16_f32 v30, v20, v21
	v_cvt_pk_bf16_f32 v31, v22, v23
	s_waitcnt lgkmcnt(3)
	v_fmac_f32_dpp v8, v95, v96 row_newbcast:0 row_mask:0xf bank_mask:0xf
	v_fmac_f32_dpp v9, v95, v96 row_newbcast:1 row_mask:0xf bank_mask:0xf
	v_mfma_f32_16x16x32_bf16 v[32:35], v[74:77], v[28:31], v[32:35]
	v_fmac_f32_dpp v10, v95, v96 row_newbcast:2 row_mask:0xf bank_mask:0xf
	v_fmac_f32_dpp v11, v95, v96 row_newbcast:3 row_mask:0xf bank_mask:0xf
	ds_read_b128 v[40:43], v104 offset:6656
	v_fmac_f32_dpp v12, v95, v96 row_newbcast:4 row_mask:0xf bank_mask:0xf
	v_fmac_f32_dpp v13, v95, v96 row_newbcast:5 row_mask:0xf bank_mask:0xf
	ds_read_b128 v[44:47], v104 offset:6672
	v_fmac_f32_dpp v14, v95, v96 row_newbcast:6 row_mask:0xf bank_mask:0xf
	v_fmac_f32_dpp v15, v95, v96 row_newbcast:7 row_mask:0xf bank_mask:0xf
	ds_read_b32 v65, v105 offset:23040
	v_fmac_f32_dpp v16, v95, v96 row_newbcast:8 row_mask:0xf bank_mask:0xf
	v_fmac_f32_dpp v17, v95, v96 row_newbcast:9 row_mask:0xf bank_mask:0xf
	ds_read_b32 v66, v107 offset:6656
	v_fmac_f32_dpp v18, v95, v96 row_newbcast:10 row_mask:0xf bank_mask:0xf
	v_fmac_f32_dpp v19, v95, v96 row_newbcast:11 row_mask:0xf bank_mask:0xf
	ds_read_b32 v48, v105 offset:14848
	v_fmac_f32_dpp v20, v95, v96 row_newbcast:12 row_mask:0xf bank_mask:0xf
	v_fmac_f32_dpp v21, v95, v96 row_newbcast:13 row_mask:0xf bank_mask:0xf
	ds_read_b64 v[68:69], v108 offset:49360
	v_fmac_f32_dpp v22, v95, v96 row_newbcast:14 row_mask:0xf bank_mask:0xf
	v_fmac_f32_dpp v23, v95, v96 row_newbcast:15 row_mask:0xf bank_mask:0xf
	s_waitcnt lgkmcnt(8)
	s_waitcnt lgkmcnt(7)
	v_xor_b32_e32 v110, 0x80000000, v32
	v_fma_f32 v109, -v32, v98, v33
	v_fma_f32 v109, v96, v99, v109
	v_fmac_f32_dpp v8, v78, v110 row_newbcast:0 row_mask:0xf bank_mask:0xf
	v_fmac_f32_dpp v9, v78, v110 row_newbcast:1 row_mask:0xf bank_mask:0xf
	v_fmac_f32_dpp v10, v78, v110 row_newbcast:2 row_mask:0xf bank_mask:0xf
	v_fmac_f32_dpp v11, v78, v110 row_newbcast:3 row_mask:0xf bank_mask:0xf
	v_fmac_f32_dpp v12, v78, v110 row_newbcast:4 row_mask:0xf bank_mask:0xf
	v_fmac_f32_dpp v13, v78, v110 row_newbcast:5 row_mask:0xf bank_mask:0xf
	v_fmac_f32_dpp v14, v78, v110 row_newbcast:6 row_mask:0xf bank_mask:0xf
	v_fmac_f32_dpp v15, v78, v110 row_newbcast:7 row_mask:0xf bank_mask:0xf
	v_fmac_f32_dpp v16, v78, v110 row_newbcast:8 row_mask:0xf bank_mask:0xf
	v_fmac_f32_dpp v17, v78, v110 row_newbcast:9 row_mask:0xf bank_mask:0xf
	v_fmac_f32_dpp v18, v78, v110 row_newbcast:10 row_mask:0xf bank_mask:0xf
	v_fmac_f32_dpp v19, v78, v110 row_newbcast:11 row_mask:0xf bank_mask:0xf
	v_fmac_f32_dpp v20, v78, v110 row_newbcast:12 row_mask:0xf bank_mask:0xf
	v_fmac_f32_dpp v21, v78, v110 row_newbcast:13 row_mask:0xf bank_mask:0xf
	v_fmac_f32_dpp v22, v78, v110 row_newbcast:14 row_mask:0xf bank_mask:0xf
	v_fmac_f32_dpp v23, v78, v110 row_newbcast:15 row_mask:0xf bank_mask:0xf
	ds_write_b32 v107, v109 offset:14592
	v_cvt_pk_bf16_f32 v24, v8, v9
	v_cvt_pk_bf16_f32 v25, v10, v11
	v_cvt_pk_bf16_f32 v26, v12, v13
	v_cvt_pk_bf16_f32 v27, v14, v15
	v_cvt_pk_bf16_f32 v28, v16, v17
	v_cvt_pk_bf16_f32 v29, v18, v19
	s_waitcnt lgkmcnt(6)
; __device__ __forceinline__ void phase_rwkv_scan(const Params& p, int l, const int tidx) {
;     ...
;       for (int s = 0; s < RTC; s++) {
;         const bf16x8 A0 = nA0, A1 = nA1;
;         const float wA[8] = {nw0.x, nw0.y, nw0.z, nw0.w, nw1.x, nw1.y, nw1.z, nw1.w};
;         const float wB[8] = {nw2.x, nw2.y, nw2.z, nw2.w, nw3.x, nw3.y, nw3.z, nw3.w};
;         const float kaA[8] = {nka0.x, nka0.y, nka0.z, nka0.w, nka1.x, nka1.y, nka1.z, nka1.w};
;         const float kaB[8] = {nka2.x, nka2.y, nka2.z, nka2.w, nka3.x, nka3.y, nka3.z, nka3.w};
;         const float kdA[8] = {nkd0.x, nkd0.y, nkd0.z, nkd0.w, nkd1.x, nkd1.y, nkd1.z, nkd1.w};
;         const float kdB[8] = {nkd2.x, nkd2.y, nkd2.z, nkd2.w, nkd3.x, nkd3.y, nkd3.z, nkd3.w};
;         const float v = nv;
;         float c1 = nc.x, c2 = nc.y;
;         asm volatile("" : "+v"(c1), "+v"(c2));
;         if (s + 1 < RTC) RW_LD(s + 1);
;         u32x4 pa = {pack2(Sa[0], Sa[1]), pack2(Sa[2], Sa[3]), pack2(Sa[4], Sa[5]), pack2(Sa[6], Sa[7])};
;         u32x4 pb = {pack2(Sb[0], Sb[1]), pack2(Sb[2], Sb[3]), pack2(Sb[4], Sb[5]), pack2(Sb[6], Sb[7])};
;         f32x4 acc = {0.f, 0.f, 0.f, 0.f};
;         acc = __builtin_amdgcn_mfma_f32_16x16x32_bf16(A0, __builtin_bit_cast(bf16x8, pa), acc, 0, 0, 0);
;         acc = __builtin_amdgcn_mfma_f32_16x16x32_bf16(A1, __builtin_bit_cast(bf16x8, pb), acc, 0, 0, 0);
;         float tA[8], tB[8];
; #pragma unroll
;         for (int c = 0; c < 8; c++) { tA[c] = Sa[c] * wA[c] + v * kdA[c]; tB[c] = Sb[c] * wB[c] + v * kdB[c]; }
;         const float sa = -acc[0];
;         const float yq = acc[1];
; #pragma unroll
;         for (int c = 0; c < 8; c++) { Sa[c] = tA[c] + sa * kaA[c]; Sb[c] = tB[c] + sa * kaB[c]; }
;         const float y = yq + sa * c1 + v * c2;
;         if (quad == 0) by[s * 64 + row] = y;
;       }
	v_mfma_f32_16x16x32_bf16 v[32:35], v[40:43], v[24:27], 0
	v_cvt_pk_bf16_f32 v30, v20, v21
	v_cvt_pk_bf16_f32 v31, v22, v23
	s_waitcnt lgkmcnt(3)
	v_fmac_f32_dpp v8, v65, v66 row_newbcast:0 row_mask:0xf bank_mask:0xf
	v_fmac_f32_dpp v9, v65, v66 row_newbcast:1 row_mask:0xf bank_mask:0xf
	v_mfma_f32_16x16x32_bf16 v[32:35], v[44:47], v[28:31], v[32:35]
	v_fmac_f32_dpp v10, v65, v66 row_newbcast:2 row_mask:0xf bank_mask:0xf
	v_fmac_f32_dpp v11, v65, v66 row_newbcast:3 row_mask:0xf bank_mask:0xf
	ds_read_b128 v[70:73], v104 offset:6912
	v_fmac_f32_dpp v12, v65, v66 row_newbcast:4 row_mask:0xf bank_mask:0xf
	v_fmac_f32_dpp v13, v65, v66 row_newbcast:5 row_mask:0xf bank_mask:0xf
	ds_read_b128 v[74:77], v104 offset:6928
	v_fmac_f32_dpp v14, v65, v66 row_newbcast:6 row_mask:0xf bank_mask:0xf
	v_fmac_f32_dpp v15, v65, v66 row_newbcast:7 row_mask:0xf bank_mask:0xf
	ds_read_b32 v95, v105 offset:23296
	v_fmac_f32_dpp v16, v65, v66 row_newbcast:8 row_mask:0xf bank_mask:0xf
	v_fmac_f32_dpp v17, v65, v66 row_newbcast:9 row_mask:0xf bank_mask:0xf
	ds_read_b32 v96, v107 offset:6912
	v_fmac_f32_dpp v18, v65, v66 row_newbcast:10 row_mask:0xf bank_mask:0xf
	v_fmac_f32_dpp v19, v65, v66 row_newbcast:11 row_mask:0xf bank_mask:0xf
	ds_read_b32 v78, v105 offset:15104
	v_fmac_f32_dpp v20, v65, v66 row_newbcast:12 row_mask:0xf bank_mask:0xf
	v_fmac_f32_dpp v21, v65, v66 row_newbcast:13 row_mask:0xf bank_mask:0xf
	ds_read_b64 v[98:99], v108 offset:49368
	v_fmac_f32_dpp v22, v65, v66 row_newbcast:14 row_mask:0xf bank_mask:0xf
	v_fmac_f32_dpp v23, v65, v66 row_newbcast:15 row_mask:0xf bank_mask:0xf
	s_waitcnt lgkmcnt(8)
	s_waitcnt lgkmcnt(7)
	v_xor_b32_e32 v110, 0x80000000, v32
	v_fma_f32 v109, -v32, v68, v33
	v_fma_f32 v109, v66, v69, v109
	v_fmac_f32_dpp v8, v48, v110 row_newbcast:0 row_mask:0xf bank_mask:0xf
	v_fmac_f32_dpp v9, v48, v110 row_newbcast:1 row_mask:0xf bank_mask:0xf
	v_fmac_f32_dpp v10, v48, v110 row_newbcast:2 row_mask:0xf bank_mask:0xf
	v_fmac_f32_dpp v11, v48, v110 row_newbcast:3 row_mask:0xf bank_mask:0xf
	v_fmac_f32_dpp v12, v48, v110 row_newbcast:4 row_mask:0xf bank_mask:0xf
	v_fmac_f32_dpp v13, v48, v110 row_newbcast:5 row_mask:0xf bank_mask:0xf
	v_fmac_f32_dpp v14, v48, v110 row_newbcast:6 row_mask:0xf bank_mask:0xf
	v_fmac_f32_dpp v15, v48, v110 row_newbcast:7 row_mask:0xf bank_mask:0xf
	v_fmac_f32_dpp v16, v48, v110 row_newbcast:8 row_mask:0xf bank_mask:0xf
	v_fmac_f32_dpp v17, v48, v110 row_newbcast:9 row_mask:0xf bank_mask:0xf
	v_fmac_f32_dpp v18, v48, v110 row_newbcast:10 row_mask:0xf bank_mask:0xf
	v_fmac_f32_dpp v19, v48, v110 row_newbcast:11 row_mask:0xf bank_mask:0xf
	v_fmac_f32_dpp v20, v48, v110 row_newbcast:12 row_mask:0xf bank_mask:0xf
	v_fmac_f32_dpp v21, v48, v110 row_newbcast:13 row_mask:0xf bank_mask:0xf
	v_fmac_f32_dpp v22, v48, v110 row_newbcast:14 row_mask:0xf bank_mask:0xf
	v_fmac_f32_dpp v23, v48, v110 row_newbcast:15 row_mask:0xf bank_mask:0xf
	ds_write_b32 v107, v109 offset:14848
	v_cvt_pk_bf16_f32 v24, v8, v9
	v_cvt_pk_bf16_f32 v25, v10, v11
	v_cvt_pk_bf16_f32 v26, v12, v13
	v_cvt_pk_bf16_f32 v27, v14, v15
	v_cvt_pk_bf16_f32 v28, v16, v17
	v_cvt_pk_bf16_f32 v29, v18, v19
	s_waitcnt lgkmcnt(6)
	v_mfma_f32_16x16x32_bf16 v[32:35], v[70:73], v[24:27], 0
	v_cvt_pk_bf16_f32 v30, v20, v21
	v_cvt_pk_bf16_f32 v31, v22, v23
	s_waitcnt lgkmcnt(3)
	v_fmac_f32_dpp v8, v95, v96 row_newbcast:0 row_mask:0xf bank_mask:0xf
	v_fmac_f32_dpp v9, v95, v96 row_newbcast:1 row_mask:0xf bank_mask:0xf
	v_mfma_f32_16x16x32_bf16 v[32:35], v[74:77], v[28:31], v[32:35]
	v_fmac_f32_dpp v10, v95, v96 row_newbcast:2 row_mask:0xf bank_mask:0xf
	v_fmac_f32_dpp v11, v95, v96 row_newbcast:3 row_mask:0xf bank_mask:0xf
	ds_read_b128 v[40:43], v104 offset:7168
	v_fmac_f32_dpp v12, v95, v96 row_newbcast:4 row_mask:0xf bank_mask:0xf
	v_fmac_f32_dpp v13, v95, v96 row_newbcast:5 row_mask:0xf bank_mask:0xf
	ds_read_b128 v[44:47], v104 offset:7184
	v_fmac_f32_dpp v14, v95, v96 row_newbcast:6 row_mask:0xf bank_mask:0xf
	v_fmac_f32_dpp v15, v95, v96 row_newbcast:7 row_mask:0xf bank_mask:0xf
	ds_read_b32 v65, v105 offset:23552
	v_fmac_f32_dpp v16, v95, v96 row_newbcast:8 row_mask:0xf bank_mask:0xf
	v_fmac_f32_dpp v17, v95, v96 row_newbcast:9 row_mask:0xf bank_mask:0xf
	ds_read_b32 v66, v107 offset:7168
	v_fmac_f32_dpp v18, v95, v96 row_newbcast:10 row_mask:0xf bank_mask:0xf
	v_fmac_f32_dpp v19, v95, v96 row_newbcast:11 row_mask:0xf bank_mask:0xf
	ds_read_b32 v48, v105 offset:15360
	v_fmac_f32_dpp v20, v95, v96 row_newbcast:12 row_mask:0xf bank_mask:0xf
	v_fmac_f32_dpp v21, v95, v96 row_newbcast:13 row_mask:0xf bank_mask:0xf
	ds_read_b64 v[68:69], v108 offset:49376
	v_fmac_f32_dpp v22, v95, v96 row_newbcast:14 row_mask:0xf bank_mask:0xf
	v_fmac_f32_dpp v23, v95, v96 row_newbcast:15 row_mask:0xf bank_mask:0xf
	s_waitcnt lgkmcnt(8)
	s_waitcnt lgkmcnt(7)
	v_xor_b32_e32 v110, 0x80000000, v32
	v_fma_f32 v109, -v32, v98, v33
	v_fma_f32 v109, v96, v99, v109
	v_fmac_f32_dpp v8, v78, v110 row_newbcast:0 row_mask:0xf bank_mask:0xf
	v_fmac_f32_dpp v9, v78, v110 row_newbcast:1 row_mask:0xf bank_mask:0xf
	v_fmac_f32_dpp v10, v78, v110 row_newbcast:2 row_mask:0xf bank_mask:0xf
	v_fmac_f32_dpp v11, v78, v110 row_newbcast:3 row_mask:0xf bank_mask:0xf
	v_fmac_f32_dpp v12, v78, v110 row_newbcast:4 row_mask:0xf bank_mask:0xf
	v_fmac_f32_dpp v13, v78, v110 row_newbcast:5 row_mask:0xf bank_mask:0xf
	v_fmac_f32_dpp v14, v78, v110 row_newbcast:6 row_mask:0xf bank_mask:0xf
	v_fmac_f32_dpp v15, v78, v110 row_newbcast:7 row_mask:0xf bank_mask:0xf
	v_fmac_f32_dpp v16, v78, v110 row_newbcast:8 row_mask:0xf bank_mask:0xf
	v_fmac_f32_dpp v17, v78, v110 row_newbcast:9 row_mask:0xf bank_mask:0xf
	v_fmac_f32_dpp v18, v78, v110 row_newbcast:10 row_mask:0xf bank_mask:0xf
	v_fmac_f32_dpp v19, v78, v110 row_newbcast:11 row_mask:0xf bank_mask:0xf
	v_fmac_f32_dpp v20, v78, v110 row_newbcast:12 row_mask:0xf bank_mask:0xf
	v_fmac_f32_dpp v21, v78, v110 row_newbcast:13 row_mask:0xf bank_mask:0xf
	v_fmac_f32_dpp v22, v78, v110 row_newbcast:14 row_mask:0xf bank_mask:0xf
	v_fmac_f32_dpp v23, v78, v110 row_newbcast:15 row_mask:0xf bank_mask:0xf
	ds_write_b32 v107, v109 offset:15104
	v_cvt_pk_bf16_f32 v24, v8, v9
	v_cvt_pk_bf16_f32 v25, v10, v11
	v_cvt_pk_bf16_f32 v26, v12, v13
	v_cvt_pk_bf16_f32 v27, v14, v15
	v_cvt_pk_bf16_f32 v28, v16, v17
	v_cvt_pk_bf16_f32 v29, v18, v19
	s_waitcnt lgkmcnt(6)
; __device__ __forceinline__ void phase_rwkv_scan(const Params& p, int l, const int tidx) {
;     ...
;       for (int s = 0; s < RTC; s++) {
;         const bf16x8 A0 = nA0, A1 = nA1;
;         const float wA[8] = {nw0.x, nw0.y, nw0.z, nw0.w, nw1.x, nw1.y, nw1.z, nw1.w};
;         const float wB[8] = {nw2.x, nw2.y, nw2.z, nw2.w, nw3.x, nw3.y, nw3.z, nw3.w};
;         const float kaA[8] = {nka0.x, nka0.y, nka0.z, nka0.w, nka1.x, nka1.y, nka1.z, nka1.w};
;         const float kaB[8] = {nka2.x, nka2.y, nka2.z, nka2.w, nka3.x, nka3.y, nka3.z, nka3.w};
;         const float kdA[8] = {nkd0.x, nkd0.y, nkd0.z, nkd0.w, nkd1.x, nkd1.y, nkd1.z, nkd1.w};
;         const float kdB[8] = {nkd2.x, nkd2.y, nkd2.z, nkd2.w, nkd3.x, nkd3.y, nkd3.z, nkd3.w};
;         const float v = nv;
;         float c1 = nc.x, c2 = nc.y;
;         asm volatile("" : "+v"(c1), "+v"(c2));
;         if (s + 1 < RTC) RW_LD(s + 1);
;         u32x4 pa = {pack2(Sa[0], Sa[1]), pack2(Sa[2], Sa[3]), pack2(Sa[4], Sa[5]), pack2(Sa[6], Sa[7])};
;         u32x4 pb = {pack2(Sb[0], Sb[1]), pack2(Sb[2], Sb[3]), pack2(Sb[4], Sb[5]), pack2(Sb[6], Sb[7])};
;         f32x4 acc = {0.f, 0.f, 0.f, 0.f};
;         acc = __builtin_amdgcn_mfma_f32_16x16x32_bf16(A0, __builtin_bit_cast(bf16x8, pa), acc, 0, 0, 0);
;         acc = __builtin_amdgcn_mfma_f32_16x16x32_bf16(A1, __builtin_bit_cast(bf16x8, pb), acc, 0, 0, 0);
;         float tA[8], tB[8];
; #pragma unroll
;         for (int c = 0; c < 8; c++) { tA[c] = Sa[c] * wA[c] + v * kdA[c]; tB[c] = Sb[c] * wB[c] + v * kdB[c]; }
;         const float sa = -acc[0];
;         const float yq = acc[1];
; #pragma unroll
;         for (int c = 0; c < 8; c++) { Sa[c] = tA[c] + sa * kaA[c]; Sb[c] = tB[c] + sa * kaB[c]; }
;         const float y = yq + sa * c1 + v * c2;
;         if (quad == 0) by[s * 64 + row] = y;
;       }
	v_mfma_f32_16x16x32_bf16 v[32:35], v[40:43], v[24:27], 0
	v_cvt_pk_bf16_f32 v30, v20, v21
	v_cvt_pk_bf16_f32 v31, v22, v23
	s_waitcnt lgkmcnt(3)
	v_fmac_f32_dpp v8, v65, v66 row_newbcast:0 row_mask:0xf bank_mask:0xf
	v_fmac_f32_dpp v9, v65, v66 row_newbcast:1 row_mask:0xf bank_mask:0xf
	v_mfma_f32_16x16x32_bf16 v[32:35], v[44:47], v[28:31], v[32:35]
	v_fmac_f32_dpp v10, v65, v66 row_newbcast:2 row_mask:0xf bank_mask:0xf
	v_fmac_f32_dpp v11, v65, v66 row_newbcast:3 row_mask:0xf bank_mask:0xf
	ds_read_b128 v[70:73], v104 offset:7424
	v_fmac_f32_dpp v12, v65, v66 row_newbcast:4 row_mask:0xf bank_mask:0xf
	v_fmac_f32_dpp v13, v65, v66 row_newbcast:5 row_mask:0xf bank_mask:0xf
	ds_read_b128 v[74:77], v104 offset:7440
	v_fmac_f32_dpp v14, v65, v66 row_newbcast:6 row_mask:0xf bank_mask:0xf
	v_fmac_f32_dpp v15, v65, v66 row_newbcast:7 row_mask:0xf bank_mask:0xf
	ds_read_b32 v95, v105 offset:23808
	v_fmac_f32_dpp v16, v65, v66 row_newbcast:8 row_mask:0xf bank_mask:0xf
	v_fmac_f32_dpp v17, v65, v66 row_newbcast:9 row_mask:0xf bank_mask:0xf
	ds_read_b32 v96, v107 offset:7424
	v_fmac_f32_dpp v18, v65, v66 row_newbcast:10 row_mask:0xf bank_mask:0xf
	v_fmac_f32_dpp v19, v65, v66 row_newbcast:11 row_mask:0xf bank_mask:0xf
	ds_read_b32 v78, v105 offset:15616
	v_fmac_f32_dpp v20, v65, v66 row_newbcast:12 row_mask:0xf bank_mask:0xf
	v_fmac_f32_dpp v21, v65, v66 row_newbcast:13 row_mask:0xf bank_mask:0xf
	ds_read_b64 v[98:99], v108 offset:49384
	v_fmac_f32_dpp v22, v65, v66 row_newbcast:14 row_mask:0xf bank_mask:0xf
	v_fmac_f32_dpp v23, v65, v66 row_newbcast:15 row_mask:0xf bank_mask:0xf
	s_waitcnt lgkmcnt(8)
	s_waitcnt lgkmcnt(7)
	v_xor_b32_e32 v110, 0x80000000, v32
	v_fma_f32 v109, -v32, v68, v33
	v_fma_f32 v109, v66, v69, v109
	v_fmac_f32_dpp v8, v48, v110 row_newbcast:0 row_mask:0xf bank_mask:0xf
	v_fmac_f32_dpp v9, v48, v110 row_newbcast:1 row_mask:0xf bank_mask:0xf
	v_fmac_f32_dpp v10, v48, v110 row_newbcast:2 row_mask:0xf bank_mask:0xf
	v_fmac_f32_dpp v11, v48, v110 row_newbcast:3 row_mask:0xf bank_mask:0xf
	v_fmac_f32_dpp v12, v48, v110 row_newbcast:4 row_mask:0xf bank_mask:0xf
	v_fmac_f32_dpp v13, v48, v110 row_newbcast:5 row_mask:0xf bank_mask:0xf
	v_fmac_f32_dpp v14, v48, v110 row_newbcast:6 row_mask:0xf bank_mask:0xf
	v_fmac_f32_dpp v15, v48, v110 row_newbcast:7 row_mask:0xf bank_mask:0xf
	v_fmac_f32_dpp v16, v48, v110 row_newbcast:8 row_mask:0xf bank_mask:0xf
	v_fmac_f32_dpp v17, v48, v110 row_newbcast:9 row_mask:0xf bank_mask:0xf
	v_fmac_f32_dpp v18, v48, v110 row_newbcast:10 row_mask:0xf bank_mask:0xf
	v_fmac_f32_dpp v19, v48, v110 row_newbcast:11 row_mask:0xf bank_mask:0xf
	v_fmac_f32_dpp v20, v48, v110 row_newbcast:12 row_mask:0xf bank_mask:0xf
	v_fmac_f32_dpp v21, v48, v110 row_newbcast:13 row_mask:0xf bank_mask:0xf
	v_fmac_f32_dpp v22, v48, v110 row_newbcast:14 row_mask:0xf bank_mask:0xf
	v_fmac_f32_dpp v23, v48, v110 row_newbcast:15 row_mask:0xf bank_mask:0xf
	ds_write_b32 v107, v109 offset:15360
	v_cvt_pk_bf16_f32 v24, v8, v9
	v_cvt_pk_bf16_f32 v25, v10, v11
	v_cvt_pk_bf16_f32 v26, v12, v13
	v_cvt_pk_bf16_f32 v27, v14, v15
	v_cvt_pk_bf16_f32 v28, v16, v17
	v_cvt_pk_bf16_f32 v29, v18, v19
	s_waitcnt lgkmcnt(6)
	v_mfma_f32_16x16x32_bf16 v[32:35], v[70:73], v[24:27], 0
	v_cvt_pk_bf16_f32 v30, v20, v21
	v_cvt_pk_bf16_f32 v31, v22, v23
	s_waitcnt lgkmcnt(3)
	v_fmac_f32_dpp v8, v95, v96 row_newbcast:0 row_mask:0xf bank_mask:0xf
	v_fmac_f32_dpp v9, v95, v96 row_newbcast:1 row_mask:0xf bank_mask:0xf
	v_mfma_f32_16x16x32_bf16 v[32:35], v[74:77], v[28:31], v[32:35]
	v_fmac_f32_dpp v10, v95, v96 row_newbcast:2 row_mask:0xf bank_mask:0xf
	v_fmac_f32_dpp v11, v95, v96 row_newbcast:3 row_mask:0xf bank_mask:0xf
	ds_read_b128 v[40:43], v104 offset:7680
	v_fmac_f32_dpp v12, v95, v96 row_newbcast:4 row_mask:0xf bank_mask:0xf
	v_fmac_f32_dpp v13, v95, v96 row_newbcast:5 row_mask:0xf bank_mask:0xf
	ds_read_b128 v[44:47], v104 offset:7696
	v_fmac_f32_dpp v14, v95, v96 row_newbcast:6 row_mask:0xf bank_mask:0xf
	v_fmac_f32_dpp v15, v95, v96 row_newbcast:7 row_mask:0xf bank_mask:0xf
	ds_read_b32 v65, v105 offset:24064
	v_fmac_f32_dpp v16, v95, v96 row_newbcast:8 row_mask:0xf bank_mask:0xf
	v_fmac_f32_dpp v17, v95, v96 row_newbcast:9 row_mask:0xf bank_mask:0xf
	ds_read_b32 v66, v107 offset:7680
	v_fmac_f32_dpp v18, v95, v96 row_newbcast:10 row_mask:0xf bank_mask:0xf
	v_fmac_f32_dpp v19, v95, v96 row_newbcast:11 row_mask:0xf bank_mask:0xf
	ds_read_b32 v48, v105 offset:15872
	v_fmac_f32_dpp v20, v95, v96 row_newbcast:12 row_mask:0xf bank_mask:0xf
	v_fmac_f32_dpp v21, v95, v96 row_newbcast:13 row_mask:0xf bank_mask:0xf
	ds_read_b64 v[68:69], v108 offset:49392
	v_fmac_f32_dpp v22, v95, v96 row_newbcast:14 row_mask:0xf bank_mask:0xf
	v_fmac_f32_dpp v23, v95, v96 row_newbcast:15 row_mask:0xf bank_mask:0xf
	s_waitcnt lgkmcnt(8)
	s_waitcnt lgkmcnt(7)
	v_xor_b32_e32 v110, 0x80000000, v32
	v_fma_f32 v109, -v32, v98, v33
	v_fma_f32 v109, v96, v99, v109
	v_fmac_f32_dpp v8, v78, v110 row_newbcast:0 row_mask:0xf bank_mask:0xf
	v_fmac_f32_dpp v9, v78, v110 row_newbcast:1 row_mask:0xf bank_mask:0xf
	v_fmac_f32_dpp v10, v78, v110 row_newbcast:2 row_mask:0xf bank_mask:0xf
	v_fmac_f32_dpp v11, v78, v110 row_newbcast:3 row_mask:0xf bank_mask:0xf
	v_fmac_f32_dpp v12, v78, v110 row_newbcast:4 row_mask:0xf bank_mask:0xf
	v_fmac_f32_dpp v13, v78, v110 row_newbcast:5 row_mask:0xf bank_mask:0xf
	v_fmac_f32_dpp v14, v78, v110 row_newbcast:6 row_mask:0xf bank_mask:0xf
	v_fmac_f32_dpp v15, v78, v110 row_newbcast:7 row_mask:0xf bank_mask:0xf
	v_fmac_f32_dpp v16, v78, v110 row_newbcast:8 row_mask:0xf bank_mask:0xf
	v_fmac_f32_dpp v17, v78, v110 row_newbcast:9 row_mask:0xf bank_mask:0xf
	v_fmac_f32_dpp v18, v78, v110 row_newbcast:10 row_mask:0xf bank_mask:0xf
	v_fmac_f32_dpp v19, v78, v110 row_newbcast:11 row_mask:0xf bank_mask:0xf
	v_fmac_f32_dpp v20, v78, v110 row_newbcast:12 row_mask:0xf bank_mask:0xf
	v_fmac_f32_dpp v21, v78, v110 row_newbcast:13 row_mask:0xf bank_mask:0xf
	v_fmac_f32_dpp v22, v78, v110 row_newbcast:14 row_mask:0xf bank_mask:0xf
	v_fmac_f32_dpp v23, v78, v110 row_newbcast:15 row_mask:0xf bank_mask:0xf
	ds_write_b32 v107, v109 offset:15616
	v_cvt_pk_bf16_f32 v24, v8, v9
	v_cvt_pk_bf16_f32 v25, v10, v11
	v_cvt_pk_bf16_f32 v26, v12, v13
	v_cvt_pk_bf16_f32 v27, v14, v15
	v_cvt_pk_bf16_f32 v28, v16, v17
	v_cvt_pk_bf16_f32 v29, v18, v19
	s_waitcnt lgkmcnt(6)
; __device__ __forceinline__ void phase_rwkv_scan(const Params& p, int l, const int tidx) {
;     ...
;       for (int s = 0; s < RTC; s++) {
;         const bf16x8 A0 = nA0, A1 = nA1;
;         const float wA[8] = {nw0.x, nw0.y, nw0.z, nw0.w, nw1.x, nw1.y, nw1.z, nw1.w};
;         const float wB[8] = {nw2.x, nw2.y, nw2.z, nw2.w, nw3.x, nw3.y, nw3.z, nw3.w};
;         const float kaA[8] = {nka0.x, nka0.y, nka0.z, nka0.w, nka1.x, nka1.y, nka1.z, nka1.w};
;         const float kaB[8] = {nka2.x, nka2.y, nka2.z, nka2.w, nka3.x, nka3.y, nka3.z, nka3.w};
;         const float kdA[8] = {nkd0.x, nkd0.y, nkd0.z, nkd0.w, nkd1.x, nkd1.y, nkd1.z, nkd1.w};
;         const float kdB[8] = {nkd2.x, nkd2.y, nkd2.z, nkd2.w, nkd3.x, nkd3.y, nkd3.z, nkd3.w};
;         const float v = nv;
;         float c1 = nc.x, c2 = nc.y;
;         asm volatile("" : "+v"(c1), "+v"(c2));
;         if (s + 1 < RTC) RW_LD(s + 1);
;         u32x4 pa = {pack2(Sa[0], Sa[1]), pack2(Sa[2], Sa[3]), pack2(Sa[4], Sa[5]), pack2(Sa[6], Sa[7])};
;         u32x4 pb = {pack2(Sb[0], Sb[1]), pack2(Sb[2], Sb[3]), pack2(Sb[4], Sb[5]), pack2(Sb[6], Sb[7])};
;         f32x4 acc = {0.f, 0.f, 0.f, 0.f};
;         acc = __builtin_amdgcn_mfma_f32_16x16x32_bf16(A0, __builtin_bit_cast(bf16x8, pa), acc, 0, 0, 0);
;         acc = __builtin_amdgcn_mfma_f32_16x16x32_bf16(A1, __builtin_bit_cast(bf16x8, pb), acc, 0, 0, 0);
;         float tA[8], tB[8];
; #pragma unroll
;         for (int c = 0; c < 8; c++) { tA[c] = Sa[c] * wA[c] + v * kdA[c]; tB[c] = Sb[c] * wB[c] + v * kdB[c]; }
;         const float sa = -acc[0];
;         const float yq = acc[1];
; #pragma unroll
;         for (int c = 0; c < 8; c++) { Sa[c] = tA[c] + sa * kaA[c]; Sb[c] = tB[c] + sa * kaB[c]; }
;         const float y = yq + sa * c1 + v * c2;
;         if (quad == 0) by[s * 64 + row] = y;
;       }
	v_mfma_f32_16x16x32_bf16 v[32:35], v[40:43], v[24:27], 0
	v_cvt_pk_bf16_f32 v30, v20, v21
	v_cvt_pk_bf16_f32 v31, v22, v23
	s_waitcnt lgkmcnt(3)
	v_fmac_f32_dpp v8, v65, v66 row_newbcast:0 row_mask:0xf bank_mask:0xf
	v_fmac_f32_dpp v9, v65, v66 row_newbcast:1 row_mask:0xf bank_mask:0xf
	v_mfma_f32_16x16x32_bf16 v[32:35], v[44:47], v[28:31], v[32:35]
	v_fmac_f32_dpp v10, v65, v66 row_newbcast:2 row_mask:0xf bank_mask:0xf
	v_fmac_f32_dpp v11, v65, v66 row_newbcast:3 row_mask:0xf bank_mask:0xf
	ds_read_b128 v[70:73], v104 offset:7936
	v_fmac_f32_dpp v12, v65, v66 row_newbcast:4 row_mask:0xf bank_mask:0xf
	v_fmac_f32_dpp v13, v65, v66 row_newbcast:5 row_mask:0xf bank_mask:0xf
	ds_read_b128 v[74:77], v104 offset:7952
	v_fmac_f32_dpp v14, v65, v66 row_newbcast:6 row_mask:0xf bank_mask:0xf
	v_fmac_f32_dpp v15, v65, v66 row_newbcast:7 row_mask:0xf bank_mask:0xf
	ds_read_b32 v94, v105 offset:7936
	v_fmac_f32_dpp v16, v65, v66 row_newbcast:8 row_mask:0xf bank_mask:0xf
	v_fmac_f32_dpp v17, v65, v66 row_newbcast:9 row_mask:0xf bank_mask:0xf
	ds_read_b32 v95, v105 offset:24320
	v_fmac_f32_dpp v18, v65, v66 row_newbcast:10 row_mask:0xf bank_mask:0xf
	v_fmac_f32_dpp v19, v65, v66 row_newbcast:11 row_mask:0xf bank_mask:0xf
	ds_read_b32 v96, v107 offset:7936
	v_fmac_f32_dpp v20, v65, v66 row_newbcast:12 row_mask:0xf bank_mask:0xf
	v_fmac_f32_dpp v21, v65, v66 row_newbcast:13 row_mask:0xf bank_mask:0xf
	ds_read_b32 v78, v105 offset:16128
	v_fmac_f32_dpp v22, v65, v66 row_newbcast:14 row_mask:0xf bank_mask:0xf
	v_fmac_f32_dpp v23, v65, v66 row_newbcast:15 row_mask:0xf bank_mask:0xf
	ds_read_b64 v[98:99], v108 offset:49400
	s_waitcnt lgkmcnt(9)
	s_waitcnt lgkmcnt(8)
	v_xor_b32_e32 v110, 0x80000000, v32
	v_fma_f32 v109, -v32, v68, v33
	v_fma_f32 v109, v66, v69, v109
	v_fmac_f32_dpp v8, v48, v110 row_newbcast:0 row_mask:0xf bank_mask:0xf
	v_fmac_f32_dpp v9, v48, v110 row_newbcast:1 row_mask:0xf bank_mask:0xf
	v_fmac_f32_dpp v10, v48, v110 row_newbcast:2 row_mask:0xf bank_mask:0xf
	v_fmac_f32_dpp v11, v48, v110 row_newbcast:3 row_mask:0xf bank_mask:0xf
	v_fmac_f32_dpp v12, v48, v110 row_newbcast:4 row_mask:0xf bank_mask:0xf
	v_fmac_f32_dpp v13, v48, v110 row_newbcast:5 row_mask:0xf bank_mask:0xf
	v_fmac_f32_dpp v14, v48, v110 row_newbcast:6 row_mask:0xf bank_mask:0xf
	v_fmac_f32_dpp v15, v48, v110 row_newbcast:7 row_mask:0xf bank_mask:0xf
	v_fmac_f32_dpp v16, v48, v110 row_newbcast:8 row_mask:0xf bank_mask:0xf
	v_fmac_f32_dpp v17, v48, v110 row_newbcast:9 row_mask:0xf bank_mask:0xf
	v_fmac_f32_dpp v18, v48, v110 row_newbcast:10 row_mask:0xf bank_mask:0xf
	v_fmac_f32_dpp v19, v48, v110 row_newbcast:11 row_mask:0xf bank_mask:0xf
	v_fmac_f32_dpp v20, v48, v110 row_newbcast:12 row_mask:0xf bank_mask:0xf
	v_fmac_f32_dpp v21, v48, v110 row_newbcast:13 row_mask:0xf bank_mask:0xf
	v_fmac_f32_dpp v22, v48, v110 row_newbcast:14 row_mask:0xf bank_mask:0xf
	v_fmac_f32_dpp v23, v48, v110 row_newbcast:15 row_mask:0xf bank_mask:0xf
	ds_write_b32 v107, v109 offset:15872
	v_cvt_pk_bf16_f32 v24, v8, v9
	v_cvt_pk_bf16_f32 v25, v10, v11
	v_cvt_pk_bf16_f32 v26, v12, v13
	v_cvt_pk_bf16_f32 v27, v14, v15
	v_cvt_pk_bf16_f32 v28, v16, v17
	v_cvt_pk_bf16_f32 v29, v18, v19
	s_waitcnt lgkmcnt(7)
	v_mfma_f32_16x16x32_bf16 v[32:35], v[70:73], v[24:27], 0
	v_cvt_pk_bf16_f32 v30, v20, v21
	v_cvt_pk_bf16_f32 v31, v22, v23
	s_waitcnt lgkmcnt(3)
; __device__ __forceinline__ void phase_rwkv_scan(const Params& p, int l, const int tidx) {
;     ...
;       for (int s = 0; s < RTC; s++) {
;         const bf16x8 A0 = nA0, A1 = nA1;
;         const float wA[8] = {nw0.x, nw0.y, nw0.z, nw0.w, nw1.x, nw1.y, nw1.z, nw1.w};
;         const float wB[8] = {nw2.x, nw2.y, nw2.z, nw2.w, nw3.x, nw3.y, nw3.z, nw3.w};
;         const float kaA[8] = {nka0.x, nka0.y, nka0.z, nka0.w, nka1.x, nka1.y, nka1.z, nka1.w};
;         const float kaB[8] = {nka2.x, nka2.y, nka2.z, nka2.w, nka3.x, nka3.y, nka3.z, nka3.w};
;         const float kdA[8] = {nkd0.x, nkd0.y, nkd0.z, nkd0.w, nkd1.x, nkd1.y, nkd1.z, nkd1.w};
;         const float kdB[8] = {nkd2.x, nkd2.y, nkd2.z, nkd2.w, nkd3.x, nkd3.y, nkd3.z, nkd3.w};
;         const float v = nv;
;         float c1 = nc.x, c2 = nc.y;
;         asm volatile("" : "+v"(c1), "+v"(c2));
;         if (s + 1 < RTC) RW_LD(s + 1);
;         u32x4 pa = {pack2(Sa[0], Sa[1]), pack2(Sa[2], Sa[3]), pack2(Sa[4], Sa[5]), pack2(Sa[6], Sa[7])};
;         u32x4 pb = {pack2(Sb[0], Sb[1]), pack2(Sb[2], Sb[3]), pack2(Sb[4], Sb[5]), pack2(Sb[6], Sb[7])};
;         f32x4 acc = {0.f, 0.f, 0.f, 0.f};
;         acc = __builtin_amdgcn_mfma_f32_16x16x32_bf16(A0, __builtin_bit_cast(bf16x8, pa), acc, 0, 0, 0);
;         acc = __builtin_amdgcn_mfma_f32_16x16x32_bf16(A1, __builtin_bit_cast(bf16x8, pb), acc, 0, 0, 0);
;         float tA[8], tB[8];
; #pragma unroll
;         for (int c = 0; c < 8; c++) { tA[c] = Sa[c] * wA[c] + v * kdA[c]; tB[c] = Sb[c] * wB[c] + v * kdB[c]; }
;         const float sa = -acc[0];
;         const float yq = acc[1];
; #pragma unroll
;         for (int c = 0; c < 8; c++) { Sa[c] = tA[c] + sa * kaA[c]; Sb[c] = tB[c] + sa * kaB[c]; }
;         const float y = yq + sa * c1 + v * c2;
;         if (quad == 0) by[s * 64 + row] = y;
;       }
;     ...
;       __syncthreads();
;     }
	v_fmac_f32_dpp v8, v95, v96 row_newbcast:0 row_mask:0xf bank_mask:0xf
	v_fmac_f32_dpp v9, v95, v96 row_newbcast:1 row_mask:0xf bank_mask:0xf
	v_mfma_f32_16x16x32_bf16 v[32:35], v[74:77], v[28:31], v[32:35]
	v_fmac_f32_dpp v10, v95, v96 row_newbcast:2 row_mask:0xf bank_mask:0xf
	v_fmac_f32_dpp v11, v95, v96 row_newbcast:3 row_mask:0xf bank_mask:0xf
	v_fmac_f32_dpp v12, v95, v96 row_newbcast:4 row_mask:0xf bank_mask:0xf
	v_fmac_f32_dpp v13, v95, v96 row_newbcast:5 row_mask:0xf bank_mask:0xf
	v_fmac_f32_dpp v14, v95, v96 row_newbcast:6 row_mask:0xf bank_mask:0xf
	v_fmac_f32_dpp v15, v95, v96 row_newbcast:7 row_mask:0xf bank_mask:0xf
	v_fmac_f32_dpp v16, v95, v96 row_newbcast:8 row_mask:0xf bank_mask:0xf
	v_fmac_f32_dpp v17, v95, v96 row_newbcast:9 row_mask:0xf bank_mask:0xf
	v_fmac_f32_dpp v18, v95, v96 row_newbcast:10 row_mask:0xf bank_mask:0xf
	v_fmac_f32_dpp v19, v95, v96 row_newbcast:11 row_mask:0xf bank_mask:0xf
	v_fmac_f32_dpp v20, v95, v96 row_newbcast:12 row_mask:0xf bank_mask:0xf
	v_fmac_f32_dpp v21, v95, v96 row_newbcast:13 row_mask:0xf bank_mask:0xf
	v_fmac_f32_dpp v22, v95, v96 row_newbcast:14 row_mask:0xf bank_mask:0xf
	v_fmac_f32_dpp v23, v95, v96 row_newbcast:15 row_mask:0xf bank_mask:0xf
	s_waitcnt lgkmcnt(2)
	s_waitcnt lgkmcnt(1)
	v_xor_b32_e32 v110, 0x80000000, v32
	v_fma_f32 v109, -v32, v98, v33
	v_fma_f32 v109, v96, v99, v109
	v_fmac_f32_dpp v8, v78, v110 row_newbcast:0 row_mask:0xf bank_mask:0xf
	v_fmac_f32_dpp v9, v78, v110 row_newbcast:1 row_mask:0xf bank_mask:0xf
	v_fmac_f32_dpp v10, v78, v110 row_newbcast:2 row_mask:0xf bank_mask:0xf
	v_fmac_f32_dpp v11, v78, v110 row_newbcast:3 row_mask:0xf bank_mask:0xf
	v_fmac_f32_dpp v12, v78, v110 row_newbcast:4 row_mask:0xf bank_mask:0xf
	v_fmac_f32_dpp v13, v78, v110 row_newbcast:5 row_mask:0xf bank_mask:0xf
	v_fmac_f32_dpp v14, v78, v110 row_newbcast:6 row_mask:0xf bank_mask:0xf
	v_fmac_f32_dpp v15, v78, v110 row_newbcast:7 row_mask:0xf bank_mask:0xf
	v_fmac_f32_dpp v16, v78, v110 row_newbcast:8 row_mask:0xf bank_mask:0xf
	v_fmac_f32_dpp v17, v78, v110 row_newbcast:9 row_mask:0xf bank_mask:0xf
	v_fmac_f32_dpp v18, v78, v110 row_newbcast:10 row_mask:0xf bank_mask:0xf
	v_fmac_f32_dpp v19, v78, v110 row_newbcast:11 row_mask:0xf bank_mask:0xf
	v_fmac_f32_dpp v20, v78, v110 row_newbcast:12 row_mask:0xf bank_mask:0xf
	v_fmac_f32_dpp v21, v78, v110 row_newbcast:13 row_mask:0xf bank_mask:0xf
	v_fmac_f32_dpp v22, v78, v110 row_newbcast:14 row_mask:0xf bank_mask:0xf
	v_fmac_f32_dpp v23, v78, v110 row_newbcast:15 row_mask:0xf bank_mask:0xf
	v_mul_f32_dpp v8, v94, v8 row_newbcast:0 row_mask:0xf bank_mask:0xf
	v_mul_f32_dpp v9, v94, v9 row_newbcast:1 row_mask:0xf bank_mask:0xf
	v_mul_f32_dpp v10, v94, v10 row_newbcast:2 row_mask:0xf bank_mask:0xf
	v_mul_f32_dpp v11, v94, v11 row_newbcast:3 row_mask:0xf bank_mask:0xf
	v_mul_f32_dpp v12, v94, v12 row_newbcast:4 row_mask:0xf bank_mask:0xf
	v_mul_f32_dpp v13, v94, v13 row_newbcast:5 row_mask:0xf bank_mask:0xf
	v_mul_f32_dpp v14, v94, v14 row_newbcast:6 row_mask:0xf bank_mask:0xf
	v_mul_f32_dpp v15, v94, v15 row_newbcast:7 row_mask:0xf bank_mask:0xf
	v_mul_f32_dpp v16, v94, v16 row_newbcast:8 row_mask:0xf bank_mask:0xf
	v_mul_f32_dpp v17, v94, v17 row_newbcast:9 row_mask:0xf bank_mask:0xf
	v_mul_f32_dpp v18, v94, v18 row_newbcast:10 row_mask:0xf bank_mask:0xf
	v_mul_f32_dpp v19, v94, v19 row_newbcast:11 row_mask:0xf bank_mask:0xf
	v_mul_f32_dpp v20, v94, v20 row_newbcast:12 row_mask:0xf bank_mask:0xf
	v_mul_f32_dpp v21, v94, v21 row_newbcast:13 row_mask:0xf bank_mask:0xf
	v_mul_f32_dpp v22, v94, v22 row_newbcast:14 row_mask:0xf bank_mask:0xf
	v_mul_f32_dpp v23, v94, v23 row_newbcast:15 row_mask:0xf bank_mask:0xf
	ds_write_b32 v107, v109 offset:16128
	s_add_i32 s0, s0, 1
	s_cmpk_eq_i32 s0, 0x80
	s_waitcnt lgkmcnt(0)
	s_barrier
	s_cbranch_scc0 .Lrw_chunk
